# residual GEMM epilogues de-serialised (loads in flight, counted vmcnt); attention k-tile loop: LDS addresses hoisted, K reads batched, V transpose reads software-pipelined
# speedup vs baseline: 1.0935x; 1.0403x over previous
.LBB0_129:
	s_add_u32 s16, s14, 0x100
	s_addc_u32 s17, s15, 0
	s_add_i32 s42, 0, 0x10000
	v_add_u32_e32 v140, s42, v143
	ds_read_b128 v[136:139], v140
	ds_read_b128 v[146:149], v140 offset:1024
	ds_read_b128 v[150:153], v140 offset:2048
	ds_read_b128 v[154:157], v140 offset:3072
	s_cmpk_eq_i32 s41, 0x54
	s_cselect_b32 s21, s11, s17
	s_cselect_b32 s20, s10, s16
	s_cselect_b32 s19, s13, s40
	s_cselect_b32 s18, s12, s39
	v_lshl_add_u64 v[140:141], s[14:15], 0, v[132:133]
	s_add_i32 m0, s26, 0xc000
	ds_read_b128 v[158:161], v145
	ds_read_b128 v[176:179], v145 offset:1024
	ds_read_b128 v[180:183], v145 offset:2048
	ds_read_b128 v[184:187], v145 offset:3072
	ds_read_b128 v[188:191], v145 offset:4096
	ds_read_b128 v[192:195], v145 offset:5120
	ds_read_b128 v[208:211], v145 offset:6144
	ds_read_b128 v[212:215], v145 offset:7168
	global_load_lds_dwordx4 v[140:141], off
	v_lshl_add_u64 v[140:141], s[14:15], 0, v[134:135]
	s_add_i32 m0, s26, 0xe000
	s_nop 0
	global_load_lds_dwordx4 v[140:141], off
	s_waitcnt lgkmcnt(8)
	s_barrier
	s_waitcnt lgkmcnt(0)
	s_setprio 1
	s_waitcnt lgkmcnt(0)
	v_mfma_f32_16x16x32_bf16 v[124:127], v[136:139], v[158:161], v[124:127]
	v_mfma_f32_16x16x32_bf16 v[120:123], v[150:153], v[158:161], v[120:123]
	v_mfma_f32_16x16x32_bf16 v[108:111], v[136:139], v[180:183], v[108:111]
	v_mfma_f32_16x16x32_bf16 v[104:107], v[150:153], v[180:183], v[104:107]
	v_mfma_f32_16x16x32_bf16 v[92:95], v[136:139], v[188:191], v[92:95]
	v_mfma_f32_16x16x32_bf16 v[88:91], v[150:153], v[188:191], v[88:91]
	v_mfma_f32_16x16x32_bf16 v[76:79], v[136:139], v[208:211], v[76:79]
	v_mfma_f32_16x16x32_bf16 v[72:75], v[150:153], v[208:211], v[72:75]
	v_mfma_f32_16x16x32_bf16 v[124:127], v[146:149], v[176:179], v[124:127]
	v_mfma_f32_16x16x32_bf16 v[120:123], v[154:157], v[176:179], v[120:123]
	v_mfma_f32_16x16x32_bf16 v[108:111], v[146:149], v[184:187], v[108:111]
	v_mfma_f32_16x16x32_bf16 v[104:107], v[154:157], v[184:187], v[104:107]
	v_mfma_f32_16x16x32_bf16 v[92:95], v[146:149], v[192:195], v[92:95]
	v_mfma_f32_16x16x32_bf16 v[88:91], v[154:157], v[192:195], v[88:91]
	v_mfma_f32_16x16x32_bf16 v[76:79], v[146:149], v[212:215], v[76:79]
	v_mfma_f32_16x16x32_bf16 v[72:75], v[154:157], v[212:215], v[72:75]
	s_setprio 0
	s_barrier
	s_add_i32 s43, 0, 0x14000
	v_add_u32_e32 v140, s43, v143
	s_add_i32 s14, s42, s25
	ds_read_b128 v[216:219], v140
	ds_read_b128 v[220:223], v140 offset:1024
	ds_read_b128 v[224:227], v140 offset:2048
	ds_read_b128 v[228:231], v140 offset:3072
	v_lshl_add_u64 v[140:141], s[18:19], 0, v[128:129]
	s_mov_b32 m0, s14
	v_lshl_add_u64 v[232:233], s[18:19], 0, v[130:131]
	global_load_lds_dwordx4 v[140:141], off
	s_add_i32 m0, s14, 0x2000
	s_nop 0
	global_load_lds_dwordx4 v[232:233], off
	s_barrier
	s_waitcnt lgkmcnt(0)
	s_setprio 1
	s_waitcnt lgkmcnt(0)
	v_mfma_f32_16x16x32_bf16 v[116:119], v[216:219], v[158:161], v[116:119]
	v_mfma_f32_16x16x32_bf16 v[112:115], v[224:227], v[158:161], v[112:115]
	v_mfma_f32_16x16x32_bf16 v[100:103], v[216:219], v[180:183], v[100:103]
	v_mfma_f32_16x16x32_bf16 v[96:99], v[224:227], v[180:183], v[96:99]
	v_mfma_f32_16x16x32_bf16 v[84:87], v[216:219], v[188:191], v[84:87]
	v_mfma_f32_16x16x32_bf16 v[80:83], v[224:227], v[188:191], v[80:83]
	v_mfma_f32_16x16x32_bf16 v[68:71], v[216:219], v[208:211], v[68:71]
	v_mfma_f32_16x16x32_bf16 v[64:67], v[224:227], v[208:211], v[64:67]
	v_mfma_f32_16x16x32_bf16 v[116:119], v[220:223], v[176:179], v[116:119]
	v_mfma_f32_16x16x32_bf16 v[112:115], v[228:231], v[176:179], v[112:115]
	v_mfma_f32_16x16x32_bf16 v[100:103], v[220:223], v[184:187], v[100:103]
	v_mfma_f32_16x16x32_bf16 v[96:99], v[228:231], v[184:187], v[96:99]
	v_mfma_f32_16x16x32_bf16 v[84:87], v[220:223], v[192:195], v[84:87]
	v_mfma_f32_16x16x32_bf16 v[80:83], v[228:231], v[192:195], v[80:83]
	v_mfma_f32_16x16x32_bf16 v[68:71], v[220:223], v[212:215], v[68:71]
	v_mfma_f32_16x16x32_bf16 v[64:67], v[228:231], v[212:215], v[64:67]
	s_setprio 0
	s_mov_b32 m0, s26
	v_lshl_add_u64 v[234:235], s[20:21], 0, v[128:129]
	s_barrier
	ds_read_b128 v[158:161], v145 offset:16384
	ds_read_b128 v[176:179], v145 offset:17408
	ds_read_b128 v[180:183], v145 offset:18432
	ds_read_b128 v[184:187], v145 offset:19456
	ds_read_b128 v[188:191], v145 offset:20480
	ds_read_b128 v[192:195], v145 offset:21504
	ds_read_b128 v[208:211], v145 offset:22528
	ds_read_b128 v[212:215], v145 offset:23552
	global_load_lds_dwordx4 v[234:235], off
	v_lshl_add_u64 v[236:237], s[20:21], 0, v[130:131]
	s_mov_b32 m0, s27
	s_nop 0
	global_load_lds_dwordx4 v[236:237], off
	s_barrier
	s_waitcnt lgkmcnt(0)
	s_setprio 1
	s_waitcnt lgkmcnt(0)
	v_mfma_f32_16x16x32_bf16 v[60:63], v[136:139], v[158:161], v[60:63]
	v_mfma_f32_16x16x32_bf16 v[56:59], v[150:153], v[158:161], v[56:59]
	v_mfma_f32_16x16x32_bf16 v[44:47], v[136:139], v[180:183], v[44:47]
	v_mfma_f32_16x16x32_bf16 v[40:43], v[150:153], v[180:183], v[40:43]
	v_mfma_f32_16x16x32_bf16 v[28:31], v[136:139], v[188:191], v[28:31]
	v_mfma_f32_16x16x32_bf16 v[24:27], v[150:153], v[188:191], v[24:27]
	v_mfma_f32_16x16x32_bf16 v[12:15], v[136:139], v[208:211], v[12:15]
	v_mfma_f32_16x16x32_bf16 v[8:11], v[150:153], v[208:211], v[8:11]
	v_mfma_f32_16x16x32_bf16 v[60:63], v[146:149], v[176:179], v[60:63]
	v_mfma_f32_16x16x32_bf16 v[56:59], v[154:157], v[176:179], v[56:59]
	v_mfma_f32_16x16x32_bf16 v[44:47], v[146:149], v[184:187], v[44:47]
	v_mfma_f32_16x16x32_bf16 v[40:43], v[154:157], v[184:187], v[40:43]
	v_mfma_f32_16x16x32_bf16 v[28:31], v[146:149], v[192:195], v[28:31]
	v_mfma_f32_16x16x32_bf16 v[24:27], v[154:157], v[192:195], v[24:27]
	v_mfma_f32_16x16x32_bf16 v[12:15], v[146:149], v[212:215], v[12:15]
	v_mfma_f32_16x16x32_bf16 v[8:11], v[154:157], v[212:215], v[8:11]
	s_setprio 0
	s_barrier
	s_add_u32 s14, s18, 0x160000
	s_addc_u32 s15, s19, 0
	s_add_i32 s42, s43, s25
	v_lshl_add_u64 v[136:137], s[14:15], 0, v[128:129]
	s_mov_b32 m0, s42
	s_nop 0
	global_load_lds_dwordx4 v[136:137], off
	v_lshl_add_u64 v[136:137], s[14:15], 0, v[130:131]
	s_add_i32 m0, s42, 0x2000
	s_nop 0
	global_load_lds_dwordx4 v[136:137], off
	s_waitcnt vmcnt(6)
	s_barrier
	s_setprio 1
	v_mfma_f32_16x16x32_bf16 v[52:55], v[216:219], v[158:161], v[52:55]
	v_mfma_f32_16x16x32_bf16 v[48:51], v[224:227], v[158:161], v[48:51]
	v_mfma_f32_16x16x32_bf16 v[36:39], v[216:219], v[180:183], v[36:39]
	v_mfma_f32_16x16x32_bf16 v[32:35], v[224:227], v[180:183], v[32:35]
	v_mfma_f32_16x16x32_bf16 v[20:23], v[216:219], v[188:191], v[20:23]
	v_mfma_f32_16x16x32_bf16 v[16:19], v[224:227], v[188:191], v[16:19]
	v_mfma_f32_16x16x32_bf16 v[4:7], v[216:219], v[208:211], v[4:7]
	v_mfma_f32_16x16x32_bf16 v[0:3], v[224:227], v[208:211], v[0:3]
	v_mfma_f32_16x16x32_bf16 v[52:55], v[220:223], v[176:179], v[52:55]
	v_mfma_f32_16x16x32_bf16 v[48:51], v[228:231], v[176:179], v[48:51]
	v_mfma_f32_16x16x32_bf16 v[36:39], v[220:223], v[184:187], v[36:39]
	v_mfma_f32_16x16x32_bf16 v[32:35], v[228:231], v[184:187], v[32:35]
	v_mfma_f32_16x16x32_bf16 v[20:23], v[220:223], v[192:195], v[20:23]
	v_mfma_f32_16x16x32_bf16 v[16:19], v[228:231], v[192:195], v[16:19]
	v_mfma_f32_16x16x32_bf16 v[4:7], v[220:223], v[212:215], v[4:7]
	v_mfma_f32_16x16x32_bf16 v[0:3], v[228:231], v[212:215], v[0:3]
	s_setprio 0
	s_add_i32 s42, 0, 0x18000
	v_add_u32_e32 v154, s42, v143
	s_barrier
	ds_read_b128 v[136:139], v154
	ds_read_b128 v[146:149], v154 offset:1024
	ds_read_b128 v[150:153], v154 offset:2048
	ds_read_b128 v[154:157], v154 offset:3072
	s_add_u32 s14, s20, 0x160000
	s_addc_u32 s15, s21, 0
	s_mov_b32 m0, s28
	v_lshl_add_u64 v[216:217], s[14:15], 0, v[128:129]
	ds_read_b128 v[158:161], v145 offset:32768
	ds_read_b128 v[176:179], v145 offset:33792
	ds_read_b128 v[180:183], v145 offset:34816
	ds_read_b128 v[184:187], v145 offset:35840
	ds_read_b128 v[188:191], v145 offset:36864
	ds_read_b128 v[192:195], v145 offset:37888
	ds_read_b128 v[208:211], v145 offset:38912
	ds_read_b128 v[212:215], v145 offset:39936
	global_load_lds_dwordx4 v[216:217], off
	v_lshl_add_u64 v[216:217], s[14:15], 0, v[130:131]
	s_mov_b32 m0, s29
	s_nop 0
	global_load_lds_dwordx4 v[216:217], off
	s_waitcnt lgkmcnt(8)
	s_barrier
	s_waitcnt lgkmcnt(0)
	s_setprio 1
	s_waitcnt lgkmcnt(0)
	v_mfma_f32_16x16x32_bf16 v[124:127], v[136:139], v[158:161], v[124:127]
	v_mfma_f32_16x16x32_bf16 v[120:123], v[150:153], v[158:161], v[120:123]
	v_mfma_f32_16x16x32_bf16 v[108:111], v[136:139], v[180:183], v[108:111]
	v_mfma_f32_16x16x32_bf16 v[104:107], v[150:153], v[180:183], v[104:107]
	v_mfma_f32_16x16x32_bf16 v[92:95], v[136:139], v[188:191], v[92:95]
	v_mfma_f32_16x16x32_bf16 v[88:91], v[150:153], v[188:191], v[88:91]
	v_mfma_f32_16x16x32_bf16 v[76:79], v[136:139], v[208:211], v[76:79]
	v_mfma_f32_16x16x32_bf16 v[72:75], v[150:153], v[208:211], v[72:75]
	v_mfma_f32_16x16x32_bf16 v[124:127], v[146:149], v[176:179], v[124:127]
	v_mfma_f32_16x16x32_bf16 v[120:123], v[154:157], v[176:179], v[120:123]
	v_mfma_f32_16x16x32_bf16 v[108:111], v[146:149], v[184:187], v[108:111]
	v_mfma_f32_16x16x32_bf16 v[104:107], v[154:157], v[184:187], v[104:107]
	v_mfma_f32_16x16x32_bf16 v[92:95], v[146:149], v[192:195], v[92:95]
	v_mfma_f32_16x16x32_bf16 v[88:91], v[154:157], v[192:195], v[88:91]
	v_mfma_f32_16x16x32_bf16 v[76:79], v[146:149], v[212:215], v[76:79]
	v_mfma_f32_16x16x32_bf16 v[72:75], v[154:157], v[212:215], v[72:75]
	s_setprio 0
	s_barrier
	s_add_i32 s20, 0, 0x1c000
	s_add_i32 s14, s42, s25
	v_add_u32_e32 v196, s20, v143
	v_lshl_add_u64 v[140:141], v[140:141], 0, s[6:7]
	s_mov_b32 m0, s14
	ds_read_b128 v[216:219], v196
	ds_read_b128 v[220:223], v196 offset:1024
	ds_read_b128 v[224:227], v196 offset:2048
	ds_read_b128 v[228:231], v196 offset:3072
	global_load_lds_dwordx4 v[140:141], off
	v_lshl_add_u64 v[140:141], v[232:233], 0, s[6:7]
	s_add_i32 m0, s14, 0x2000
	s_nop 0
	global_load_lds_dwordx4 v[140:141], off
	s_barrier
	s_waitcnt lgkmcnt(0)
	s_setprio 1
	s_waitcnt lgkmcnt(0)
	v_mfma_f32_16x16x32_bf16 v[116:119], v[216:219], v[158:161], v[116:119]
	v_mfma_f32_16x16x32_bf16 v[112:115], v[224:227], v[158:161], v[112:115]
	v_mfma_f32_16x16x32_bf16 v[100:103], v[216:219], v[180:183], v[100:103]
	v_mfma_f32_16x16x32_bf16 v[96:99], v[224:227], v[180:183], v[96:99]
	v_mfma_f32_16x16x32_bf16 v[84:87], v[216:219], v[188:191], v[84:87]
	v_mfma_f32_16x16x32_bf16 v[80:83], v[224:227], v[188:191], v[80:83]
	v_mfma_f32_16x16x32_bf16 v[68:71], v[216:219], v[208:211], v[68:71]
	v_mfma_f32_16x16x32_bf16 v[64:67], v[224:227], v[208:211], v[64:67]
	v_mfma_f32_16x16x32_bf16 v[116:119], v[220:223], v[176:179], v[116:119]
	v_mfma_f32_16x16x32_bf16 v[112:115], v[228:231], v[176:179], v[112:115]
	v_mfma_f32_16x16x32_bf16 v[100:103], v[220:223], v[184:187], v[100:103]
	v_mfma_f32_16x16x32_bf16 v[96:99], v[228:231], v[184:187], v[96:99]
	v_mfma_f32_16x16x32_bf16 v[84:87], v[220:223], v[192:195], v[84:87]
	v_mfma_f32_16x16x32_bf16 v[80:83], v[228:231], v[192:195], v[80:83]
	v_mfma_f32_16x16x32_bf16 v[68:71], v[220:223], v[212:215], v[68:71]
	v_mfma_f32_16x16x32_bf16 v[64:67], v[228:231], v[212:215], v[64:67]
	s_setprio 0
	s_mov_b32 m0, s30
	v_lshl_add_u64 v[140:141], v[234:235], 0, s[6:7]
	s_barrier
	ds_read_b128 v[158:161], v145 offset:49152
	ds_read_b128 v[176:179], v145 offset:50176
	ds_read_b128 v[180:183], v145 offset:51200
	ds_read_b128 v[184:187], v145 offset:52224
	ds_read_b128 v[188:191], v145 offset:53248
	ds_read_b128 v[192:195], v145 offset:54272
	ds_read_b128 v[208:211], v145 offset:55296
	ds_read_b128 v[212:215], v145 offset:56320
	global_load_lds_dwordx4 v[140:141], off
	v_lshl_add_u64 v[140:141], v[236:237], 0, s[6:7]
	s_mov_b32 m0, s31
	s_nop 0
	global_load_lds_dwordx4 v[140:141], off
	s_barrier
	s_waitcnt lgkmcnt(0)
	s_setprio 1
	s_waitcnt lgkmcnt(0)
	v_mfma_f32_16x16x32_bf16 v[60:63], v[136:139], v[158:161], v[60:63]
	v_mfma_f32_16x16x32_bf16 v[56:59], v[150:153], v[158:161], v[56:59]
	v_mfma_f32_16x16x32_bf16 v[44:47], v[136:139], v[180:183], v[44:47]
	v_mfma_f32_16x16x32_bf16 v[40:43], v[150:153], v[180:183], v[40:43]
	v_mfma_f32_16x16x32_bf16 v[28:31], v[136:139], v[188:191], v[28:31]
	v_mfma_f32_16x16x32_bf16 v[24:27], v[150:153], v[188:191], v[24:27]
	v_mfma_f32_16x16x32_bf16 v[12:15], v[136:139], v[208:211], v[12:15]
	v_mfma_f32_16x16x32_bf16 v[8:11], v[150:153], v[208:211], v[8:11]
	v_mfma_f32_16x16x32_bf16 v[60:63], v[146:149], v[176:179], v[60:63]
	v_mfma_f32_16x16x32_bf16 v[56:59], v[154:157], v[176:179], v[56:59]
	v_mfma_f32_16x16x32_bf16 v[44:47], v[146:149], v[184:187], v[44:47]
	v_mfma_f32_16x16x32_bf16 v[40:43], v[154:157], v[184:187], v[40:43]
	v_mfma_f32_16x16x32_bf16 v[28:31], v[146:149], v[192:195], v[28:31]
	v_mfma_f32_16x16x32_bf16 v[24:27], v[154:157], v[192:195], v[24:27]
	v_mfma_f32_16x16x32_bf16 v[12:15], v[146:149], v[212:215], v[12:15]
	v_mfma_f32_16x16x32_bf16 v[8:11], v[154:157], v[212:215], v[8:11]
	s_setprio 0
	s_barrier
	s_add_u32 s14, s18, 0x160080
	s_addc_u32 s15, s19, 0
	s_add_i32 s18, s20, s25
	v_lshl_add_u64 v[136:137], s[14:15], 0, v[128:129]
	s_mov_b32 m0, s18
	s_nop 0
	global_load_lds_dwordx4 v[136:137], off
	v_lshl_add_u64 v[136:137], s[14:15], 0, v[130:131]
	s_add_i32 m0, s18, 0x2000
	s_nop 0
	global_load_lds_dwordx4 v[136:137], off
	s_waitcnt vmcnt(6)
	s_barrier
	s_setprio 1
	v_mfma_f32_16x16x32_bf16 v[52:55], v[216:219], v[158:161], v[52:55]
	v_mfma_f32_16x16x32_bf16 v[48:51], v[224:227], v[158:161], v[48:51]
	v_mfma_f32_16x16x32_bf16 v[36:39], v[216:219], v[180:183], v[36:39]
	v_mfma_f32_16x16x32_bf16 v[32:35], v[224:227], v[180:183], v[32:35]
	v_mfma_f32_16x16x32_bf16 v[20:23], v[216:219], v[188:191], v[20:23]
	v_mfma_f32_16x16x32_bf16 v[16:19], v[224:227], v[188:191], v[16:19]
	v_mfma_f32_16x16x32_bf16 v[4:7], v[216:219], v[208:211], v[4:7]
	v_mfma_f32_16x16x32_bf16 v[0:3], v[224:227], v[208:211], v[0:3]
	v_mfma_f32_16x16x32_bf16 v[52:55], v[220:223], v[176:179], v[52:55]
	v_mfma_f32_16x16x32_bf16 v[48:51], v[228:231], v[176:179], v[48:51]
	v_mfma_f32_16x16x32_bf16 v[36:39], v[220:223], v[184:187], v[36:39]
	v_mfma_f32_16x16x32_bf16 v[32:35], v[228:231], v[184:187], v[32:35]
	v_mfma_f32_16x16x32_bf16 v[20:23], v[220:223], v[192:195], v[20:23]
	v_mfma_f32_16x16x32_bf16 v[16:19], v[228:231], v[192:195], v[16:19]
	v_mfma_f32_16x16x32_bf16 v[4:7], v[220:223], v[212:215], v[4:7]
	v_mfma_f32_16x16x32_bf16 v[0:3], v[228:231], v[212:215], v[0:3]
	s_setprio 0
	s_add_i32 s41, s41, 2
	s_add_u32 s39, s39, 0x100
	s_addc_u32 s40, s40, 0
	s_cmpk_gt_u32 s41, 0x55
	s_mov_b64 s[14:15], s[16:17]
	s_barrier
	s_cbranch_scc0 .LBB0_129
	v_lshl_add_u32 v136, s37, 8, v142
	v_lshl_or_b32 v137, s38, 8, v144
	v_lshl_add_u32 v137, v136, 11, v137
	v_lshlrev_b32_e32 v138, 1, v137
	v_lshlrev_b32_e32 v139, 2, v137
	s_mov_b32 s38, s35
	s_mov_b32 s37, s36
	v_readlane_b32 s14, v255, 34
	v_readlane_b32 s15, v255, 35
	s_nop 4
	s_mov_b64 s[16:17], s[76:77]
	global_load_dwordx2 v[148:149], v138, s[14:15] offset:0
	global_load_dwordx2 v[150:151], v138, s[14:15] offset:32
	global_load_dwordx2 v[152:153], v138, s[14:15] offset:256
	global_load_dwordx2 v[154:155], v138, s[14:15] offset:288
	s_add_u32 s14, s14, 0x10000
	s_addc_u32 s15, s15, 0
	global_load_dwordx2 v[156:157], v138, s[14:15] offset:0
	global_load_dwordx2 v[158:159], v138, s[14:15] offset:32
	global_load_dwordx2 v[160:161], v138, s[14:15] offset:256
	global_load_dwordx2 v[176:177], v138, s[14:15] offset:288
	s_add_u32 s14, s14, 0x10000
	s_addc_u32 s15, s15, 0
	global_load_dwordx2 v[178:179], v138, s[14:15] offset:0
	global_load_dwordx2 v[180:181], v138, s[14:15] offset:32
	global_load_dwordx2 v[182:183], v138, s[14:15] offset:256
	global_load_dwordx2 v[184:185], v138, s[14:15] offset:288
	s_add_u32 s14, s14, 0x10000
	s_addc_u32 s15, s15, 0
	global_load_dwordx2 v[186:187], v138, s[14:15] offset:0
	global_load_dwordx2 v[188:189], v138, s[14:15] offset:32
	global_load_dwordx2 v[190:191], v138, s[14:15] offset:256
	global_load_dwordx2 v[192:193], v138, s[14:15] offset:288
	s_add_u32 s14, s14, 0x50000
	s_addc_u32 s15, s15, 0
	global_load_dwordx2 v[194:195], v138, s[14:15] offset:0
	global_load_dwordx2 v[208:209], v138, s[14:15] offset:32
	global_load_dwordx2 v[210:211], v138, s[14:15] offset:256
	global_load_dwordx2 v[212:213], v138, s[14:15] offset:288
	s_add_u32 s14, s14, 0x10000
	s_addc_u32 s15, s15, 0
	global_load_dwordx2 v[214:215], v138, s[14:15] offset:0
	global_load_dwordx2 v[216:217], v138, s[14:15] offset:32
	global_load_dwordx2 v[218:219], v138, s[14:15] offset:256
	global_load_dwordx2 v[220:221], v138, s[14:15] offset:288
	s_add_u32 s14, s14, 0x10000
	s_addc_u32 s15, s15, 0
	global_load_dwordx2 v[222:223], v138, s[14:15] offset:0
	global_load_dwordx2 v[224:225], v138, s[14:15] offset:32
	global_load_dwordx2 v[226:227], v138, s[14:15] offset:256
	global_load_dwordx2 v[228:229], v138, s[14:15] offset:288
	s_add_u32 s14, s14, 0x10000
	s_addc_u32 s15, s15, 0
	global_load_dwordx2 v[230:231], v138, s[14:15] offset:0
	s_waitcnt vmcnt(28)
	v_lshlrev_b32_e32 v146, 16, v148
	v_and_b32_e32 v147, 0xffff0000, v148
	v_lshlrev_b32_e32 v148, 16, v149
	v_and_b32_e32 v149, 0xffff0000, v149
	v_pk_mul_f32 v[146:147], v[146:147], s[74:75] op_sel_hi:[1,0]
	v_pk_mul_f32 v[148:149], v[148:149], s[74:75] op_sel_hi:[1,0]
	v_pk_fma_f32 v[124:125], v[124:125], 0.5, v[146:147] op_sel_hi:[1,0,1]
	v_pk_fma_f32 v[126:127], v[126:127], 0.5, v[148:149] op_sel_hi:[1,0,1]
	global_store_dwordx4 v139, v[124:127], s[16:17] offset:0
	global_load_dwordx2 v[148:149], v138, s[14:15] offset:32
	s_waitcnt vmcnt(29)
	v_lshlrev_b32_e32 v146, 16, v150
	v_and_b32_e32 v147, 0xffff0000, v150
	v_lshlrev_b32_e32 v150, 16, v151
	v_and_b32_e32 v151, 0xffff0000, v151
	v_pk_mul_f32 v[146:147], v[146:147], s[74:75] op_sel_hi:[1,0]
	v_pk_mul_f32 v[150:151], v[150:151], s[74:75] op_sel_hi:[1,0]
	v_pk_fma_f32 v[120:121], v[120:121], 0.5, v[146:147] op_sel_hi:[1,0,1]
	v_pk_fma_f32 v[122:123], v[122:123], 0.5, v[150:151] op_sel_hi:[1,0,1]
	global_store_dwordx4 v139, v[120:123], s[16:17] offset:64
	global_load_dwordx2 v[150:151], v138, s[14:15] offset:256
	s_waitcnt vmcnt(30)
	v_lshlrev_b32_e32 v146, 16, v152
	v_and_b32_e32 v147, 0xffff0000, v152
	v_lshlrev_b32_e32 v152, 16, v153
	v_and_b32_e32 v153, 0xffff0000, v153
	v_pk_mul_f32 v[146:147], v[146:147], s[74:75] op_sel_hi:[1,0]
	v_pk_mul_f32 v[152:153], v[152:153], s[74:75] op_sel_hi:[1,0]
	v_pk_fma_f32 v[116:117], v[116:117], 0.5, v[146:147] op_sel_hi:[1,0,1]
	v_pk_fma_f32 v[118:119], v[118:119], 0.5, v[152:153] op_sel_hi:[1,0,1]
	global_store_dwordx4 v139, v[116:119], s[16:17] offset:512
	global_load_dwordx2 v[152:153], v138, s[14:15] offset:288
	s_waitcnt vmcnt(31)
	v_lshlrev_b32_e32 v146, 16, v154
	v_and_b32_e32 v147, 0xffff0000, v154
	v_lshlrev_b32_e32 v154, 16, v155
	v_and_b32_e32 v155, 0xffff0000, v155
	v_pk_mul_f32 v[146:147], v[146:147], s[74:75] op_sel_hi:[1,0]
	v_pk_mul_f32 v[154:155], v[154:155], s[74:75] op_sel_hi:[1,0]
	v_pk_fma_f32 v[112:113], v[112:113], 0.5, v[146:147] op_sel_hi:[1,0,1]
	v_pk_fma_f32 v[114:115], v[114:115], 0.5, v[154:155] op_sel_hi:[1,0,1]
	global_store_dwordx4 v139, v[112:115], s[16:17] offset:576
	s_waitcnt vmcnt(31)
	v_lshlrev_b32_e32 v146, 16, v156
	v_and_b32_e32 v147, 0xffff0000, v156
	v_lshlrev_b32_e32 v156, 16, v157
	v_and_b32_e32 v157, 0xffff0000, v157
	v_pk_mul_f32 v[146:147], v[146:147], s[74:75] op_sel_hi:[1,0]
	v_pk_mul_f32 v[156:157], v[156:157], s[74:75] op_sel_hi:[1,0]
	v_pk_fma_f32 v[108:109], v[108:109], 0.5, v[146:147] op_sel_hi:[1,0,1]
	v_pk_fma_f32 v[110:111], v[110:111], 0.5, v[156:157] op_sel_hi:[1,0,1]
	s_add_u32 s16, s16, 0x20000
	s_addc_u32 s17, s17, 0
	global_store_dwordx4 v139, v[108:111], s[16:17] offset:0
	s_waitcnt vmcnt(31)
	v_lshlrev_b32_e32 v146, 16, v158
	v_and_b32_e32 v147, 0xffff0000, v158
	v_lshlrev_b32_e32 v158, 16, v159
	v_and_b32_e32 v159, 0xffff0000, v159
	v_pk_mul_f32 v[146:147], v[146:147], s[74:75] op_sel_hi:[1,0]
	v_pk_mul_f32 v[158:159], v[158:159], s[74:75] op_sel_hi:[1,0]
	v_pk_fma_f32 v[104:105], v[104:105], 0.5, v[146:147] op_sel_hi:[1,0,1]
	v_pk_fma_f32 v[106:107], v[106:107], 0.5, v[158:159] op_sel_hi:[1,0,1]
	global_store_dwordx4 v139, v[104:107], s[16:17] offset:64
	s_waitcnt vmcnt(31)
	v_lshlrev_b32_e32 v146, 16, v160
	v_and_b32_e32 v147, 0xffff0000, v160
	v_lshlrev_b32_e32 v160, 16, v161
	v_and_b32_e32 v161, 0xffff0000, v161
	v_pk_mul_f32 v[146:147], v[146:147], s[74:75] op_sel_hi:[1,0]
	v_pk_mul_f32 v[160:161], v[160:161], s[74:75] op_sel_hi:[1,0]
	v_pk_fma_f32 v[100:101], v[100:101], 0.5, v[146:147] op_sel_hi:[1,0,1]
	v_pk_fma_f32 v[102:103], v[102:103], 0.5, v[160:161] op_sel_hi:[1,0,1]
	global_store_dwordx4 v139, v[100:103], s[16:17] offset:512
	s_waitcnt vmcnt(31)
	v_lshlrev_b32_e32 v146, 16, v176
	v_and_b32_e32 v147, 0xffff0000, v176
	v_lshlrev_b32_e32 v176, 16, v177
	v_and_b32_e32 v177, 0xffff0000, v177
	v_pk_mul_f32 v[146:147], v[146:147], s[74:75] op_sel_hi:[1,0]
	v_pk_mul_f32 v[176:177], v[176:177], s[74:75] op_sel_hi:[1,0]
	v_pk_fma_f32 v[96:97], v[96:97], 0.5, v[146:147] op_sel_hi:[1,0,1]
	v_pk_fma_f32 v[98:99], v[98:99], 0.5, v[176:177] op_sel_hi:[1,0,1]
	global_store_dwordx4 v139, v[96:99], s[16:17] offset:576
	s_waitcnt vmcnt(31)
	v_lshlrev_b32_e32 v146, 16, v178
	v_and_b32_e32 v147, 0xffff0000, v178
	v_lshlrev_b32_e32 v178, 16, v179
	v_and_b32_e32 v179, 0xffff0000, v179
	v_pk_mul_f32 v[146:147], v[146:147], s[74:75] op_sel_hi:[1,0]
	v_pk_mul_f32 v[178:179], v[178:179], s[74:75] op_sel_hi:[1,0]
	v_pk_fma_f32 v[92:93], v[92:93], 0.5, v[146:147] op_sel_hi:[1,0,1]
	v_pk_fma_f32 v[94:95], v[94:95], 0.5, v[178:179] op_sel_hi:[1,0,1]
	s_add_u32 s16, s16, 0x20000
	s_addc_u32 s17, s17, 0
	global_store_dwordx4 v139, v[92:95], s[16:17] offset:0
	s_waitcnt vmcnt(31)
	v_lshlrev_b32_e32 v146, 16, v180
	v_and_b32_e32 v147, 0xffff0000, v180
	v_lshlrev_b32_e32 v180, 16, v181
	v_and_b32_e32 v181, 0xffff0000, v181
	v_pk_mul_f32 v[146:147], v[146:147], s[74:75] op_sel_hi:[1,0]
	v_pk_mul_f32 v[180:181], v[180:181], s[74:75] op_sel_hi:[1,0]
	v_pk_fma_f32 v[88:89], v[88:89], 0.5, v[146:147] op_sel_hi:[1,0,1]
	v_pk_fma_f32 v[90:91], v[90:91], 0.5, v[180:181] op_sel_hi:[1,0,1]
	global_store_dwordx4 v139, v[88:91], s[16:17] offset:64
	s_waitcnt vmcnt(31)
	v_lshlrev_b32_e32 v146, 16, v182
	v_and_b32_e32 v147, 0xffff0000, v182
	v_lshlrev_b32_e32 v182, 16, v183
	v_and_b32_e32 v183, 0xffff0000, v183
	v_pk_mul_f32 v[146:147], v[146:147], s[74:75] op_sel_hi:[1,0]
	v_pk_mul_f32 v[182:183], v[182:183], s[74:75] op_sel_hi:[1,0]
	v_pk_fma_f32 v[84:85], v[84:85], 0.5, v[146:147] op_sel_hi:[1,0,1]
	v_pk_fma_f32 v[86:87], v[86:87], 0.5, v[182:183] op_sel_hi:[1,0,1]
	global_store_dwordx4 v139, v[84:87], s[16:17] offset:512
	s_waitcnt vmcnt(31)
	v_lshlrev_b32_e32 v146, 16, v184
	v_and_b32_e32 v147, 0xffff0000, v184
	v_lshlrev_b32_e32 v184, 16, v185
	v_and_b32_e32 v185, 0xffff0000, v185
	v_pk_mul_f32 v[146:147], v[146:147], s[74:75] op_sel_hi:[1,0]
	v_pk_mul_f32 v[184:185], v[184:185], s[74:75] op_sel_hi:[1,0]
	v_pk_fma_f32 v[80:81], v[80:81], 0.5, v[146:147] op_sel_hi:[1,0,1]
	v_pk_fma_f32 v[82:83], v[82:83], 0.5, v[184:185] op_sel_hi:[1,0,1]
	global_store_dwordx4 v139, v[80:83], s[16:17] offset:576
	s_waitcnt vmcnt(31)
	v_lshlrev_b32_e32 v146, 16, v186
	v_and_b32_e32 v147, 0xffff0000, v186
	v_lshlrev_b32_e32 v186, 16, v187
	v_and_b32_e32 v187, 0xffff0000, v187
	v_pk_mul_f32 v[146:147], v[146:147], s[74:75] op_sel_hi:[1,0]
	v_pk_mul_f32 v[186:187], v[186:187], s[74:75] op_sel_hi:[1,0]
	v_pk_fma_f32 v[76:77], v[76:77], 0.5, v[146:147] op_sel_hi:[1,0,1]
	v_pk_fma_f32 v[78:79], v[78:79], 0.5, v[186:187] op_sel_hi:[1,0,1]
	s_add_u32 s16, s16, 0x20000
	s_addc_u32 s17, s17, 0
	global_store_dwordx4 v139, v[76:79], s[16:17] offset:0
	s_waitcnt vmcnt(31)
	v_lshlrev_b32_e32 v146, 16, v188
	v_and_b32_e32 v147, 0xffff0000, v188
	v_lshlrev_b32_e32 v188, 16, v189
	v_and_b32_e32 v189, 0xffff0000, v189
	v_pk_mul_f32 v[146:147], v[146:147], s[74:75] op_sel_hi:[1,0]
	v_pk_mul_f32 v[188:189], v[188:189], s[74:75] op_sel_hi:[1,0]
	v_pk_fma_f32 v[72:73], v[72:73], 0.5, v[146:147] op_sel_hi:[1,0,1]
	v_pk_fma_f32 v[74:75], v[74:75], 0.5, v[188:189] op_sel_hi:[1,0,1]
	global_store_dwordx4 v139, v[72:75], s[16:17] offset:64
	s_waitcnt vmcnt(31)
	v_lshlrev_b32_e32 v146, 16, v190
	v_and_b32_e32 v147, 0xffff0000, v190
	v_lshlrev_b32_e32 v190, 16, v191
	v_and_b32_e32 v191, 0xffff0000, v191
	v_pk_mul_f32 v[146:147], v[146:147], s[74:75] op_sel_hi:[1,0]
	v_pk_mul_f32 v[190:191], v[190:191], s[74:75] op_sel_hi:[1,0]
	v_pk_fma_f32 v[68:69], v[68:69], 0.5, v[146:147] op_sel_hi:[1,0,1]
	v_pk_fma_f32 v[70:71], v[70:71], 0.5, v[190:191] op_sel_hi:[1,0,1]
	global_store_dwordx4 v139, v[68:71], s[16:17] offset:512
	s_waitcnt vmcnt(31)
	v_lshlrev_b32_e32 v146, 16, v192
	v_and_b32_e32 v147, 0xffff0000, v192
	v_lshlrev_b32_e32 v192, 16, v193
	v_and_b32_e32 v193, 0xffff0000, v193
	v_pk_mul_f32 v[146:147], v[146:147], s[74:75] op_sel_hi:[1,0]
	v_pk_mul_f32 v[192:193], v[192:193], s[74:75] op_sel_hi:[1,0]
	v_pk_fma_f32 v[64:65], v[64:65], 0.5, v[146:147] op_sel_hi:[1,0,1]
	v_pk_fma_f32 v[66:67], v[66:67], 0.5, v[192:193] op_sel_hi:[1,0,1]
	global_store_dwordx4 v139, v[64:67], s[16:17] offset:576
	s_waitcnt vmcnt(31)
	v_lshlrev_b32_e32 v146, 16, v194
	v_and_b32_e32 v147, 0xffff0000, v194
	v_lshlrev_b32_e32 v194, 16, v195
	v_and_b32_e32 v195, 0xffff0000, v195
	v_pk_mul_f32 v[146:147], v[146:147], s[74:75] op_sel_hi:[1,0]
	v_pk_mul_f32 v[194:195], v[194:195], s[74:75] op_sel_hi:[1,0]
	v_pk_fma_f32 v[60:61], v[60:61], 0.5, v[146:147] op_sel_hi:[1,0,1]
	v_pk_fma_f32 v[62:63], v[62:63], 0.5, v[194:195] op_sel_hi:[1,0,1]
	s_add_u32 s16, s16, 0xa0000
	s_addc_u32 s17, s17, 0
	global_store_dwordx4 v139, v[60:63], s[16:17] offset:0
	s_waitcnt vmcnt(31)
	v_lshlrev_b32_e32 v146, 16, v208
	v_and_b32_e32 v147, 0xffff0000, v208
	v_lshlrev_b32_e32 v208, 16, v209
	v_and_b32_e32 v209, 0xffff0000, v209
	v_pk_mul_f32 v[146:147], v[146:147], s[74:75] op_sel_hi:[1,0]
	v_pk_mul_f32 v[208:209], v[208:209], s[74:75] op_sel_hi:[1,0]
	v_pk_fma_f32 v[56:57], v[56:57], 0.5, v[146:147] op_sel_hi:[1,0,1]
	v_pk_fma_f32 v[58:59], v[58:59], 0.5, v[208:209] op_sel_hi:[1,0,1]
	global_store_dwordx4 v139, v[56:59], s[16:17] offset:64
	s_waitcnt vmcnt(31)
	v_lshlrev_b32_e32 v146, 16, v210
	v_and_b32_e32 v147, 0xffff0000, v210
	v_lshlrev_b32_e32 v210, 16, v211
	v_and_b32_e32 v211, 0xffff0000, v211
	v_pk_mul_f32 v[146:147], v[146:147], s[74:75] op_sel_hi:[1,0]
	v_pk_mul_f32 v[210:211], v[210:211], s[74:75] op_sel_hi:[1,0]
	v_pk_fma_f32 v[52:53], v[52:53], 0.5, v[146:147] op_sel_hi:[1,0,1]
	v_pk_fma_f32 v[54:55], v[54:55], 0.5, v[210:211] op_sel_hi:[1,0,1]
	global_store_dwordx4 v139, v[52:55], s[16:17] offset:512
	s_waitcnt vmcnt(31)
	v_lshlrev_b32_e32 v146, 16, v212
	v_and_b32_e32 v147, 0xffff0000, v212
	v_lshlrev_b32_e32 v212, 16, v213
	v_and_b32_e32 v213, 0xffff0000, v213
	v_pk_mul_f32 v[146:147], v[146:147], s[74:75] op_sel_hi:[1,0]
	v_pk_mul_f32 v[212:213], v[212:213], s[74:75] op_sel_hi:[1,0]
	v_pk_fma_f32 v[48:49], v[48:49], 0.5, v[146:147] op_sel_hi:[1,0,1]
	v_pk_fma_f32 v[50:51], v[50:51], 0.5, v[212:213] op_sel_hi:[1,0,1]
	global_store_dwordx4 v139, v[48:51], s[16:17] offset:576
	s_waitcnt vmcnt(31)
	v_lshlrev_b32_e32 v146, 16, v214
	v_and_b32_e32 v147, 0xffff0000, v214
	v_lshlrev_b32_e32 v214, 16, v215
	v_and_b32_e32 v215, 0xffff0000, v215
	v_pk_mul_f32 v[146:147], v[146:147], s[74:75] op_sel_hi:[1,0]
	v_pk_mul_f32 v[214:215], v[214:215], s[74:75] op_sel_hi:[1,0]
	v_pk_fma_f32 v[44:45], v[44:45], 0.5, v[146:147] op_sel_hi:[1,0,1]
	v_pk_fma_f32 v[46:47], v[46:47], 0.5, v[214:215] op_sel_hi:[1,0,1]
	s_add_u32 s16, s16, 0x20000
	s_addc_u32 s17, s17, 0
	global_store_dwordx4 v139, v[44:47], s[16:17] offset:0
	s_waitcnt vmcnt(31)
	v_lshlrev_b32_e32 v146, 16, v216
	v_and_b32_e32 v147, 0xffff0000, v216
	v_lshlrev_b32_e32 v216, 16, v217
	v_and_b32_e32 v217, 0xffff0000, v217
	v_pk_mul_f32 v[146:147], v[146:147], s[74:75] op_sel_hi:[1,0]
	v_pk_mul_f32 v[216:217], v[216:217], s[74:75] op_sel_hi:[1,0]
	v_pk_fma_f32 v[40:41], v[40:41], 0.5, v[146:147] op_sel_hi:[1,0,1]
	v_pk_fma_f32 v[42:43], v[42:43], 0.5, v[216:217] op_sel_hi:[1,0,1]
	global_store_dwordx4 v139, v[40:43], s[16:17] offset:64
	s_waitcnt vmcnt(31)
	v_lshlrev_b32_e32 v146, 16, v218
	v_and_b32_e32 v147, 0xffff0000, v218
	v_lshlrev_b32_e32 v218, 16, v219
	v_and_b32_e32 v219, 0xffff0000, v219
	v_pk_mul_f32 v[146:147], v[146:147], s[74:75] op_sel_hi:[1,0]
	v_pk_mul_f32 v[218:219], v[218:219], s[74:75] op_sel_hi:[1,0]
	v_pk_fma_f32 v[36:37], v[36:37], 0.5, v[146:147] op_sel_hi:[1,0,1]
	v_pk_fma_f32 v[38:39], v[38:39], 0.5, v[218:219] op_sel_hi:[1,0,1]
	global_store_dwordx4 v139, v[36:39], s[16:17] offset:512
	s_waitcnt vmcnt(31)
	v_lshlrev_b32_e32 v146, 16, v220
	v_and_b32_e32 v147, 0xffff0000, v220
	v_lshlrev_b32_e32 v220, 16, v221
	v_and_b32_e32 v221, 0xffff0000, v221
	v_pk_mul_f32 v[146:147], v[146:147], s[74:75] op_sel_hi:[1,0]
	v_pk_mul_f32 v[220:221], v[220:221], s[74:75] op_sel_hi:[1,0]
	v_pk_fma_f32 v[32:33], v[32:33], 0.5, v[146:147] op_sel_hi:[1,0,1]
	v_pk_fma_f32 v[34:35], v[34:35], 0.5, v[220:221] op_sel_hi:[1,0,1]
	global_store_dwordx4 v139, v[32:35], s[16:17] offset:576
	s_waitcnt vmcnt(31)
	v_lshlrev_b32_e32 v146, 16, v222
	v_and_b32_e32 v147, 0xffff0000, v222
	v_lshlrev_b32_e32 v222, 16, v223
	v_and_b32_e32 v223, 0xffff0000, v223
	v_pk_mul_f32 v[146:147], v[146:147], s[74:75] op_sel_hi:[1,0]
	v_pk_mul_f32 v[222:223], v[222:223], s[74:75] op_sel_hi:[1,0]
	v_pk_fma_f32 v[28:29], v[28:29], 0.5, v[146:147] op_sel_hi:[1,0,1]
	v_pk_fma_f32 v[30:31], v[30:31], 0.5, v[222:223] op_sel_hi:[1,0,1]
	s_add_u32 s16, s16, 0x20000
	s_addc_u32 s17, s17, 0
	global_store_dwordx4 v139, v[28:31], s[16:17] offset:0
	s_waitcnt vmcnt(31)
	v_lshlrev_b32_e32 v146, 16, v224
	v_and_b32_e32 v147, 0xffff0000, v224
	v_lshlrev_b32_e32 v224, 16, v225
	v_and_b32_e32 v225, 0xffff0000, v225
	v_pk_mul_f32 v[146:147], v[146:147], s[74:75] op_sel_hi:[1,0]
	v_pk_mul_f32 v[224:225], v[224:225], s[74:75] op_sel_hi:[1,0]
	v_pk_fma_f32 v[24:25], v[24:25], 0.5, v[146:147] op_sel_hi:[1,0,1]
	v_pk_fma_f32 v[26:27], v[26:27], 0.5, v[224:225] op_sel_hi:[1,0,1]
	global_store_dwordx4 v139, v[24:27], s[16:17] offset:64
	s_waitcnt vmcnt(31)
	v_lshlrev_b32_e32 v146, 16, v226
	v_and_b32_e32 v147, 0xffff0000, v226
	v_lshlrev_b32_e32 v226, 16, v227
	v_and_b32_e32 v227, 0xffff0000, v227
	v_pk_mul_f32 v[146:147], v[146:147], s[74:75] op_sel_hi:[1,0]
	v_pk_mul_f32 v[226:227], v[226:227], s[74:75] op_sel_hi:[1,0]
	v_pk_fma_f32 v[20:21], v[20:21], 0.5, v[146:147] op_sel_hi:[1,0,1]
	v_pk_fma_f32 v[22:23], v[22:23], 0.5, v[226:227] op_sel_hi:[1,0,1]
	global_store_dwordx4 v139, v[20:23], s[16:17] offset:512
	s_waitcnt vmcnt(31)
	v_lshlrev_b32_e32 v146, 16, v228
	v_and_b32_e32 v147, 0xffff0000, v228
	v_lshlrev_b32_e32 v228, 16, v229
	v_and_b32_e32 v229, 0xffff0000, v229
	v_pk_mul_f32 v[146:147], v[146:147], s[74:75] op_sel_hi:[1,0]
	v_pk_mul_f32 v[228:229], v[228:229], s[74:75] op_sel_hi:[1,0]
	v_pk_fma_f32 v[16:17], v[16:17], 0.5, v[146:147] op_sel_hi:[1,0,1]
	v_pk_fma_f32 v[18:19], v[18:19], 0.5, v[228:229] op_sel_hi:[1,0,1]
	global_store_dwordx4 v139, v[16:19], s[16:17] offset:576
	s_waitcnt vmcnt(31)
	v_lshlrev_b32_e32 v146, 16, v230
	v_and_b32_e32 v147, 0xffff0000, v230
	v_lshlrev_b32_e32 v230, 16, v231
	v_and_b32_e32 v231, 0xffff0000, v231
	v_pk_mul_f32 v[146:147], v[146:147], s[74:75] op_sel_hi:[1,0]
	v_pk_mul_f32 v[230:231], v[230:231], s[74:75] op_sel_hi:[1,0]
	v_pk_fma_f32 v[12:13], v[12:13], 0.5, v[146:147] op_sel_hi:[1,0,1]
	v_pk_fma_f32 v[14:15], v[14:15], 0.5, v[230:231] op_sel_hi:[1,0,1]
	s_add_u32 s16, s16, 0x20000
	s_addc_u32 s17, s17, 0
	global_store_dwordx4 v139, v[12:15], s[16:17] offset:0
	s_waitcnt vmcnt(30)
	v_lshlrev_b32_e32 v146, 16, v148
	v_and_b32_e32 v147, 0xffff0000, v148
	v_lshlrev_b32_e32 v148, 16, v149
	v_and_b32_e32 v149, 0xffff0000, v149
	v_pk_mul_f32 v[146:147], v[146:147], s[74:75] op_sel_hi:[1,0]
	v_pk_mul_f32 v[148:149], v[148:149], s[74:75] op_sel_hi:[1,0]
	v_pk_fma_f32 v[8:9], v[8:9], 0.5, v[146:147] op_sel_hi:[1,0,1]
	v_pk_fma_f32 v[10:11], v[10:11], 0.5, v[148:149] op_sel_hi:[1,0,1]
	global_store_dwordx4 v139, v[8:11], s[16:17] offset:64
	s_waitcnt vmcnt(29)
	v_lshlrev_b32_e32 v146, 16, v150
	v_and_b32_e32 v147, 0xffff0000, v150
	v_lshlrev_b32_e32 v150, 16, v151
	v_and_b32_e32 v151, 0xffff0000, v151
	v_pk_mul_f32 v[146:147], v[146:147], s[74:75] op_sel_hi:[1,0]
	v_pk_mul_f32 v[150:151], v[150:151], s[74:75] op_sel_hi:[1,0]
	v_pk_fma_f32 v[4:5], v[4:5], 0.5, v[146:147] op_sel_hi:[1,0,1]
	v_pk_fma_f32 v[6:7], v[6:7], 0.5, v[150:151] op_sel_hi:[1,0,1]
	global_store_dwordx4 v139, v[4:7], s[16:17] offset:512
	s_waitcnt vmcnt(28)
	v_lshlrev_b32_e32 v146, 16, v152
	v_and_b32_e32 v147, 0xffff0000, v152
	v_lshlrev_b32_e32 v152, 16, v153
	v_and_b32_e32 v153, 0xffff0000, v153
	v_pk_mul_f32 v[146:147], v[146:147], s[74:75] op_sel_hi:[1,0]
	v_pk_mul_f32 v[152:153], v[152:153], s[74:75] op_sel_hi:[1,0]
	v_pk_fma_f32 v[0:1], v[0:1], 0.5, v[146:147] op_sel_hi:[1,0,1]
	v_pk_fma_f32 v[2:3], v[2:3], 0.5, v[152:153] op_sel_hi:[1,0,1]
	global_store_dwordx4 v139, v[0:3], s[16:17] offset:576
	s_mov_b64 s[16:17], s[12:13]
	s_mov_b64 s[14:15], s[10:11]
	s_and_b64 vcc, exec, s[8:9]
	s_cbranch_vccz .LBB0_118
	s_waitcnt vmcnt(0)
	s_cmpk_gt_u32 s1, 0xff
	s_cbranch_scc1 .LBB0_133
	s_barrier

.LBB0_167:
	s_add_u32 s22, s20, 0x100
	s_addc_u32 s23, s21, 0
	s_add_i32 s46, 0, 0x10000
	v_add_u32_e32 v140, s46, v143
	ds_read_b128 v[136:139], v140
	ds_read_b128 v[146:149], v140 offset:1024
	ds_read_b128 v[150:153], v140 offset:2048
	ds_read_b128 v[154:157], v140 offset:3072
	s_cmp_eq_u32 s45, 28
	s_cselect_b32 s27, s13, s23
	s_cselect_b32 s26, s41, s22
	s_cselect_b32 s25, s11, s44
	s_cselect_b32 s24, s42, s43
	v_lshl_add_u64 v[140:141], s[20:21], 0, v[132:133]
	s_add_i32 m0, s19, 0xc000
	ds_read_b128 v[158:161], v145
	ds_read_b128 v[176:179], v145 offset:1024
	ds_read_b128 v[180:183], v145 offset:2048
	ds_read_b128 v[184:187], v145 offset:3072
	ds_read_b128 v[188:191], v145 offset:4096
	ds_read_b128 v[192:195], v145 offset:5120
	ds_read_b128 v[208:211], v145 offset:6144
	ds_read_b128 v[212:215], v145 offset:7168
	global_load_lds_dwordx4 v[140:141], off
	v_lshl_add_u64 v[140:141], s[20:21], 0, v[134:135]
	s_add_i32 m0, s19, 0xe000
	s_nop 0
	global_load_lds_dwordx4 v[140:141], off
	s_waitcnt lgkmcnt(8)
	s_barrier
	s_waitcnt lgkmcnt(0)
	s_setprio 1
	s_waitcnt lgkmcnt(0)
	v_mfma_f32_16x16x32_bf16 v[124:127], v[136:139], v[158:161], v[124:127]
	v_mfma_f32_16x16x32_bf16 v[120:123], v[150:153], v[158:161], v[120:123]
	v_mfma_f32_16x16x32_bf16 v[108:111], v[136:139], v[180:183], v[108:111]
	v_mfma_f32_16x16x32_bf16 v[104:107], v[150:153], v[180:183], v[104:107]
	v_mfma_f32_16x16x32_bf16 v[92:95], v[136:139], v[188:191], v[92:95]
	v_mfma_f32_16x16x32_bf16 v[88:91], v[150:153], v[188:191], v[88:91]
	v_mfma_f32_16x16x32_bf16 v[76:79], v[136:139], v[208:211], v[76:79]
	v_mfma_f32_16x16x32_bf16 v[72:75], v[150:153], v[208:211], v[72:75]
	v_mfma_f32_16x16x32_bf16 v[124:127], v[146:149], v[176:179], v[124:127]
	v_mfma_f32_16x16x32_bf16 v[120:123], v[154:157], v[176:179], v[120:123]
	v_mfma_f32_16x16x32_bf16 v[108:111], v[146:149], v[184:187], v[108:111]
	v_mfma_f32_16x16x32_bf16 v[104:107], v[154:157], v[184:187], v[104:107]
	v_mfma_f32_16x16x32_bf16 v[92:95], v[146:149], v[192:195], v[92:95]
	v_mfma_f32_16x16x32_bf16 v[88:91], v[154:157], v[192:195], v[88:91]
	v_mfma_f32_16x16x32_bf16 v[76:79], v[146:149], v[212:215], v[76:79]
	v_mfma_f32_16x16x32_bf16 v[72:75], v[154:157], v[212:215], v[72:75]
	s_setprio 0
	s_barrier
	s_add_i32 s47, 0, 0x14000
	v_add_u32_e32 v140, s47, v143
	s_add_i32 s20, s46, s31
	ds_read_b128 v[216:219], v140
	ds_read_b128 v[220:223], v140 offset:1024
	ds_read_b128 v[224:227], v140 offset:2048
	ds_read_b128 v[228:231], v140 offset:3072
	v_lshl_add_u64 v[140:141], s[24:25], 0, v[128:129]
	s_mov_b32 m0, s20
	v_lshl_add_u64 v[232:233], s[24:25], 0, v[130:131]
	global_load_lds_dwordx4 v[140:141], off
	s_add_i32 m0, s20, 0x2000
	s_nop 0
	global_load_lds_dwordx4 v[232:233], off
	s_barrier
	s_waitcnt lgkmcnt(0)
	s_setprio 1
	s_waitcnt lgkmcnt(0)
	v_mfma_f32_16x16x32_bf16 v[116:119], v[216:219], v[158:161], v[116:119]
	v_mfma_f32_16x16x32_bf16 v[112:115], v[224:227], v[158:161], v[112:115]
	v_mfma_f32_16x16x32_bf16 v[100:103], v[216:219], v[180:183], v[100:103]
	v_mfma_f32_16x16x32_bf16 v[96:99], v[224:227], v[180:183], v[96:99]
	v_mfma_f32_16x16x32_bf16 v[84:87], v[216:219], v[188:191], v[84:87]
	v_mfma_f32_16x16x32_bf16 v[80:83], v[224:227], v[188:191], v[80:83]
	v_mfma_f32_16x16x32_bf16 v[68:71], v[216:219], v[208:211], v[68:71]
	v_mfma_f32_16x16x32_bf16 v[64:67], v[224:227], v[208:211], v[64:67]
	v_mfma_f32_16x16x32_bf16 v[116:119], v[220:223], v[176:179], v[116:119]
	v_mfma_f32_16x16x32_bf16 v[112:115], v[228:231], v[176:179], v[112:115]
	v_mfma_f32_16x16x32_bf16 v[100:103], v[220:223], v[184:187], v[100:103]
	v_mfma_f32_16x16x32_bf16 v[96:99], v[228:231], v[184:187], v[96:99]
	v_mfma_f32_16x16x32_bf16 v[84:87], v[220:223], v[192:195], v[84:87]
	v_mfma_f32_16x16x32_bf16 v[80:83], v[228:231], v[192:195], v[80:83]
	v_mfma_f32_16x16x32_bf16 v[68:71], v[220:223], v[212:215], v[68:71]
	v_mfma_f32_16x16x32_bf16 v[64:67], v[228:231], v[212:215], v[64:67]
	s_setprio 0
	s_mov_b32 m0, s19
	v_lshl_add_u64 v[234:235], s[26:27], 0, v[128:129]
	s_barrier
	ds_read_b128 v[158:161], v145 offset:16384
	ds_read_b128 v[176:179], v145 offset:17408
	ds_read_b128 v[180:183], v145 offset:18432
	ds_read_b128 v[184:187], v145 offset:19456
	ds_read_b128 v[188:191], v145 offset:20480
	ds_read_b128 v[192:195], v145 offset:21504
	ds_read_b128 v[208:211], v145 offset:22528
	ds_read_b128 v[212:215], v145 offset:23552
	global_load_lds_dwordx4 v[234:235], off
	v_lshl_add_u64 v[236:237], s[26:27], 0, v[130:131]
	s_mov_b32 m0, s34
	s_nop 0
	global_load_lds_dwordx4 v[236:237], off
	s_barrier
	s_waitcnt lgkmcnt(0)
	s_setprio 1
	s_waitcnt lgkmcnt(0)
	v_mfma_f32_16x16x32_bf16 v[60:63], v[136:139], v[158:161], v[60:63]
	v_mfma_f32_16x16x32_bf16 v[56:59], v[150:153], v[158:161], v[56:59]
	v_mfma_f32_16x16x32_bf16 v[52:55], v[136:139], v[180:183], v[52:55]
	v_mfma_f32_16x16x32_bf16 v[48:51], v[150:153], v[180:183], v[48:51]
	v_mfma_f32_16x16x32_bf16 v[36:39], v[136:139], v[188:191], v[36:39]
	v_mfma_f32_16x16x32_bf16 v[32:35], v[150:153], v[188:191], v[32:35]
	v_mfma_f32_16x16x32_bf16 v[12:15], v[136:139], v[208:211], v[12:15]
	v_mfma_f32_16x16x32_bf16 v[8:11], v[150:153], v[208:211], v[8:11]
	v_mfma_f32_16x16x32_bf16 v[60:63], v[146:149], v[176:179], v[60:63]
	v_mfma_f32_16x16x32_bf16 v[56:59], v[154:157], v[176:179], v[56:59]
	v_mfma_f32_16x16x32_bf16 v[52:55], v[146:149], v[184:187], v[52:55]
	v_mfma_f32_16x16x32_bf16 v[48:51], v[154:157], v[184:187], v[48:51]
	v_mfma_f32_16x16x32_bf16 v[36:39], v[146:149], v[192:195], v[36:39]
	v_mfma_f32_16x16x32_bf16 v[32:35], v[154:157], v[192:195], v[32:35]
	v_mfma_f32_16x16x32_bf16 v[12:15], v[146:149], v[212:215], v[12:15]
	v_mfma_f32_16x16x32_bf16 v[8:11], v[154:157], v[212:215], v[8:11]
	s_setprio 0
	s_barrier
	s_add_u32 s20, s24, 0x80000
	s_addc_u32 s21, s25, 0
	s_add_i32 s46, s47, s31
	v_lshl_add_u64 v[136:137], s[20:21], 0, v[128:129]
	s_mov_b32 m0, s46
	s_nop 0
	global_load_lds_dwordx4 v[136:137], off
	v_lshl_add_u64 v[136:137], s[20:21], 0, v[130:131]
	s_add_i32 m0, s46, 0x2000
	s_nop 0
	global_load_lds_dwordx4 v[136:137], off
	s_waitcnt vmcnt(6)
	s_barrier
	s_setprio 1
	v_mfma_f32_16x16x32_bf16 v[44:47], v[216:219], v[158:161], v[44:47]
	v_mfma_f32_16x16x32_bf16 v[40:43], v[224:227], v[158:161], v[40:43]
	v_mfma_f32_16x16x32_bf16 v[28:31], v[216:219], v[180:183], v[28:31]
	v_mfma_f32_16x16x32_bf16 v[24:27], v[224:227], v[180:183], v[24:27]
	v_mfma_f32_16x16x32_bf16 v[20:23], v[216:219], v[188:191], v[20:23]
	v_mfma_f32_16x16x32_bf16 v[16:19], v[224:227], v[188:191], v[16:19]
	v_mfma_f32_16x16x32_bf16 v[4:7], v[216:219], v[208:211], v[4:7]
	v_mfma_f32_16x16x32_bf16 v[0:3], v[224:227], v[208:211], v[0:3]
	v_mfma_f32_16x16x32_bf16 v[44:47], v[220:223], v[176:179], v[44:47]
	v_mfma_f32_16x16x32_bf16 v[40:43], v[228:231], v[176:179], v[40:43]
	v_mfma_f32_16x16x32_bf16 v[28:31], v[220:223], v[184:187], v[28:31]
	v_mfma_f32_16x16x32_bf16 v[24:27], v[228:231], v[184:187], v[24:27]
	v_mfma_f32_16x16x32_bf16 v[20:23], v[220:223], v[192:195], v[20:23]
	v_mfma_f32_16x16x32_bf16 v[16:19], v[228:231], v[192:195], v[16:19]
	v_mfma_f32_16x16x32_bf16 v[4:7], v[220:223], v[212:215], v[4:7]
	v_mfma_f32_16x16x32_bf16 v[0:3], v[228:231], v[212:215], v[0:3]
	s_setprio 0
	s_add_i32 s46, 0, 0x18000
	v_add_u32_e32 v154, s46, v143
	s_barrier
	ds_read_b128 v[136:139], v154
	ds_read_b128 v[146:149], v154 offset:1024
	ds_read_b128 v[150:153], v154 offset:2048
	ds_read_b128 v[154:157], v154 offset:3072
	s_add_u32 s20, s26, 0x80000
	s_addc_u32 s21, s27, 0
	s_mov_b32 m0, s35
	v_lshl_add_u64 v[216:217], s[20:21], 0, v[128:129]
	ds_read_b128 v[158:161], v145 offset:32768
	ds_read_b128 v[176:179], v145 offset:33792
	ds_read_b128 v[180:183], v145 offset:34816
	ds_read_b128 v[184:187], v145 offset:35840
	ds_read_b128 v[188:191], v145 offset:36864
	ds_read_b128 v[192:195], v145 offset:37888
	ds_read_b128 v[208:211], v145 offset:38912
	ds_read_b128 v[212:215], v145 offset:39936
	global_load_lds_dwordx4 v[216:217], off
	v_lshl_add_u64 v[216:217], s[20:21], 0, v[130:131]
	s_mov_b32 m0, s36
	s_nop 0
	global_load_lds_dwordx4 v[216:217], off
	s_waitcnt lgkmcnt(8)
	s_barrier
	s_waitcnt lgkmcnt(0)
	s_setprio 1
	s_waitcnt lgkmcnt(0)
	v_mfma_f32_16x16x32_bf16 v[124:127], v[136:139], v[158:161], v[124:127]
	v_mfma_f32_16x16x32_bf16 v[120:123], v[150:153], v[158:161], v[120:123]
	v_mfma_f32_16x16x32_bf16 v[108:111], v[136:139], v[180:183], v[108:111]
	v_mfma_f32_16x16x32_bf16 v[104:107], v[150:153], v[180:183], v[104:107]
	v_mfma_f32_16x16x32_bf16 v[92:95], v[136:139], v[188:191], v[92:95]
	v_mfma_f32_16x16x32_bf16 v[88:91], v[150:153], v[188:191], v[88:91]
	v_mfma_f32_16x16x32_bf16 v[76:79], v[136:139], v[208:211], v[76:79]
	v_mfma_f32_16x16x32_bf16 v[72:75], v[150:153], v[208:211], v[72:75]
	v_mfma_f32_16x16x32_bf16 v[124:127], v[146:149], v[176:179], v[124:127]
	v_mfma_f32_16x16x32_bf16 v[120:123], v[154:157], v[176:179], v[120:123]
	v_mfma_f32_16x16x32_bf16 v[108:111], v[146:149], v[184:187], v[108:111]
	v_mfma_f32_16x16x32_bf16 v[104:107], v[154:157], v[184:187], v[104:107]
	v_mfma_f32_16x16x32_bf16 v[92:95], v[146:149], v[192:195], v[92:95]
	v_mfma_f32_16x16x32_bf16 v[88:91], v[154:157], v[192:195], v[88:91]
	v_mfma_f32_16x16x32_bf16 v[76:79], v[146:149], v[212:215], v[76:79]
	v_mfma_f32_16x16x32_bf16 v[72:75], v[154:157], v[212:215], v[72:75]
	s_setprio 0
	s_barrier
	s_add_i32 s26, 0, 0x1c000
	s_add_i32 s20, s46, s31
	v_add_u32_e32 v196, s26, v143
	v_lshl_add_u64 v[140:141], v[140:141], 0, s[6:7]
	s_mov_b32 m0, s20
	ds_read_b128 v[216:219], v196
	ds_read_b128 v[220:223], v196 offset:1024
	ds_read_b128 v[224:227], v196 offset:2048
	ds_read_b128 v[228:231], v196 offset:3072
	global_load_lds_dwordx4 v[140:141], off
	v_lshl_add_u64 v[140:141], v[232:233], 0, s[6:7]
	s_add_i32 m0, s20, 0x2000
	s_nop 0
	global_load_lds_dwordx4 v[140:141], off
	s_barrier
	s_waitcnt lgkmcnt(0)
	s_setprio 1
	s_waitcnt lgkmcnt(0)
	v_mfma_f32_16x16x32_bf16 v[116:119], v[216:219], v[158:161], v[116:119]
	v_mfma_f32_16x16x32_bf16 v[112:115], v[224:227], v[158:161], v[112:115]
	v_mfma_f32_16x16x32_bf16 v[100:103], v[216:219], v[180:183], v[100:103]
	v_mfma_f32_16x16x32_bf16 v[96:99], v[224:227], v[180:183], v[96:99]
	v_mfma_f32_16x16x32_bf16 v[84:87], v[216:219], v[188:191], v[84:87]
	v_mfma_f32_16x16x32_bf16 v[80:83], v[224:227], v[188:191], v[80:83]
	v_mfma_f32_16x16x32_bf16 v[68:71], v[216:219], v[208:211], v[68:71]
	v_mfma_f32_16x16x32_bf16 v[64:67], v[224:227], v[208:211], v[64:67]
	v_mfma_f32_16x16x32_bf16 v[116:119], v[220:223], v[176:179], v[116:119]
	v_mfma_f32_16x16x32_bf16 v[112:115], v[228:231], v[176:179], v[112:115]
	v_mfma_f32_16x16x32_bf16 v[100:103], v[220:223], v[184:187], v[100:103]
	v_mfma_f32_16x16x32_bf16 v[96:99], v[228:231], v[184:187], v[96:99]
	v_mfma_f32_16x16x32_bf16 v[84:87], v[220:223], v[192:195], v[84:87]
	v_mfma_f32_16x16x32_bf16 v[80:83], v[228:231], v[192:195], v[80:83]
	v_mfma_f32_16x16x32_bf16 v[68:71], v[220:223], v[212:215], v[68:71]
	v_mfma_f32_16x16x32_bf16 v[64:67], v[228:231], v[212:215], v[64:67]
	s_setprio 0
	s_mov_b32 m0, s37
	v_lshl_add_u64 v[140:141], v[234:235], 0, s[6:7]
	s_barrier
	ds_read_b128 v[158:161], v145 offset:49152
	ds_read_b128 v[176:179], v145 offset:50176
	ds_read_b128 v[180:183], v145 offset:51200
	ds_read_b128 v[184:187], v145 offset:52224
	ds_read_b128 v[188:191], v145 offset:53248
	ds_read_b128 v[192:195], v145 offset:54272
	ds_read_b128 v[208:211], v145 offset:55296
	ds_read_b128 v[212:215], v145 offset:56320
	global_load_lds_dwordx4 v[140:141], off
	v_lshl_add_u64 v[140:141], v[236:237], 0, s[6:7]
	s_mov_b32 m0, s38
	s_nop 0
	global_load_lds_dwordx4 v[140:141], off
	s_barrier
	s_waitcnt lgkmcnt(0)
	s_setprio 1
	s_waitcnt lgkmcnt(0)
	v_mfma_f32_16x16x32_bf16 v[60:63], v[136:139], v[158:161], v[60:63]
	v_mfma_f32_16x16x32_bf16 v[56:59], v[150:153], v[158:161], v[56:59]
	v_mfma_f32_16x16x32_bf16 v[52:55], v[136:139], v[180:183], v[52:55]
	v_mfma_f32_16x16x32_bf16 v[48:51], v[150:153], v[180:183], v[48:51]
	v_mfma_f32_16x16x32_bf16 v[36:39], v[136:139], v[188:191], v[36:39]
	v_mfma_f32_16x16x32_bf16 v[32:35], v[150:153], v[188:191], v[32:35]
	v_mfma_f32_16x16x32_bf16 v[12:15], v[136:139], v[208:211], v[12:15]
	v_mfma_f32_16x16x32_bf16 v[8:11], v[150:153], v[208:211], v[8:11]
	v_mfma_f32_16x16x32_bf16 v[60:63], v[146:149], v[176:179], v[60:63]
	v_mfma_f32_16x16x32_bf16 v[56:59], v[154:157], v[176:179], v[56:59]
	v_mfma_f32_16x16x32_bf16 v[52:55], v[146:149], v[184:187], v[52:55]
	v_mfma_f32_16x16x32_bf16 v[48:51], v[154:157], v[184:187], v[48:51]
	v_mfma_f32_16x16x32_bf16 v[36:39], v[146:149], v[192:195], v[36:39]
	v_mfma_f32_16x16x32_bf16 v[32:35], v[154:157], v[192:195], v[32:35]
	v_mfma_f32_16x16x32_bf16 v[12:15], v[146:149], v[212:215], v[12:15]
	v_mfma_f32_16x16x32_bf16 v[8:11], v[154:157], v[212:215], v[8:11]
	s_setprio 0
	s_barrier
	s_add_u32 s20, s24, 0x80080
	s_addc_u32 s21, s25, 0
	s_add_i32 s24, s26, s31
	v_lshl_add_u64 v[136:137], s[20:21], 0, v[128:129]
	s_mov_b32 m0, s24
	s_nop 0
	global_load_lds_dwordx4 v[136:137], off
	v_lshl_add_u64 v[136:137], s[20:21], 0, v[130:131]
	s_add_i32 m0, s24, 0x2000
	s_nop 0
	global_load_lds_dwordx4 v[136:137], off
	s_waitcnt vmcnt(6)
	s_barrier
	s_setprio 1
	v_mfma_f32_16x16x32_bf16 v[44:47], v[216:219], v[158:161], v[44:47]
	v_mfma_f32_16x16x32_bf16 v[40:43], v[224:227], v[158:161], v[40:43]
	v_mfma_f32_16x16x32_bf16 v[28:31], v[216:219], v[180:183], v[28:31]
	v_mfma_f32_16x16x32_bf16 v[24:27], v[224:227], v[180:183], v[24:27]
	v_mfma_f32_16x16x32_bf16 v[20:23], v[216:219], v[188:191], v[20:23]
	v_mfma_f32_16x16x32_bf16 v[16:19], v[224:227], v[188:191], v[16:19]
	v_mfma_f32_16x16x32_bf16 v[4:7], v[216:219], v[208:211], v[4:7]
	v_mfma_f32_16x16x32_bf16 v[0:3], v[224:227], v[208:211], v[0:3]
	v_mfma_f32_16x16x32_bf16 v[44:47], v[220:223], v[176:179], v[44:47]
	v_mfma_f32_16x16x32_bf16 v[40:43], v[228:231], v[176:179], v[40:43]
	v_mfma_f32_16x16x32_bf16 v[28:31], v[220:223], v[184:187], v[28:31]
	v_mfma_f32_16x16x32_bf16 v[24:27], v[228:231], v[184:187], v[24:27]
	v_mfma_f32_16x16x32_bf16 v[20:23], v[220:223], v[192:195], v[20:23]
	v_mfma_f32_16x16x32_bf16 v[16:19], v[228:231], v[192:195], v[16:19]
	v_mfma_f32_16x16x32_bf16 v[4:7], v[220:223], v[212:215], v[4:7]
	v_mfma_f32_16x16x32_bf16 v[0:3], v[228:231], v[212:215], v[0:3]
	s_setprio 0
	s_add_i32 s45, s45, 2
	s_add_u32 s43, s43, 0x100
	s_addc_u32 s44, s44, 0
	s_cmp_gt_u32 s45, 29
	s_mov_b64 s[20:21], s[22:23]
	s_barrier
	s_cbranch_scc0 .LBB0_167
	v_lshl_add_u32 v136, s18, 8, v142
	v_lshl_or_b32 v137, s40, 8, v144
	v_lshl_add_u32 v137, v136, 11, v137
	v_lshlrev_b32_e32 v138, 1, v137
	v_lshlrev_b32_e32 v139, 2, v137
	s_mov_b32 s40, s10
	s_mov_b32 s18, s12
	s_mov_b32 s11, 0x160000
	s_mov_b64 s[20:21], s[76:77]
	s_mov_b64 s[22:23], s[76:77]
	global_load_dwordx4 v[148:151], v139, s[20:21] offset:0
	global_load_dwordx4 v[152:155], v139, s[20:21] offset:64
	global_load_dwordx4 v[156:159], v139, s[20:21] offset:512
	global_load_dwordx4 v[176:179], v139, s[20:21] offset:576
	s_add_u32 s20, s20, 0x20000
	s_addc_u32 s21, s21, 0
	global_load_dwordx4 v[180:183], v139, s[20:21] offset:0
	global_load_dwordx4 v[184:187], v139, s[20:21] offset:64
	global_load_dwordx4 v[188:191], v139, s[20:21] offset:512
	global_load_dwordx4 v[192:195], v139, s[20:21] offset:576
	s_add_u32 s20, s20, 0x20000
	s_addc_u32 s21, s21, 0
	global_load_dwordx4 v[208:211], v139, s[20:21] offset:0
	global_load_dwordx4 v[212:215], v139, s[20:21] offset:64
	global_load_dwordx4 v[216:219], v139, s[20:21] offset:512
	global_load_dwordx4 v[220:223], v139, s[20:21] offset:576
	s_add_u32 s20, s20, 0x20000
	s_addc_u32 s21, s21, 0
	global_load_dwordx4 v[224:227], v139, s[20:21] offset:0
	global_load_dwordx4 v[228:231], v139, s[20:21] offset:64
	s_waitcnt vmcnt(13)
	v_pk_fma_f32 v[124:125], v[148:149], s[74:75], v[124:125] op_sel_hi:[1,0,1]
	v_pk_fma_f32 v[126:127], v[150:151], s[74:75], v[126:127] op_sel_hi:[1,0,1]
	global_store_dwordx4 v139, v[124:127], s[22:23] offset:0
	global_load_dwordx4 v[148:151], v139, s[20:21] offset:512
	s_waitcnt vmcnt(14)
	v_pk_fma_f32 v[120:121], v[152:153], s[74:75], v[120:121] op_sel_hi:[1,0,1]
	v_pk_fma_f32 v[122:123], v[154:155], s[74:75], v[122:123] op_sel_hi:[1,0,1]
	global_store_dwordx4 v139, v[120:123], s[22:23] offset:64
	global_load_dwordx4 v[152:155], v139, s[20:21] offset:576
	s_waitcnt vmcnt(15)
	v_pk_fma_f32 v[116:117], v[156:157], s[74:75], v[116:117] op_sel_hi:[1,0,1]
	v_pk_fma_f32 v[118:119], v[158:159], s[74:75], v[118:119] op_sel_hi:[1,0,1]
	global_store_dwordx4 v139, v[116:119], s[22:23] offset:512
	s_add_u32 s20, s20, 0xa0000
	s_addc_u32 s21, s21, 0
	global_load_dwordx4 v[156:159], v139, s[20:21] offset:0
	s_waitcnt vmcnt(16)
	v_pk_fma_f32 v[112:113], v[176:177], s[74:75], v[112:113] op_sel_hi:[1,0,1]
	v_pk_fma_f32 v[114:115], v[178:179], s[74:75], v[114:115] op_sel_hi:[1,0,1]
	global_store_dwordx4 v139, v[112:115], s[22:23] offset:576
	global_load_dwordx4 v[176:179], v139, s[20:21] offset:64
	s_waitcnt vmcnt(17)
	v_pk_fma_f32 v[108:109], v[180:181], s[74:75], v[108:109] op_sel_hi:[1,0,1]
	v_pk_fma_f32 v[110:111], v[182:183], s[74:75], v[110:111] op_sel_hi:[1,0,1]
	s_add_u32 s22, s22, 0x20000
	s_addc_u32 s23, s23, 0
	global_store_dwordx4 v139, v[108:111], s[22:23] offset:0
	global_load_dwordx4 v[180:183], v139, s[20:21] offset:512
	s_waitcnt vmcnt(18)
	v_pk_fma_f32 v[104:105], v[184:185], s[74:75], v[104:105] op_sel_hi:[1,0,1]
	v_pk_fma_f32 v[106:107], v[186:187], s[74:75], v[106:107] op_sel_hi:[1,0,1]
	global_store_dwordx4 v139, v[104:107], s[22:23] offset:64
	global_load_dwordx4 v[184:187], v139, s[20:21] offset:576
	s_waitcnt vmcnt(19)
	v_pk_fma_f32 v[100:101], v[188:189], s[74:75], v[100:101] op_sel_hi:[1,0,1]
	v_pk_fma_f32 v[102:103], v[190:191], s[74:75], v[102:103] op_sel_hi:[1,0,1]
	global_store_dwordx4 v139, v[100:103], s[22:23] offset:512
	s_add_u32 s20, s20, 0x20000
	s_addc_u32 s21, s21, 0
	global_load_dwordx4 v[188:191], v139, s[20:21] offset:0
	s_waitcnt vmcnt(20)
	v_pk_fma_f32 v[96:97], v[192:193], s[74:75], v[96:97] op_sel_hi:[1,0,1]
	v_pk_fma_f32 v[98:99], v[194:195], s[74:75], v[98:99] op_sel_hi:[1,0,1]
	global_store_dwordx4 v139, v[96:99], s[22:23] offset:576
	global_load_dwordx4 v[192:195], v139, s[20:21] offset:64
	s_waitcnt vmcnt(21)
	v_pk_fma_f32 v[92:93], v[208:209], s[74:75], v[92:93] op_sel_hi:[1,0,1]
	v_pk_fma_f32 v[94:95], v[210:211], s[74:75], v[94:95] op_sel_hi:[1,0,1]
	s_add_u32 s22, s22, 0x20000
	s_addc_u32 s23, s23, 0
	global_store_dwordx4 v139, v[92:95], s[22:23] offset:0
	global_load_dwordx4 v[208:211], v139, s[20:21] offset:512
	s_waitcnt vmcnt(22)
	v_pk_fma_f32 v[88:89], v[212:213], s[74:75], v[88:89] op_sel_hi:[1,0,1]
	v_pk_fma_f32 v[90:91], v[214:215], s[74:75], v[90:91] op_sel_hi:[1,0,1]
	global_store_dwordx4 v139, v[88:91], s[22:23] offset:64
	global_load_dwordx4 v[212:215], v139, s[20:21] offset:576
	s_waitcnt vmcnt(23)
	v_pk_fma_f32 v[84:85], v[216:217], s[74:75], v[84:85] op_sel_hi:[1,0,1]
	v_pk_fma_f32 v[86:87], v[218:219], s[74:75], v[86:87] op_sel_hi:[1,0,1]
	global_store_dwordx4 v139, v[84:87], s[22:23] offset:512
	s_add_u32 s20, s20, 0x20000
	s_addc_u32 s21, s21, 0
	global_load_dwordx4 v[216:219], v139, s[20:21] offset:0
	s_waitcnt vmcnt(24)
	v_pk_fma_f32 v[80:81], v[220:221], s[74:75], v[80:81] op_sel_hi:[1,0,1]
	v_pk_fma_f32 v[82:83], v[222:223], s[74:75], v[82:83] op_sel_hi:[1,0,1]
	global_store_dwordx4 v139, v[80:83], s[22:23] offset:576
	global_load_dwordx4 v[220:223], v139, s[20:21] offset:64
	s_waitcnt vmcnt(25)
	v_pk_fma_f32 v[76:77], v[224:225], s[74:75], v[76:77] op_sel_hi:[1,0,1]
	v_pk_fma_f32 v[78:79], v[226:227], s[74:75], v[78:79] op_sel_hi:[1,0,1]
	s_add_u32 s22, s22, 0x20000
	s_addc_u32 s23, s23, 0
	global_store_dwordx4 v139, v[76:79], s[22:23] offset:0
	global_load_dwordx4 v[224:227], v139, s[20:21] offset:512
	s_waitcnt vmcnt(26)
	v_pk_fma_f32 v[72:73], v[228:229], s[74:75], v[72:73] op_sel_hi:[1,0,1]
	v_pk_fma_f32 v[74:75], v[230:231], s[74:75], v[74:75] op_sel_hi:[1,0,1]
	global_store_dwordx4 v139, v[72:75], s[22:23] offset:64
	global_load_dwordx4 v[228:231], v139, s[20:21] offset:576
	s_waitcnt vmcnt(26)
	v_pk_fma_f32 v[68:69], v[148:149], s[74:75], v[68:69] op_sel_hi:[1,0,1]
	v_pk_fma_f32 v[70:71], v[150:151], s[74:75], v[70:71] op_sel_hi:[1,0,1]
	global_store_dwordx4 v139, v[68:71], s[22:23] offset:512
	s_add_u32 s20, s20, 0x20000
	s_addc_u32 s21, s21, 0
	global_load_dwordx4 v[148:151], v139, s[20:21] offset:0
	s_waitcnt vmcnt(26)
	v_pk_fma_f32 v[64:65], v[152:153], s[74:75], v[64:65] op_sel_hi:[1,0,1]
	v_pk_fma_f32 v[66:67], v[154:155], s[74:75], v[66:67] op_sel_hi:[1,0,1]
	global_store_dwordx4 v139, v[64:67], s[22:23] offset:576
	global_load_dwordx4 v[152:155], v139, s[20:21] offset:64
	s_waitcnt vmcnt(26)
	v_pk_fma_f32 v[60:61], v[156:157], s[74:75], v[60:61] op_sel_hi:[1,0,1]
	v_pk_fma_f32 v[62:63], v[158:159], s[74:75], v[62:63] op_sel_hi:[1,0,1]
	s_add_u32 s22, s22, 0xa0000
	s_addc_u32 s23, s23, 0
	global_store_dwordx4 v139, v[60:63], s[22:23] offset:0
	global_load_dwordx4 v[156:159], v139, s[20:21] offset:512
	s_waitcnt vmcnt(26)
	v_pk_fma_f32 v[56:57], v[176:177], s[74:75], v[56:57] op_sel_hi:[1,0,1]
	v_pk_fma_f32 v[58:59], v[178:179], s[74:75], v[58:59] op_sel_hi:[1,0,1]
	global_store_dwordx4 v139, v[56:59], s[22:23] offset:64
	global_load_dwordx4 v[176:179], v139, s[20:21] offset:576
	s_waitcnt vmcnt(26)
	v_pk_fma_f32 v[44:45], v[180:181], s[74:75], v[44:45] op_sel_hi:[1,0,1]
	v_pk_fma_f32 v[46:47], v[182:183], s[74:75], v[46:47] op_sel_hi:[1,0,1]
	global_store_dwordx4 v139, v[44:47], s[22:23] offset:512
	s_waitcnt vmcnt(25)
	v_pk_fma_f32 v[40:41], v[184:185], s[74:75], v[40:41] op_sel_hi:[1,0,1]
	v_pk_fma_f32 v[42:43], v[186:187], s[74:75], v[42:43] op_sel_hi:[1,0,1]
	global_store_dwordx4 v139, v[40:43], s[22:23] offset:576
	s_waitcnt vmcnt(24)
	v_pk_fma_f32 v[52:53], v[188:189], s[74:75], v[52:53] op_sel_hi:[1,0,1]
	v_pk_fma_f32 v[54:55], v[190:191], s[74:75], v[54:55] op_sel_hi:[1,0,1]
	s_add_u32 s22, s22, 0x20000
	s_addc_u32 s23, s23, 0
	global_store_dwordx4 v139, v[52:55], s[22:23] offset:0
	s_waitcnt vmcnt(23)
	v_pk_fma_f32 v[48:49], v[192:193], s[74:75], v[48:49] op_sel_hi:[1,0,1]
	v_pk_fma_f32 v[50:51], v[194:195], s[74:75], v[50:51] op_sel_hi:[1,0,1]
	global_store_dwordx4 v139, v[48:51], s[22:23] offset:64
	s_waitcnt vmcnt(22)
	v_pk_fma_f32 v[28:29], v[208:209], s[74:75], v[28:29] op_sel_hi:[1,0,1]
	v_pk_fma_f32 v[30:31], v[210:211], s[74:75], v[30:31] op_sel_hi:[1,0,1]
	global_store_dwordx4 v139, v[28:31], s[22:23] offset:512
	s_waitcnt vmcnt(21)
	v_pk_fma_f32 v[24:25], v[212:213], s[74:75], v[24:25] op_sel_hi:[1,0,1]
	v_pk_fma_f32 v[26:27], v[214:215], s[74:75], v[26:27] op_sel_hi:[1,0,1]
	global_store_dwordx4 v139, v[24:27], s[22:23] offset:576
	s_waitcnt vmcnt(20)
	v_pk_fma_f32 v[36:37], v[216:217], s[74:75], v[36:37] op_sel_hi:[1,0,1]
	v_pk_fma_f32 v[38:39], v[218:219], s[74:75], v[38:39] op_sel_hi:[1,0,1]
	s_add_u32 s22, s22, 0x20000
	s_addc_u32 s23, s23, 0
	global_store_dwordx4 v139, v[36:39], s[22:23] offset:0
	s_waitcnt vmcnt(19)
	v_pk_fma_f32 v[32:33], v[220:221], s[74:75], v[32:33] op_sel_hi:[1,0,1]
	v_pk_fma_f32 v[34:35], v[222:223], s[74:75], v[34:35] op_sel_hi:[1,0,1]
	global_store_dwordx4 v139, v[32:35], s[22:23] offset:64
	s_waitcnt vmcnt(18)
	v_pk_fma_f32 v[20:21], v[224:225], s[74:75], v[20:21] op_sel_hi:[1,0,1]
	v_pk_fma_f32 v[22:23], v[226:227], s[74:75], v[22:23] op_sel_hi:[1,0,1]
	global_store_dwordx4 v139, v[20:23], s[22:23] offset:512
	s_waitcnt vmcnt(17)
	v_pk_fma_f32 v[16:17], v[228:229], s[74:75], v[16:17] op_sel_hi:[1,0,1]
	v_pk_fma_f32 v[18:19], v[230:231], s[74:75], v[18:19] op_sel_hi:[1,0,1]
	global_store_dwordx4 v139, v[16:19], s[22:23] offset:576
	s_waitcnt vmcnt(16)
	v_pk_fma_f32 v[12:13], v[148:149], s[74:75], v[12:13] op_sel_hi:[1,0,1]
	v_pk_fma_f32 v[14:15], v[150:151], s[74:75], v[14:15] op_sel_hi:[1,0,1]
	s_add_u32 s22, s22, 0x20000
	s_addc_u32 s23, s23, 0
	global_store_dwordx4 v139, v[12:15], s[22:23] offset:0
	s_waitcnt vmcnt(15)
	v_pk_fma_f32 v[8:9], v[152:153], s[74:75], v[8:9] op_sel_hi:[1,0,1]
	v_pk_fma_f32 v[10:11], v[154:155], s[74:75], v[10:11] op_sel_hi:[1,0,1]
	global_store_dwordx4 v139, v[8:11], s[22:23] offset:64
	s_waitcnt vmcnt(14)
	v_pk_fma_f32 v[4:5], v[156:157], s[74:75], v[4:5] op_sel_hi:[1,0,1]
	v_pk_fma_f32 v[6:7], v[158:159], s[74:75], v[6:7] op_sel_hi:[1,0,1]
	global_store_dwordx4 v139, v[4:7], s[22:23] offset:512
	s_waitcnt vmcnt(13)
	v_pk_fma_f32 v[0:1], v[176:177], s[74:75], v[0:1] op_sel_hi:[1,0,1]
	v_pk_fma_f32 v[2:3], v[178:179], s[74:75], v[2:3] op_sel_hi:[1,0,1]
	global_store_dwordx4 v139, v[0:3], s[22:23] offset:576
	s_mov_b64 s[22:23], s[16:17]
	s_mov_b64 s[20:21], s[14:15]
	s_and_b64 vcc, exec, s[8:9]
	s_cbranch_vccz .LBB0_160
	s_waitcnt vmcnt(0)
	s_cmpk_gt_u32 s1, 0xff
	s_cbranch_scc1 .LBB0_171
	s_barrier

.LBB0_213:
	s_or_b64 exec, exec, s[22:23]
	s_xor_b64 s[22:23], s[10:11], -1
	s_add_i32 s10, 0, 0x10000
	v_lshl_add_u32 v192, v0, 2, s10
	v_cmp_eq_u32_e64 s[10:11], 0, v0
	v_add_u32_e32 v230, s39, v0
	v_mad_i64_i32 v[0:1], s[26:27], v1, s67, 0
	v_lshl_or_b32 v0, v2, 4, v0
	v_mov_b32_e32 v14, v129
	v_mov_b32_e32 v15, v129
	s_lshl_b32 s44, s28, 1
	v_lshl_add_u64 v[180:181], s[20:21], 0, v[0:1]
	v_mov_b32_e32 v0, v129
	v_mov_b32_e32 v1, v129
	v_mov_b32_e32 v2, v129
	v_mov_b32_e32 v3, v129
	v_mov_b32_e32 v4, v129
	s_waitcnt lgkmcnt(0)
	v_mov_b32_e32 v5, v129
	v_mov_b32_e32 v6, v129
	v_mov_b32_e32 v7, v129
	v_mov_b32_e32 v8, v129
	v_mov_b32_e32 v9, v129
	v_mov_b32_e32 v10, v129
	v_mov_b32_e32 v11, v129
	v_mov_b32_e32 v12, v129
	v_mov_b32_e32 v13, v129
	v_mov_b64_e32 v[30:31], v[14:15]
	v_mov_b64_e32 v[46:47], v[14:15]
	v_mov_b64_e32 v[62:63], v[14:15]
	s_add_i32 s44, s44, 2
	s_or_b32 s45, s42, 31
	s_lshl_b32 s46, s41, 3
	s_mov_b32 s47, 0
	v_and_b32_e32 v221, 31, v183
	v_lshrrev_b32_e32 v222, 5, v183
	v_and_b32_e32 v223, 3, v183
	v_lshlrev_b32_e32 v223, 2, v223
	v_bfe_u32 v224, v183, 2, 2
	v_or_b32_e32 v223, v223, v224
	v_add_u32_e32 v225, s46, v222
	v_lshlrev_b32_e32 v226, 8, v221
	v_xor_b32_e32 v227, v225, v223
	v_lshl_add_u32 v209, v227, 4, v226
	v_add_u32_e32 v227, 2, v225
	v_xor_b32_e32 v227, v227, v223
	v_lshl_add_u32 v210, v227, 4, v226
	v_add_u32_e32 v227, 4, v225
	v_xor_b32_e32 v227, v227, v223
	v_lshl_add_u32 v211, v227, 4, v226
	v_add_u32_e32 v227, 6, v225
	v_xor_b32_e32 v227, v227, v223
	v_lshl_add_u32 v212, v227, 4, v226
	v_lshrrev_b32_e32 v227, 3, v183
	v_bfe_u32 v228, v183, 1, 1
	v_and_or_b32 v227, v227, 2, v228
	v_and_b32_e32 v228, 1, v183
	v_lshlrev_b32_e32 v228, 3, v228
	v_lshl_or_b32 v229, v222, 2, v224
	v_lshl_add_u32 v228, v229, 8, v228
	v_xor_b32_e32 v229, v227, v222
	v_lshl_add_u32 v229, v229, 4, v228
	v_lshl_add_u32 v213, v224, 6, v229
	v_xor_b32_e32 v193, 1, v224
	v_lshl_add_u32 v215, v193, 6, v229
	v_xor_b32_e32 v193, 2, v224
	v_lshl_add_u32 v217, v193, 6, v229
	v_xor_b32_e32 v193, 3, v224
	v_lshl_add_u32 v219, v193, 6, v229
	v_add_u32_e32 v229, 2, v222
	v_xor_b32_e32 v229, v227, v229
	v_lshl_add_u32 v229, v229, 4, v228
	v_add_u32_e32 v229, 0x800, v229
	v_lshl_add_u32 v214, v224, 6, v229
	v_xor_b32_e32 v193, 1, v224
	v_lshl_add_u32 v216, v193, 6, v229
	v_xor_b32_e32 v193, 2, v224
	v_lshl_add_u32 v218, v193, 6, v229
	v_xor_b32_e32 v193, 3, v224
	v_lshl_add_u32 v220, v193, 6, v229
	s_addk_i32 s48, 0x80
	v_mov_b32_e32 v232, 0
	v_mov_b32_e32 v235, 0xf149f2ca
	v_mov_b64_e32 v[28:29], v[12:13]
	v_mov_b64_e32 v[26:27], v[10:11]
	v_mov_b64_e32 v[24:25], v[8:9]
	v_mov_b64_e32 v[22:23], v[6:7]
	v_mov_b64_e32 v[20:21], v[4:5]
	v_mov_b64_e32 v[18:19], v[2:3]
	v_mov_b64_e32 v[16:17], v[0:1]
	v_mov_b64_e32 v[44:45], v[12:13]
	v_mov_b64_e32 v[42:43], v[10:11]
	v_mov_b64_e32 v[40:41], v[8:9]
	v_mov_b64_e32 v[38:39], v[6:7]
	v_mov_b64_e32 v[36:37], v[4:5]
	v_mov_b64_e32 v[34:35], v[2:3]
	v_mov_b64_e32 v[32:33], v[0:1]
	v_mov_b64_e32 v[60:61], v[12:13]
	v_mov_b64_e32 v[58:59], v[10:11]
	v_mov_b64_e32 v[56:57], v[8:9]
	v_mov_b64_e32 v[54:55], v[6:7]
	v_mov_b64_e32 v[52:53], v[4:5]
	v_mov_b64_e32 v[50:51], v[2:3]
	v_mov_b64_e32 v[48:49], v[0:1]
	s_mov_b32 s28, 0
	s_barrier

.LBB0_216:
	s_and_b32 s50, s28, 1
	s_cmp_gt_i32 s47, s45
	s_cbranch_scc1 .LBB0_228
	v_mov_b32_e32 v233, v183
	s_lshl_b32 s28, s50, 15
	s_add_i32 s51, s28, 0
	v_ashrrev_i32_e32 v234, 5, v233
	v_lshlrev_b32_e32 v237, 2, v233
	v_bfe_u32 v231, v233, 2, 2
	s_setprio 1
	s_cmp_eq_u32 s50, 0
	s_cbranch_scc1 .Lattn_qk_b0
	ds_read_b128 v[64:67], v209 offset:32768
	ds_read_b128 v[68:71], v210 offset:32768
	ds_read_b128 v[72:75], v211 offset:32768
	ds_read_b128 v[76:79], v212 offset:32768
	ds_read_b128 v[112:115], v209 offset:40960
	ds_read_b128 v[116:119], v210 offset:40960
	ds_read_b128 v[120:123], v211 offset:40960
	ds_read_b128 v[124:127], v212 offset:40960
	s_waitcnt lgkmcnt(7)
	v_mfma_f32_32x32x16_bf16 v[96:111], v[64:67], v[130:133], 0
	s_waitcnt lgkmcnt(6)
	v_mfma_f32_32x32x16_bf16 v[96:111], v[68:71], v[134:137], v[96:111]
	s_waitcnt lgkmcnt(5)
	v_mfma_f32_32x32x16_bf16 v[96:111], v[72:75], v[138:141], v[96:111]
	s_waitcnt lgkmcnt(4)
	v_mfma_f32_32x32x16_bf16 v[96:111], v[76:79], v[142:145], v[96:111]
	s_waitcnt lgkmcnt(3)
	v_mfma_f32_32x32x16_bf16 v[80:95], v[112:115], v[130:133], 0
	s_waitcnt lgkmcnt(2)
	v_mfma_f32_32x32x16_bf16 v[80:95], v[116:119], v[134:137], v[80:95]
	s_waitcnt lgkmcnt(1)
	v_mfma_f32_32x32x16_bf16 v[80:95], v[120:123], v[138:141], v[80:95]
	s_waitcnt lgkmcnt(0)
	v_mfma_f32_32x32x16_bf16 v[80:95], v[124:127], v[142:145], v[80:95]
	s_branch .Lattn_qk_join
.Lattn_qk_b0:
	ds_read_b128 v[64:67], v209 offset:0
	ds_read_b128 v[68:71], v210 offset:0
	ds_read_b128 v[72:75], v211 offset:0
	ds_read_b128 v[76:79], v212 offset:0
	ds_read_b128 v[112:115], v209 offset:8192
	ds_read_b128 v[116:119], v210 offset:8192
	ds_read_b128 v[120:123], v211 offset:8192
	ds_read_b128 v[124:127], v212 offset:8192
	s_waitcnt lgkmcnt(7)
	v_mfma_f32_32x32x16_bf16 v[96:111], v[64:67], v[130:133], 0
	s_waitcnt lgkmcnt(6)
	v_mfma_f32_32x32x16_bf16 v[96:111], v[68:71], v[134:137], v[96:111]
	s_waitcnt lgkmcnt(5)
	v_mfma_f32_32x32x16_bf16 v[96:111], v[72:75], v[138:141], v[96:111]
	s_waitcnt lgkmcnt(4)
	v_mfma_f32_32x32x16_bf16 v[96:111], v[76:79], v[142:145], v[96:111]
	s_waitcnt lgkmcnt(3)
	v_mfma_f32_32x32x16_bf16 v[80:95], v[112:115], v[130:133], 0
	s_waitcnt lgkmcnt(2)
	v_mfma_f32_32x32x16_bf16 v[80:95], v[116:119], v[134:137], v[80:95]
	s_waitcnt lgkmcnt(1)
	v_mfma_f32_32x32x16_bf16 v[80:95], v[120:123], v[138:141], v[80:95]
	s_waitcnt lgkmcnt(0)
	v_mfma_f32_32x32x16_bf16 v[80:95], v[124:127], v[142:145], v[80:95]
.Lattn_qk_join:
	s_setprio 0
	s_lshl_b32 s28, s50, 2
	s_add_i32 s28, s28, 0
	s_add_i32 s28, s28, 0x10410
	v_mov_b32_e32 v64, s28
	ds_read_b32 v64, v64
	s_waitcnt lgkmcnt(0)
	v_readfirstlane_b32 s28, v64
	s_sub_i32 s28, s43, s28
	s_cmpk_gt_i32 s28, 0x7f
	s_cselect_b64 s[30:31], -1, 0
	s_cmpk_lt_i32 s28, 0x80
	s_cselect_b64 s[34:35], -1, 0
	s_add_i32 s28, s47, 63
	s_cmp_gt_i32 s28, s42
	s_cselect_b64 s[28:29], -1, 0
	s_or_b64 s[52:53], s[34:35], s[28:29]
	s_mov_b64 s[34:35], -1
	s_and_b64 vcc, exec, s[52:53]
	s_cbranch_vccnz .LBB0_219
	v_max_f32_e32 v64, v97, v97
	v_max_f32_e32 v65, v96, v96
	v_max_f32_e32 v64, v65, v64
	v_max3_f32 v64, v64, v98, v99
	v_max3_f32 v64, v64, v100, v101
	v_max3_f32 v64, v64, v102, v103
	v_max3_f32 v64, v64, v104, v105
	v_max3_f32 v64, v64, v106, v107
	v_max3_f32 v64, v64, v108, v109
	v_max3_f32 v64, v64, v110, v111
	v_max3_f32 v64, v64, v80, v81
	v_max3_f32 v64, v64, v82, v83
	v_max3_f32 v64, v64, v84, v85
	v_max3_f32 v64, v64, v86, v87
	v_max3_f32 v64, v64, v88, v89
	v_max3_f32 v64, v64, v90, v91
	v_max3_f32 v64, v64, v92, v93
	v_max3_f32 v64, v64, v94, v95
	v_xor_b32_e32 v254, 0x80, v237
	ds_bpermute_b32 v65, v254, v64
	v_mov_b32_e32 v66, s89
	ds_read_b32 v66, v66
	v_mul_f32_e32 v113, 0x3e38aa3b, v95
	s_mov_b64 s[34:35], 0
	s_waitcnt lgkmcnt(1)
	v_max_f32_e32 v65, v65, v65
	v_max_f32_e32 v64, v64, v65
	s_waitcnt lgkmcnt(0)
	v_fmamk_f32 v64, v64, 0x3e38aa3b, v66
	v_max_f32_e32 v65, v235, v235
	v_max_f32_e32 v236, v65, v64
	v_sub_f32_e32 v79, v66, v236
	v_fmamk_f32 v64, v96, 0x3e38aa3b, v79
	v_exp_f32_e32 v246, v64
	v_fmamk_f32 v64, v97, 0x3e38aa3b, v79
	v_exp_f32_e32 v247, v64
	v_fmamk_f32 v64, v98, 0x3e38aa3b, v79
	v_exp_f32_e32 v248, v64
	v_fmamk_f32 v64, v99, 0x3e38aa3b, v79
	v_exp_f32_e32 v249, v64
	v_fmamk_f32 v65, v100, 0x3e38aa3b, v79
	v_add_f32_e32 v64, 0, v246
	v_exp_f32_e32 v250, v65
	v_fmamk_f32 v65, v101, 0x3e38aa3b, v79
	v_add_f32_e32 v64, v247, v64
	v_exp_f32_e32 v251, v65
	v_fmamk_f32 v65, v102, 0x3e38aa3b, v79
	v_add_f32_e32 v64, v248, v64
	v_exp_f32_e32 v252, v65
	v_fmamk_f32 v65, v103, 0x3e38aa3b, v79
	v_add_f32_e32 v64, v249, v64
	v_exp_f32_e32 v253, v65
	v_fmamk_f32 v65, v104, 0x3e38aa3b, v79
	v_add_f32_e32 v64, v250, v64
	v_exp_f32_e32 v238, v65
	v_fmamk_f32 v65, v105, 0x3e38aa3b, v79
	v_add_f32_e32 v64, v251, v64
	v_exp_f32_e32 v239, v65
	v_fmamk_f32 v65, v106, 0x3e38aa3b, v79
	v_add_f32_e32 v64, v252, v64
	v_exp_f32_e32 v240, v65
	v_fmamk_f32 v65, v107, 0x3e38aa3b, v79
	v_add_f32_e32 v64, v253, v64
	v_exp_f32_e32 v241, v65
	v_fmamk_f32 v65, v108, 0x3e38aa3b, v79
	v_add_f32_e32 v64, v238, v64
	v_exp_f32_e32 v242, v65
	v_fmamk_f32 v65, v109, 0x3e38aa3b, v79
	v_add_f32_e32 v64, v239, v64
	v_exp_f32_e32 v243, v65
	v_fmamk_f32 v65, v110, 0x3e38aa3b, v79
	v_add_f32_e32 v64, v240, v64
	v_exp_f32_e32 v244, v65
	v_fmamk_f32 v65, v111, 0x3e38aa3b, v79
	v_add_f32_e32 v64, v241, v64
	v_exp_f32_e32 v245, v65
	v_add_f32_e32 v64, v242, v64
	v_add_f32_e32 v64, v243, v64
	v_add_f32_e32 v64, v244, v64
	v_add_f32_e32 v68, v245, v64
	v_fmamk_f32 v64, v80, 0x3e38aa3b, v79
	v_exp_f32_e32 v64, v64
	v_fmamk_f32 v65, v81, 0x3e38aa3b, v79
	v_exp_f32_e32 v65, v65
	v_fmamk_f32 v66, v82, 0x3e38aa3b, v79
	v_exp_f32_e32 v66, v66
	v_fmamk_f32 v67, v83, 0x3e38aa3b, v79
	v_exp_f32_e32 v67, v67
	v_add_f32_e32 v68, v64, v68
	v_add_f32_e32 v68, v65, v68
	v_add_f32_e32 v68, v66, v68
	v_add_f32_e32 v72, v67, v68
	v_fmamk_f32 v68, v84, 0x3e38aa3b, v79
	v_exp_f32_e32 v68, v68
	v_fmamk_f32 v69, v85, 0x3e38aa3b, v79
	v_exp_f32_e32 v69, v69
	v_fmamk_f32 v70, v86, 0x3e38aa3b, v79
	v_exp_f32_e32 v70, v70
	v_fmamk_f32 v71, v87, 0x3e38aa3b, v79
	v_exp_f32_e32 v71, v71
	v_add_f32_e32 v72, v68, v72
	v_add_f32_e32 v72, v69, v72
	v_add_f32_e32 v72, v70, v72
	v_add_f32_e32 v76, v71, v72
	v_fmamk_f32 v72, v88, 0x3e38aa3b, v79
	v_exp_f32_e32 v72, v72
	v_fmamk_f32 v73, v89, 0x3e38aa3b, v79
	v_exp_f32_e32 v73, v73
	v_fmamk_f32 v74, v90, 0x3e38aa3b, v79
	v_exp_f32_e32 v74, v74
	v_fmamk_f32 v75, v91, 0x3e38aa3b, v79
	v_exp_f32_e32 v75, v75
	v_add_f32_e32 v76, v72, v76
	v_add_f32_e32 v76, v73, v76
	v_add_f32_e32 v76, v74, v76
	v_add_f32_e32 v112, v75, v76
	v_fmamk_f32 v76, v92, 0x3e38aa3b, v79
	v_exp_f32_e32 v76, v76
	v_fmamk_f32 v77, v93, 0x3e38aa3b, v79
	v_exp_f32_e32 v77, v77
	v_fmamk_f32 v78, v94, 0x3e38aa3b, v79
	v_exp_f32_e32 v78, v78
	v_add_f32_e32 v112, v76, v112
	v_add_f32_e32 v112, v77, v112
	v_pk_add_f32 v[112:113], v[78:79], v[112:113]

.LBB0_223:
	v_lshl_add_u32 v80, v234, 2, s47
	v_sub_u32_e32 v80, v178, v80
	v_cmp_le_i32_e32 vcc, 0, v80
	s_nop 1
	v_cndmask_b32_e32 v64, v202, v64, vcc
	v_cmp_le_i32_e32 vcc, 1, v80
	s_nop 1
	v_cndmask_b32_e32 v65, v202, v65, vcc
	v_cmp_le_i32_e32 vcc, 2, v80
	s_nop 1
	v_cndmask_b32_e32 v66, v202, v66, vcc
	v_cmp_le_i32_e32 vcc, 3, v80
	s_nop 1
	v_cndmask_b32_e32 v67, v202, v67, vcc
	v_cmp_le_i32_e32 vcc, 8, v80
	s_nop 1
	v_cndmask_b32_e32 v68, v202, v68, vcc
	v_cmp_le_i32_e32 vcc, 9, v80
	s_nop 1
	v_cndmask_b32_e32 v69, v202, v69, vcc
	v_cmp_le_i32_e32 vcc, 10, v80
	s_nop 1
	v_cndmask_b32_e32 v70, v202, v70, vcc
	v_cmp_le_i32_e32 vcc, 11, v80
	s_nop 1
	v_cndmask_b32_e32 v71, v202, v71, vcc
	v_cmp_le_i32_e32 vcc, 16, v80
	s_nop 1
	v_cndmask_b32_e32 v72, v202, v72, vcc
	v_cmp_le_i32_e32 vcc, 17, v80
	s_nop 1
	v_cndmask_b32_e32 v73, v202, v73, vcc
	v_cmp_le_i32_e32 vcc, 18, v80
	s_nop 1
	v_cndmask_b32_e32 v74, v202, v74, vcc
	v_cmp_le_i32_e32 vcc, 19, v80
	s_nop 1
	v_cndmask_b32_e32 v75, v202, v75, vcc
	v_cmp_le_i32_e32 vcc, 24, v80
	s_nop 1
	v_cndmask_b32_e32 v76, v202, v76, vcc
	v_cmp_le_i32_e32 vcc, 25, v80
	s_nop 1
	v_cndmask_b32_e32 v77, v202, v77, vcc
	v_cmp_le_i32_e32 vcc, 26, v80
	s_nop 1
	v_cndmask_b32_e32 v78, v202, v78, vcc
	v_cmp_le_i32_e32 vcc, 27, v80
	s_nop 1
	v_cndmask_b32_e32 v79, v202, v79, vcc
	v_cmp_le_i32_e32 vcc, 32, v80
	s_nop 1
	v_cndmask_b32_e32 v112, v202, v112, vcc
	v_cmp_le_i32_e32 vcc, 33, v80
	s_nop 1
	v_cndmask_b32_e32 v113, v202, v113, vcc
	v_cmp_le_i32_e32 vcc, 34, v80
	s_nop 1
	v_cndmask_b32_e32 v114, v202, v114, vcc
	v_cmp_le_i32_e32 vcc, 35, v80
	s_nop 1
	v_cndmask_b32_e32 v115, v202, v115, vcc
	v_cmp_le_i32_e32 vcc, 40, v80
	s_nop 1
	v_cndmask_b32_e32 v116, v202, v116, vcc
	v_cmp_le_i32_e32 vcc, 41, v80
	s_nop 1
	v_cndmask_b32_e32 v117, v202, v117, vcc
	v_cmp_le_i32_e32 vcc, 42, v80
	s_nop 1
	v_cndmask_b32_e32 v118, v202, v118, vcc
	v_cmp_le_i32_e32 vcc, 43, v80
	s_nop 1
	v_cndmask_b32_e32 v119, v202, v119, vcc
	v_cmp_le_i32_e32 vcc, 48, v80
	s_nop 1
	v_cndmask_b32_e32 v120, v202, v120, vcc
	v_cmp_le_i32_e32 vcc, 49, v80
	s_nop 1
	v_cndmask_b32_e32 v121, v202, v121, vcc
	v_cmp_le_i32_e32 vcc, 50, v80
	s_nop 1
	v_cndmask_b32_e32 v122, v202, v122, vcc
	v_cmp_le_i32_e32 vcc, 51, v80
	s_nop 1
	v_cndmask_b32_e32 v123, v202, v123, vcc
	v_cmp_le_i32_e32 vcc, 56, v80
	s_nop 1
	v_cndmask_b32_e32 v124, v202, v124, vcc
	v_cmp_le_i32_e32 vcc, 57, v80
	s_nop 1
	v_cndmask_b32_e32 v125, v202, v125, vcc
	v_cmp_le_i32_e32 vcc, 58, v80
	s_nop 1
	v_cndmask_b32_e32 v126, v202, v126, vcc
	v_cmp_le_i32_e32 vcc, 59, v80
	s_nop 1
	v_cndmask_b32_e32 v127, v202, v127, vcc

.LBB0_227:
	s_waitcnt lgkmcnt(0)
	v_add_f32_e32 v81, v81, v82
	v_fmac_f32_e32 v81, v232, v80
	s_setprio 1
	s_cmp_eq_u32 s50, 0
	s_cbranch_scc1 .Lattn_pv_b0
	ds_read_b64_tr_b16 v[92:93], v213 offset:49152
	ds_read_b64_tr_b16 v[94:95], v214 offset:49152
	ds_read_b64_tr_b16 v[96:97], v215 offset:49152
	ds_read_b64_tr_b16 v[98:99], v216 offset:49152
	ds_read_b64_tr_b16 v[100:101], v217 offset:49152
	ds_read_b64_tr_b16 v[102:103], v218 offset:49152
	ds_read_b64_tr_b16 v[104:105], v219 offset:49152
	ds_read_b64_tr_b16 v[106:107], v220 offset:49152
	ds_read_b64_tr_b16 v[108:109], v213 offset:53248
	ds_read_b64_tr_b16 v[110:111], v214 offset:53248
	ds_read_b64_tr_b16 v[112:113], v215 offset:53248
	ds_read_b64_tr_b16 v[114:115], v216 offset:53248
	v_cvt_pk_bf16_f32 v82, v246, v247
	v_cvt_pk_bf16_f32 v83, v248, v249
	v_cvt_pk_bf16_f32 v84, v250, v251
	v_cvt_pk_bf16_f32 v85, v252, v253
	s_nop 1
	s_waitcnt lgkmcnt(10)
	v_mfma_f32_32x32x16_bf16 v[48:63], v[92:95], v[82:85], v[48:63]
	v_cvt_pk_bf16_f32 v86, v238, v239
	v_cvt_pk_bf16_f32 v87, v240, v241
	v_cvt_pk_bf16_f32 v88, v242, v243
	v_cvt_pk_bf16_f32 v89, v244, v245
	ds_read_b64_tr_b16 v[116:117], v217 offset:53248
	ds_read_b64_tr_b16 v[118:119], v218 offset:53248
	s_waitcnt lgkmcnt(10)
	v_mfma_f32_32x32x16_bf16 v[32:47], v[96:99], v[82:85], v[32:47]
	ds_read_b64_tr_b16 v[120:121], v219 offset:53248
	ds_read_b64_tr_b16 v[122:123], v220 offset:53248
	s_waitcnt lgkmcnt(10)
	v_mfma_f32_32x32x16_bf16 v[16:31], v[100:103], v[82:85], v[16:31]
	ds_read_b64_tr_b16 v[92:93], v213 offset:57344
	ds_read_b64_tr_b16 v[94:95], v214 offset:57344
	s_waitcnt lgkmcnt(10)
	v_mfma_f32_32x32x16_bf16 v[0:15], v[104:107], v[82:85], v[0:15]
	ds_read_b64_tr_b16 v[96:97], v215 offset:57344
	ds_read_b64_tr_b16 v[98:99], v216 offset:57344
	s_waitcnt lgkmcnt(10)
	v_mfma_f32_32x32x16_bf16 v[48:63], v[108:111], v[86:89], v[48:63]
	v_cvt_pk_bf16_f32 v82, v64, v65
	v_cvt_pk_bf16_f32 v83, v66, v67
	v_cvt_pk_bf16_f32 v84, v68, v69
	v_cvt_pk_bf16_f32 v85, v70, v71
	ds_read_b64_tr_b16 v[100:101], v217 offset:57344
	ds_read_b64_tr_b16 v[102:103], v218 offset:57344
	s_waitcnt lgkmcnt(10)
	v_mfma_f32_32x32x16_bf16 v[32:47], v[112:115], v[86:89], v[32:47]
	ds_read_b64_tr_b16 v[104:105], v219 offset:57344
	ds_read_b64_tr_b16 v[106:107], v220 offset:57344
	s_waitcnt lgkmcnt(10)
	v_mfma_f32_32x32x16_bf16 v[16:31], v[116:119], v[86:89], v[16:31]
	ds_read_b64_tr_b16 v[108:109], v213 offset:61440
	ds_read_b64_tr_b16 v[110:111], v214 offset:61440
	s_waitcnt lgkmcnt(10)
	v_mfma_f32_32x32x16_bf16 v[0:15], v[120:123], v[86:89], v[0:15]
	ds_read_b64_tr_b16 v[112:113], v215 offset:61440
	ds_read_b64_tr_b16 v[114:115], v216 offset:61440
	s_waitcnt lgkmcnt(10)
	v_mfma_f32_32x32x16_bf16 v[48:63], v[92:95], v[82:85], v[48:63]
	v_cvt_pk_bf16_f32 v86, v72, v73
	v_cvt_pk_bf16_f32 v87, v74, v75
	v_cvt_pk_bf16_f32 v88, v76, v77
	v_cvt_pk_bf16_f32 v89, v78, v79
	ds_read_b64_tr_b16 v[116:117], v217 offset:61440
	ds_read_b64_tr_b16 v[118:119], v218 offset:61440
	s_waitcnt lgkmcnt(10)
	v_mfma_f32_32x32x16_bf16 v[32:47], v[96:99], v[82:85], v[32:47]
	ds_read_b64_tr_b16 v[120:121], v219 offset:61440
	ds_read_b64_tr_b16 v[122:123], v220 offset:61440
	s_waitcnt lgkmcnt(10)
	v_mfma_f32_32x32x16_bf16 v[16:31], v[100:103], v[82:85], v[16:31]
	s_waitcnt lgkmcnt(8)
	v_mfma_f32_32x32x16_bf16 v[0:15], v[104:107], v[82:85], v[0:15]
	s_waitcnt lgkmcnt(6)
	v_mfma_f32_32x32x16_bf16 v[48:63], v[108:111], v[86:89], v[48:63]
	s_waitcnt lgkmcnt(4)
	v_mfma_f32_32x32x16_bf16 v[32:47], v[112:115], v[86:89], v[32:47]
	s_waitcnt lgkmcnt(2)
	v_mfma_f32_32x32x16_bf16 v[16:31], v[116:119], v[86:89], v[16:31]
	s_waitcnt lgkmcnt(0)
	v_mfma_f32_32x32x16_bf16 v[0:15], v[120:123], v[86:89], v[0:15]
	s_branch .Lattn_pv_join
.Lattn_pv_b0:
	ds_read_b64_tr_b16 v[92:93], v213 offset:16384
	ds_read_b64_tr_b16 v[94:95], v214 offset:16384
	ds_read_b64_tr_b16 v[96:97], v215 offset:16384
	ds_read_b64_tr_b16 v[98:99], v216 offset:16384
	ds_read_b64_tr_b16 v[100:101], v217 offset:16384
	ds_read_b64_tr_b16 v[102:103], v218 offset:16384
	ds_read_b64_tr_b16 v[104:105], v219 offset:16384
	ds_read_b64_tr_b16 v[106:107], v220 offset:16384
	ds_read_b64_tr_b16 v[108:109], v213 offset:20480
	ds_read_b64_tr_b16 v[110:111], v214 offset:20480
	ds_read_b64_tr_b16 v[112:113], v215 offset:20480
	ds_read_b64_tr_b16 v[114:115], v216 offset:20480
	v_cvt_pk_bf16_f32 v82, v246, v247
	v_cvt_pk_bf16_f32 v83, v248, v249
	v_cvt_pk_bf16_f32 v84, v250, v251
	v_cvt_pk_bf16_f32 v85, v252, v253
	s_nop 1
	s_waitcnt lgkmcnt(10)
	v_mfma_f32_32x32x16_bf16 v[48:63], v[92:95], v[82:85], v[48:63]
	v_cvt_pk_bf16_f32 v86, v238, v239
	v_cvt_pk_bf16_f32 v87, v240, v241
	v_cvt_pk_bf16_f32 v88, v242, v243
	v_cvt_pk_bf16_f32 v89, v244, v245
	ds_read_b64_tr_b16 v[116:117], v217 offset:20480
	ds_read_b64_tr_b16 v[118:119], v218 offset:20480
	s_waitcnt lgkmcnt(10)
	v_mfma_f32_32x32x16_bf16 v[32:47], v[96:99], v[82:85], v[32:47]
	ds_read_b64_tr_b16 v[120:121], v219 offset:20480
	ds_read_b64_tr_b16 v[122:123], v220 offset:20480
	s_waitcnt lgkmcnt(10)
	v_mfma_f32_32x32x16_bf16 v[16:31], v[100:103], v[82:85], v[16:31]
	ds_read_b64_tr_b16 v[92:93], v213 offset:24576
	ds_read_b64_tr_b16 v[94:95], v214 offset:24576
	s_waitcnt lgkmcnt(10)
	v_mfma_f32_32x32x16_bf16 v[0:15], v[104:107], v[82:85], v[0:15]
	ds_read_b64_tr_b16 v[96:97], v215 offset:24576
	ds_read_b64_tr_b16 v[98:99], v216 offset:24576
	s_waitcnt lgkmcnt(10)
	v_mfma_f32_32x32x16_bf16 v[48:63], v[108:111], v[86:89], v[48:63]
	v_cvt_pk_bf16_f32 v82, v64, v65
	v_cvt_pk_bf16_f32 v83, v66, v67
	v_cvt_pk_bf16_f32 v84, v68, v69
	v_cvt_pk_bf16_f32 v85, v70, v71
	ds_read_b64_tr_b16 v[100:101], v217 offset:24576
	ds_read_b64_tr_b16 v[102:103], v218 offset:24576
	s_waitcnt lgkmcnt(10)
	v_mfma_f32_32x32x16_bf16 v[32:47], v[112:115], v[86:89], v[32:47]
	ds_read_b64_tr_b16 v[104:105], v219 offset:24576
	ds_read_b64_tr_b16 v[106:107], v220 offset:24576
	s_waitcnt lgkmcnt(10)
	v_mfma_f32_32x32x16_bf16 v[16:31], v[116:119], v[86:89], v[16:31]
	ds_read_b64_tr_b16 v[108:109], v213 offset:28672
	ds_read_b64_tr_b16 v[110:111], v214 offset:28672
	s_waitcnt lgkmcnt(10)
	v_mfma_f32_32x32x16_bf16 v[0:15], v[120:123], v[86:89], v[0:15]
	ds_read_b64_tr_b16 v[112:113], v215 offset:28672
	ds_read_b64_tr_b16 v[114:115], v216 offset:28672
	s_waitcnt lgkmcnt(10)
	v_mfma_f32_32x32x16_bf16 v[48:63], v[92:95], v[82:85], v[48:63]
	v_cvt_pk_bf16_f32 v86, v72, v73
	v_cvt_pk_bf16_f32 v87, v74, v75
	v_cvt_pk_bf16_f32 v88, v76, v77
	v_cvt_pk_bf16_f32 v89, v78, v79
	ds_read_b64_tr_b16 v[116:117], v217 offset:28672
	ds_read_b64_tr_b16 v[118:119], v218 offset:28672
	s_waitcnt lgkmcnt(10)
	v_mfma_f32_32x32x16_bf16 v[32:47], v[96:99], v[82:85], v[32:47]
	ds_read_b64_tr_b16 v[120:121], v219 offset:28672
	ds_read_b64_tr_b16 v[122:123], v220 offset:28672
	s_waitcnt lgkmcnt(10)
	v_mfma_f32_32x32x16_bf16 v[16:31], v[100:103], v[82:85], v[16:31]
	s_waitcnt lgkmcnt(8)
	v_mfma_f32_32x32x16_bf16 v[0:15], v[104:107], v[82:85], v[0:15]
	s_waitcnt lgkmcnt(6)
	v_mfma_f32_32x32x16_bf16 v[48:63], v[108:111], v[86:89], v[48:63]
	s_waitcnt lgkmcnt(4)
	v_mfma_f32_32x32x16_bf16 v[32:47], v[112:115], v[86:89], v[32:47]
	s_waitcnt lgkmcnt(2)
	v_mfma_f32_32x32x16_bf16 v[16:31], v[116:119], v[86:89], v[16:31]
	s_waitcnt lgkmcnt(0)
	v_mfma_f32_32x32x16_bf16 v[0:15], v[120:123], v[86:89], v[0:15]
.Lattn_pv_join:
	s_setprio 0
	v_mov_b32_e32 v232, v81
	s_andn2_b64 vcc, exec, s[26:27]
	s_cbranch_vccz .LBB0_229
	s_branch .LBB0_233

.LBB0_471:
	v_bfe_u32 v17, v9, 4, 2
	v_and_b32_e32 v18, 15, v9
	v_lshlrev_b32_e32 v19, 4, v17
	v_lshlrev_b32_e32 v9, 2, v9
	s_waitcnt vmcnt(0)
	v_lshl_or_b32 v150, s8, 6, v18
	v_lshl_or_b32 v18, v18, 6, v19
	s_lshl_b32 s8, s8, 13
	v_and_b32_e32 v9, 32, v9
	v_bitop3_b32 v19, v18, s8, v9 bitop3:0xde
	s_lshl_b32 s8, s9, 5
	s_and_b32 s10, s8, 0x60
	s_add_i32 m0, s29, 0x18000
	v_lshl_add_u64 v[6:7], v[6:7], 0, s[6:7]
	s_lshl_b32 s8, s10, 7
	s_waitcnt vmcnt(4)
	s_barrier
	global_load_lds_dwordx4 v[6:7], off
	v_lshl_add_u64 v[4:5], v[4:5], 0, s[6:7]
	s_add_i32 m0, s29, 0x1a000
	s_add_i32 s35, s29, 0x8000
	s_add_i32 s36, s29, 0xa000
	v_bitop3_b32 v151, v18, s8, v9 bitop3:0xde
	global_load_lds_dwordx4 v[4:5], off
	v_lshl_add_u64 v[2:3], v[2:3], 0, s[6:7]
	s_mov_b32 m0, s35
	s_add_u32 s8, s22, 0x160080
	global_load_lds_dwordx4 v[2:3], off
	v_lshl_add_u64 v[0:1], v[0:1], 0, s[6:7]
	s_mov_b32 m0, s36
	s_addc_u32 s9, s23, 0
	global_load_lds_dwordx4 v[0:1], off
	s_add_i32 m0, s29, 0x1c000
	v_lshl_add_u64 v[0:1], s[8:9], 0, v[128:129]
	global_load_lds_dwordx4 v[0:1], off
	v_lshl_add_u64 v[0:1], s[8:9], 0, v[134:135]
	s_add_i32 m0, s29, 0x1e000
	s_movk_i32 s11, 0x1600
	global_load_lds_dwordx4 v[0:1], off
	v_lshl_or_b32 v152, v17, 2, s10
	v_lshrrev_b32_e32 v1, 1, v8
	v_mul_lo_u32 v0, v11, s11
	s_mov_b32 s10, 0x16000
	v_mad_u64_u32 v[0:1], s[8:9], v1, s10, v[0:1]
	v_or_b32_e32 v0, v0, v10
	v_add_lshl_u32 v0, v0, v12, 1
	v_mov_b32_e32 v1, v129
	s_mov_b64 s[12:13], 0x160080
	v_lshl_add_u64 v[136:137], v[0:1], 0, s[12:13]
	v_lshrrev_b32_e32 v1, 1, v13
	v_mul_lo_u32 v0, v15, s11
	v_mad_u64_u32 v[0:1], s[8:9], v1, s10, v[0:1]
	s_waitcnt vmcnt(6)
	s_ashr_i32 s37, s0, 31
	v_or_b32_e32 v0, v0, v14
	s_waitcnt lgkmcnt(0)
	s_cmp_lg_u64 s[14:15], 0
	v_add_lshl_u32 v0, v0, v16, 1
	v_mov_b32_e32 v1, v129
	s_cselect_b64 s[16:17], -1, 0
	v_lshl_add_u64 v[138:139], v[0:1], 0, s[12:13]
	s_mov_b32 s38, 0
	v_add_u32_e32 v153, 0, v19
	s_barrier
	s_branch .LBB0_473
.LBB0_473:
	s_add_i32 s38, s38, 1
	s_mul_i32 s8, s38, s65
	s_mul_hi_u32 s9, s38, s68
	s_add_i32 s9, s9, s8
	s_mul_i32 s8, s38, s68
	s_add_u32 s12, s8, s0
	s_addc_u32 s13, s9, s37
	v_cmp_gt_i64_e64 s[8:9], s[12:13], v[164:165]
	v_cmp_lt_i64_e64 s[10:11], s[12:13], v[166:167]
	s_and_b64 vcc, exec, s[8:9]
	s_cbranch_vccnz .LBB0_479
	s_ashr_i32 s13, s12, 31
	s_lshr_b32 s13, s13, 29
	s_add_i32 s18, s12, s13
	s_and_b32 s13, s18, -8
	s_sub_i32 s19, s12, s13
	s_cmp_gt_i32 s19, -1
	s_mov_b64 s[12:13], -1
	s_cbranch_scc0 .LBB0_476
	s_lshl_b32 s24, s19, 7
	s_mov_b64 s[12:13], 0

.LBB0_484:
	s_add_u32 s10, s20, 0x100
	s_addc_u32 s11, s21, 0
	s_add_i32 s46, 0, 0x10000
	v_add_u32_e32 v148, s46, v151
	ds_read_b128 v[130:133], v148
	ds_read_b128 v[140:143], v148 offset:1024
	ds_read_b128 v[144:147], v148 offset:2048
	ds_read_b128 v[154:157], v148 offset:3072
	s_cmpk_eq_i32 s45, 0x54
	s_cselect_b32 s25, s19, s11
	s_cselect_b32 s24, s18, s10
	s_cselect_b32 s23, s13, s44
	s_cselect_b32 s22, s12, s43
	v_lshl_add_u64 v[148:149], s[20:21], 0, v[136:137]
	s_add_i32 m0, s29, 0xc000
	ds_read_b128 v[158:161], v153
	ds_read_b128 v[176:179], v153 offset:1024
	ds_read_b128 v[180:183], v153 offset:2048
	ds_read_b128 v[184:187], v153 offset:3072
	ds_read_b128 v[188:191], v153 offset:4096
	ds_read_b128 v[192:195], v153 offset:5120
	ds_read_b128 v[208:211], v153 offset:6144
	ds_read_b128 v[212:215], v153 offset:7168
	global_load_lds_dwordx4 v[148:149], off
	v_lshl_add_u64 v[148:149], s[20:21], 0, v[138:139]
	s_add_i32 m0, s29, 0xe000
	s_nop 0
	global_load_lds_dwordx4 v[148:149], off
	s_waitcnt lgkmcnt(8)
	s_barrier
	s_waitcnt lgkmcnt(0)
	s_setprio 1
	s_waitcnt lgkmcnt(0)
	v_mfma_f32_16x16x32_bf16 v[124:127], v[130:133], v[158:161], v[124:127]
	v_mfma_f32_16x16x32_bf16 v[120:123], v[144:147], v[158:161], v[120:123]
	v_mfma_f32_16x16x32_bf16 v[108:111], v[130:133], v[180:183], v[108:111]
	v_mfma_f32_16x16x32_bf16 v[104:107], v[144:147], v[180:183], v[104:107]
	v_mfma_f32_16x16x32_bf16 v[92:95], v[130:133], v[188:191], v[92:95]
	v_mfma_f32_16x16x32_bf16 v[88:91], v[144:147], v[188:191], v[88:91]
	v_mfma_f32_16x16x32_bf16 v[76:79], v[130:133], v[208:211], v[76:79]
	v_mfma_f32_16x16x32_bf16 v[72:75], v[144:147], v[208:211], v[72:75]
	v_mfma_f32_16x16x32_bf16 v[124:127], v[140:143], v[176:179], v[124:127]
	v_mfma_f32_16x16x32_bf16 v[120:123], v[154:157], v[176:179], v[120:123]
	v_mfma_f32_16x16x32_bf16 v[108:111], v[140:143], v[184:187], v[108:111]
	v_mfma_f32_16x16x32_bf16 v[104:107], v[154:157], v[184:187], v[104:107]
	v_mfma_f32_16x16x32_bf16 v[92:95], v[140:143], v[192:195], v[92:95]
	v_mfma_f32_16x16x32_bf16 v[88:91], v[154:157], v[192:195], v[88:91]
	v_mfma_f32_16x16x32_bf16 v[76:79], v[140:143], v[212:215], v[76:79]
	v_mfma_f32_16x16x32_bf16 v[72:75], v[154:157], v[212:215], v[72:75]
	s_setprio 0
	s_barrier
	s_add_i32 s47, 0, 0x14000
	v_add_u32_e32 v148, s47, v151
	s_add_i32 s20, s46, s28
	ds_read_b128 v[216:219], v148
	ds_read_b128 v[220:223], v148 offset:1024
	ds_read_b128 v[224:227], v148 offset:2048
	ds_read_b128 v[228:231], v148 offset:3072
	v_lshl_add_u64 v[148:149], s[22:23], 0, v[128:129]
	s_mov_b32 m0, s20
	v_lshl_add_u64 v[232:233], s[22:23], 0, v[134:135]
	global_load_lds_dwordx4 v[148:149], off
	s_add_i32 m0, s20, 0x2000
	s_nop 0
	global_load_lds_dwordx4 v[232:233], off
	s_barrier
	s_waitcnt lgkmcnt(0)
	s_setprio 1
	s_waitcnt lgkmcnt(0)
	v_mfma_f32_16x16x32_bf16 v[116:119], v[216:219], v[158:161], v[116:119]
	v_mfma_f32_16x16x32_bf16 v[112:115], v[224:227], v[158:161], v[112:115]
	v_mfma_f32_16x16x32_bf16 v[100:103], v[216:219], v[180:183], v[100:103]
	v_mfma_f32_16x16x32_bf16 v[96:99], v[224:227], v[180:183], v[96:99]
	v_mfma_f32_16x16x32_bf16 v[84:87], v[216:219], v[188:191], v[84:87]
	v_mfma_f32_16x16x32_bf16 v[80:83], v[224:227], v[188:191], v[80:83]
	v_mfma_f32_16x16x32_bf16 v[68:71], v[216:219], v[208:211], v[68:71]
	v_mfma_f32_16x16x32_bf16 v[64:67], v[224:227], v[208:211], v[64:67]
	v_mfma_f32_16x16x32_bf16 v[116:119], v[220:223], v[176:179], v[116:119]
	v_mfma_f32_16x16x32_bf16 v[112:115], v[228:231], v[176:179], v[112:115]
	v_mfma_f32_16x16x32_bf16 v[100:103], v[220:223], v[184:187], v[100:103]
	v_mfma_f32_16x16x32_bf16 v[96:99], v[228:231], v[184:187], v[96:99]
	v_mfma_f32_16x16x32_bf16 v[84:87], v[220:223], v[192:195], v[84:87]
	v_mfma_f32_16x16x32_bf16 v[80:83], v[228:231], v[192:195], v[80:83]
	v_mfma_f32_16x16x32_bf16 v[68:71], v[220:223], v[212:215], v[68:71]
	v_mfma_f32_16x16x32_bf16 v[64:67], v[228:231], v[212:215], v[64:67]
	s_setprio 0
	s_mov_b32 m0, s29
	v_lshl_add_u64 v[234:235], s[24:25], 0, v[128:129]
	s_barrier
	ds_read_b128 v[158:161], v153 offset:16384
	ds_read_b128 v[176:179], v153 offset:17408
	ds_read_b128 v[180:183], v153 offset:18432
	ds_read_b128 v[184:187], v153 offset:19456
	ds_read_b128 v[188:191], v153 offset:20480
	ds_read_b128 v[192:195], v153 offset:21504
	ds_read_b128 v[208:211], v153 offset:22528
	ds_read_b128 v[212:215], v153 offset:23552
	global_load_lds_dwordx4 v[234:235], off
	v_lshl_add_u64 v[236:237], s[24:25], 0, v[134:135]
	s_mov_b32 m0, s30
	s_nop 0
	global_load_lds_dwordx4 v[236:237], off
	s_barrier
	s_waitcnt lgkmcnt(0)
	s_setprio 1
	s_waitcnt lgkmcnt(0)
	v_mfma_f32_16x16x32_bf16 v[60:63], v[130:133], v[158:161], v[60:63]
	v_mfma_f32_16x16x32_bf16 v[56:59], v[144:147], v[158:161], v[56:59]
	v_mfma_f32_16x16x32_bf16 v[44:47], v[130:133], v[180:183], v[44:47]
	v_mfma_f32_16x16x32_bf16 v[40:43], v[144:147], v[180:183], v[40:43]
	v_mfma_f32_16x16x32_bf16 v[28:31], v[130:133], v[188:191], v[28:31]
	v_mfma_f32_16x16x32_bf16 v[24:27], v[144:147], v[188:191], v[24:27]
	v_mfma_f32_16x16x32_bf16 v[12:15], v[130:133], v[208:211], v[12:15]
	v_mfma_f32_16x16x32_bf16 v[8:11], v[144:147], v[208:211], v[8:11]
	v_mfma_f32_16x16x32_bf16 v[60:63], v[140:143], v[176:179], v[60:63]
	v_mfma_f32_16x16x32_bf16 v[56:59], v[154:157], v[176:179], v[56:59]
	v_mfma_f32_16x16x32_bf16 v[44:47], v[140:143], v[184:187], v[44:47]
	v_mfma_f32_16x16x32_bf16 v[40:43], v[154:157], v[184:187], v[40:43]
	v_mfma_f32_16x16x32_bf16 v[28:31], v[140:143], v[192:195], v[28:31]
	v_mfma_f32_16x16x32_bf16 v[24:27], v[154:157], v[192:195], v[24:27]
	v_mfma_f32_16x16x32_bf16 v[12:15], v[140:143], v[212:215], v[12:15]
	v_mfma_f32_16x16x32_bf16 v[8:11], v[154:157], v[212:215], v[8:11]
	s_setprio 0
	s_barrier
	s_add_u32 s20, s22, 0x160000
	s_addc_u32 s21, s23, 0
	s_add_i32 s46, s47, s28
	v_lshl_add_u64 v[130:131], s[20:21], 0, v[128:129]
	s_mov_b32 m0, s46
	s_nop 0
	global_load_lds_dwordx4 v[130:131], off
	v_lshl_add_u64 v[130:131], s[20:21], 0, v[134:135]
	s_add_i32 m0, s46, 0x2000
	s_nop 0
	global_load_lds_dwordx4 v[130:131], off
	s_waitcnt vmcnt(6)
	s_barrier
	s_setprio 1
	v_mfma_f32_16x16x32_bf16 v[52:55], v[216:219], v[158:161], v[52:55]
	v_mfma_f32_16x16x32_bf16 v[48:51], v[224:227], v[158:161], v[48:51]
	v_mfma_f32_16x16x32_bf16 v[36:39], v[216:219], v[180:183], v[36:39]
	v_mfma_f32_16x16x32_bf16 v[32:35], v[224:227], v[180:183], v[32:35]
	v_mfma_f32_16x16x32_bf16 v[20:23], v[216:219], v[188:191], v[20:23]
	v_mfma_f32_16x16x32_bf16 v[16:19], v[224:227], v[188:191], v[16:19]
	v_mfma_f32_16x16x32_bf16 v[4:7], v[216:219], v[208:211], v[4:7]
	v_mfma_f32_16x16x32_bf16 v[0:3], v[224:227], v[208:211], v[0:3]
	v_mfma_f32_16x16x32_bf16 v[52:55], v[220:223], v[176:179], v[52:55]
	v_mfma_f32_16x16x32_bf16 v[48:51], v[228:231], v[176:179], v[48:51]
	v_mfma_f32_16x16x32_bf16 v[36:39], v[220:223], v[184:187], v[36:39]
	v_mfma_f32_16x16x32_bf16 v[32:35], v[228:231], v[184:187], v[32:35]
	v_mfma_f32_16x16x32_bf16 v[20:23], v[220:223], v[192:195], v[20:23]
	v_mfma_f32_16x16x32_bf16 v[16:19], v[228:231], v[192:195], v[16:19]
	v_mfma_f32_16x16x32_bf16 v[4:7], v[220:223], v[212:215], v[4:7]
	v_mfma_f32_16x16x32_bf16 v[0:3], v[228:231], v[212:215], v[0:3]
	s_setprio 0
	s_add_i32 s46, 0, 0x18000
	v_add_u32_e32 v154, s46, v151
	s_barrier
	ds_read_b128 v[130:133], v154
	ds_read_b128 v[140:143], v154 offset:1024
	ds_read_b128 v[144:147], v154 offset:2048
	ds_read_b128 v[154:157], v154 offset:3072
	s_add_u32 s20, s24, 0x160000
	s_addc_u32 s21, s25, 0
	s_mov_b32 m0, s31
	v_lshl_add_u64 v[216:217], s[20:21], 0, v[128:129]
	ds_read_b128 v[158:161], v153 offset:32768
	ds_read_b128 v[176:179], v153 offset:33792
	ds_read_b128 v[180:183], v153 offset:34816
	ds_read_b128 v[184:187], v153 offset:35840
	ds_read_b128 v[188:191], v153 offset:36864
	ds_read_b128 v[192:195], v153 offset:37888
	ds_read_b128 v[208:211], v153 offset:38912
	ds_read_b128 v[212:215], v153 offset:39936
	global_load_lds_dwordx4 v[216:217], off
	v_lshl_add_u64 v[216:217], s[20:21], 0, v[134:135]
	s_mov_b32 m0, s34
	s_nop 0
	global_load_lds_dwordx4 v[216:217], off
	s_waitcnt lgkmcnt(8)
	s_barrier
	s_waitcnt lgkmcnt(0)
	s_setprio 1
	s_waitcnt lgkmcnt(0)
	v_mfma_f32_16x16x32_bf16 v[124:127], v[130:133], v[158:161], v[124:127]
	v_mfma_f32_16x16x32_bf16 v[120:123], v[144:147], v[158:161], v[120:123]
	v_mfma_f32_16x16x32_bf16 v[108:111], v[130:133], v[180:183], v[108:111]
	v_mfma_f32_16x16x32_bf16 v[104:107], v[144:147], v[180:183], v[104:107]
	v_mfma_f32_16x16x32_bf16 v[92:95], v[130:133], v[188:191], v[92:95]
	v_mfma_f32_16x16x32_bf16 v[88:91], v[144:147], v[188:191], v[88:91]
	v_mfma_f32_16x16x32_bf16 v[76:79], v[130:133], v[208:211], v[76:79]
	v_mfma_f32_16x16x32_bf16 v[72:75], v[144:147], v[208:211], v[72:75]
	v_mfma_f32_16x16x32_bf16 v[124:127], v[140:143], v[176:179], v[124:127]
	v_mfma_f32_16x16x32_bf16 v[120:123], v[154:157], v[176:179], v[120:123]
	v_mfma_f32_16x16x32_bf16 v[108:111], v[140:143], v[184:187], v[108:111]
	v_mfma_f32_16x16x32_bf16 v[104:107], v[154:157], v[184:187], v[104:107]
	v_mfma_f32_16x16x32_bf16 v[92:95], v[140:143], v[192:195], v[92:95]
	v_mfma_f32_16x16x32_bf16 v[88:91], v[154:157], v[192:195], v[88:91]
	v_mfma_f32_16x16x32_bf16 v[76:79], v[140:143], v[212:215], v[76:79]
	v_mfma_f32_16x16x32_bf16 v[72:75], v[154:157], v[212:215], v[72:75]
	s_setprio 0
	s_barrier
	s_add_i32 s24, 0, 0x1c000
	s_add_i32 s20, s46, s28
	v_add_u32_e32 v228, s24, v151
	v_lshl_add_u64 v[148:149], v[148:149], 0, s[6:7]
	s_mov_b32 m0, s20
	ds_read_b128 v[216:219], v228
	ds_read_b128 v[220:223], v228 offset:1024
	ds_read_b128 v[224:227], v228 offset:2048
	ds_read_b128 v[228:231], v228 offset:3072
	global_load_lds_dwordx4 v[148:149], off
	v_lshl_add_u64 v[148:149], v[232:233], 0, s[6:7]
	s_add_i32 m0, s20, 0x2000
	s_nop 0
	global_load_lds_dwordx4 v[148:149], off
	s_barrier
	s_waitcnt lgkmcnt(0)
	s_setprio 1
	s_waitcnt lgkmcnt(0)
	v_mfma_f32_16x16x32_bf16 v[116:119], v[216:219], v[158:161], v[116:119]
	v_mfma_f32_16x16x32_bf16 v[112:115], v[224:227], v[158:161], v[112:115]
	v_mfma_f32_16x16x32_bf16 v[100:103], v[216:219], v[180:183], v[100:103]
	v_mfma_f32_16x16x32_bf16 v[96:99], v[224:227], v[180:183], v[96:99]
	v_mfma_f32_16x16x32_bf16 v[84:87], v[216:219], v[188:191], v[84:87]
	v_mfma_f32_16x16x32_bf16 v[80:83], v[224:227], v[188:191], v[80:83]
	v_mfma_f32_16x16x32_bf16 v[68:71], v[216:219], v[208:211], v[68:71]
	v_mfma_f32_16x16x32_bf16 v[64:67], v[224:227], v[208:211], v[64:67]
	v_mfma_f32_16x16x32_bf16 v[116:119], v[220:223], v[176:179], v[116:119]
	v_mfma_f32_16x16x32_bf16 v[112:115], v[228:231], v[176:179], v[112:115]
	v_mfma_f32_16x16x32_bf16 v[100:103], v[220:223], v[184:187], v[100:103]
	v_mfma_f32_16x16x32_bf16 v[96:99], v[228:231], v[184:187], v[96:99]
	v_mfma_f32_16x16x32_bf16 v[84:87], v[220:223], v[192:195], v[84:87]
	v_mfma_f32_16x16x32_bf16 v[80:83], v[228:231], v[192:195], v[80:83]
	v_mfma_f32_16x16x32_bf16 v[68:71], v[220:223], v[212:215], v[68:71]
	v_mfma_f32_16x16x32_bf16 v[64:67], v[228:231], v[212:215], v[64:67]
	s_setprio 0
	s_mov_b32 m0, s35
	v_lshl_add_u64 v[148:149], v[234:235], 0, s[6:7]
	s_barrier
	ds_read_b128 v[158:161], v153 offset:49152
	ds_read_b128 v[176:179], v153 offset:50176
	ds_read_b128 v[180:183], v153 offset:51200
	ds_read_b128 v[184:187], v153 offset:52224
	ds_read_b128 v[188:191], v153 offset:53248
	ds_read_b128 v[192:195], v153 offset:54272
	ds_read_b128 v[208:211], v153 offset:55296
	ds_read_b128 v[212:215], v153 offset:56320
	global_load_lds_dwordx4 v[148:149], off
	v_lshl_add_u64 v[148:149], v[236:237], 0, s[6:7]
	s_mov_b32 m0, s36
	s_nop 0
	global_load_lds_dwordx4 v[148:149], off
	s_barrier
	s_waitcnt lgkmcnt(0)
	s_setprio 1
	s_waitcnt lgkmcnt(0)
	v_mfma_f32_16x16x32_bf16 v[60:63], v[130:133], v[158:161], v[60:63]
	v_mfma_f32_16x16x32_bf16 v[56:59], v[144:147], v[158:161], v[56:59]
	v_mfma_f32_16x16x32_bf16 v[44:47], v[130:133], v[180:183], v[44:47]
	v_mfma_f32_16x16x32_bf16 v[40:43], v[144:147], v[180:183], v[40:43]
	v_mfma_f32_16x16x32_bf16 v[28:31], v[130:133], v[188:191], v[28:31]
	v_mfma_f32_16x16x32_bf16 v[24:27], v[144:147], v[188:191], v[24:27]
	v_mfma_f32_16x16x32_bf16 v[12:15], v[130:133], v[208:211], v[12:15]
	v_mfma_f32_16x16x32_bf16 v[8:11], v[144:147], v[208:211], v[8:11]
	v_mfma_f32_16x16x32_bf16 v[60:63], v[140:143], v[176:179], v[60:63]
	v_mfma_f32_16x16x32_bf16 v[56:59], v[154:157], v[176:179], v[56:59]
	v_mfma_f32_16x16x32_bf16 v[44:47], v[140:143], v[184:187], v[44:47]
	v_mfma_f32_16x16x32_bf16 v[40:43], v[154:157], v[184:187], v[40:43]
	v_mfma_f32_16x16x32_bf16 v[28:31], v[140:143], v[192:195], v[28:31]
	v_mfma_f32_16x16x32_bf16 v[24:27], v[154:157], v[192:195], v[24:27]
	v_mfma_f32_16x16x32_bf16 v[12:15], v[140:143], v[212:215], v[12:15]
	v_mfma_f32_16x16x32_bf16 v[8:11], v[154:157], v[212:215], v[8:11]
	s_setprio 0
	s_barrier
	s_add_u32 s20, s22, 0x160080
	s_addc_u32 s21, s23, 0
	s_add_i32 s22, s24, s28
	v_lshl_add_u64 v[130:131], s[20:21], 0, v[128:129]
	s_mov_b32 m0, s22
	s_nop 0
	global_load_lds_dwordx4 v[130:131], off
	v_lshl_add_u64 v[130:131], s[20:21], 0, v[134:135]
	s_add_i32 m0, s22, 0x2000
	s_nop 0
	global_load_lds_dwordx4 v[130:131], off
	s_waitcnt vmcnt(6)
	s_barrier
	s_setprio 1
	v_mfma_f32_16x16x32_bf16 v[52:55], v[216:219], v[158:161], v[52:55]
	v_mfma_f32_16x16x32_bf16 v[48:51], v[224:227], v[158:161], v[48:51]
	v_mfma_f32_16x16x32_bf16 v[36:39], v[216:219], v[180:183], v[36:39]
	v_mfma_f32_16x16x32_bf16 v[32:35], v[224:227], v[180:183], v[32:35]
	v_mfma_f32_16x16x32_bf16 v[20:23], v[216:219], v[188:191], v[20:23]
	v_mfma_f32_16x16x32_bf16 v[16:19], v[224:227], v[188:191], v[16:19]
	v_mfma_f32_16x16x32_bf16 v[4:7], v[216:219], v[208:211], v[4:7]
	v_mfma_f32_16x16x32_bf16 v[0:3], v[224:227], v[208:211], v[0:3]
	v_mfma_f32_16x16x32_bf16 v[52:55], v[220:223], v[176:179], v[52:55]
	v_mfma_f32_16x16x32_bf16 v[48:51], v[228:231], v[176:179], v[48:51]
	v_mfma_f32_16x16x32_bf16 v[36:39], v[220:223], v[184:187], v[36:39]
	v_mfma_f32_16x16x32_bf16 v[32:35], v[228:231], v[184:187], v[32:35]
	v_mfma_f32_16x16x32_bf16 v[20:23], v[220:223], v[192:195], v[20:23]
	v_mfma_f32_16x16x32_bf16 v[16:19], v[228:231], v[192:195], v[16:19]
	v_mfma_f32_16x16x32_bf16 v[4:7], v[220:223], v[212:215], v[4:7]
	v_mfma_f32_16x16x32_bf16 v[0:3], v[228:231], v[212:215], v[0:3]
	s_setprio 0
	s_add_i32 s45, s45, 2
	s_add_u32 s43, s43, 0x100
	s_addc_u32 s44, s44, 0
	s_cmpk_gt_u32 s45, 0x55
	s_mov_b64 s[20:21], s[10:11]
	s_barrier
	s_cbranch_scc0 .LBB0_484
	v_lshl_add_u32 v130, s42, 8, v150
	v_lshl_or_b32 v131, s41, 8, v152
	v_lshl_add_u32 v131, v130, 11, v131
	v_lshlrev_b32_e32 v132, 1, v131
	v_lshlrev_b32_e32 v133, 2, v131
	s_and_b64 vcc, exec, s[16:17]
	s_cbranch_vccz .Le484_bf16
	s_mov_b64 s[20:21], s[14:15]
	s_mov_b64 s[22:23], s[76:77]
	global_load_dwordx4 v[142:145], v133, s[20:21] offset:0
	global_load_dwordx4 v[154:157], v133, s[20:21] offset:64
	global_load_dwordx4 v[158:161], v133, s[20:21] offset:512
	global_load_dwordx4 v[176:179], v133, s[20:21] offset:576
	s_add_u32 s20, s20, 0x20000
	s_addc_u32 s21, s21, 0
	global_load_dwordx4 v[180:183], v133, s[20:21] offset:0
	global_load_dwordx4 v[184:187], v133, s[20:21] offset:64
	global_load_dwordx4 v[188:191], v133, s[20:21] offset:512
	global_load_dwordx4 v[192:195], v133, s[20:21] offset:576
	s_add_u32 s20, s20, 0x20000
	s_addc_u32 s21, s21, 0
	global_load_dwordx4 v[208:211], v133, s[20:21] offset:0
	global_load_dwordx4 v[212:215], v133, s[20:21] offset:64
	global_load_dwordx4 v[216:219], v133, s[20:21] offset:512
	global_load_dwordx4 v[220:223], v133, s[20:21] offset:576
	s_add_u32 s20, s20, 0x20000
	s_addc_u32 s21, s21, 0
	global_load_dwordx4 v[224:227], v133, s[20:21] offset:0
	global_load_dwordx4 v[228:231], v133, s[20:21] offset:64
	s_waitcnt vmcnt(13)
	v_pk_mul_f32 v[142:143], v[142:143], s[74:75] op_sel_hi:[1,0]
	v_pk_mul_f32 v[144:145], v[144:145], s[74:75] op_sel_hi:[1,0]
	v_pk_fma_f32 v[124:125], v[124:125], 0.5, v[142:143] op_sel_hi:[1,0,1]
	v_pk_fma_f32 v[126:127], v[126:127], 0.5, v[144:145] op_sel_hi:[1,0,1]
	global_store_dwordx4 v133, v[124:127], s[22:23] offset:0
	global_load_dwordx4 v[142:145], v133, s[20:21] offset:512
	s_waitcnt vmcnt(14)
	v_pk_mul_f32 v[154:155], v[154:155], s[74:75] op_sel_hi:[1,0]
	v_pk_mul_f32 v[156:157], v[156:157], s[74:75] op_sel_hi:[1,0]
	v_pk_fma_f32 v[120:121], v[120:121], 0.5, v[154:155] op_sel_hi:[1,0,1]
	v_pk_fma_f32 v[122:123], v[122:123], 0.5, v[156:157] op_sel_hi:[1,0,1]
	global_store_dwordx4 v133, v[120:123], s[22:23] offset:64
	global_load_dwordx4 v[154:157], v133, s[20:21] offset:576
	s_waitcnt vmcnt(15)
	v_pk_mul_f32 v[158:159], v[158:159], s[74:75] op_sel_hi:[1,0]
	v_pk_mul_f32 v[160:161], v[160:161], s[74:75] op_sel_hi:[1,0]
	v_pk_fma_f32 v[116:117], v[116:117], 0.5, v[158:159] op_sel_hi:[1,0,1]
	v_pk_fma_f32 v[118:119], v[118:119], 0.5, v[160:161] op_sel_hi:[1,0,1]
	global_store_dwordx4 v133, v[116:119], s[22:23] offset:512
	s_add_u32 s20, s20, 0xa0000
	s_addc_u32 s21, s21, 0
	global_load_dwordx4 v[158:161], v133, s[20:21] offset:0
	s_waitcnt vmcnt(16)
	v_pk_mul_f32 v[176:177], v[176:177], s[74:75] op_sel_hi:[1,0]
	v_pk_mul_f32 v[178:179], v[178:179], s[74:75] op_sel_hi:[1,0]
	v_pk_fma_f32 v[112:113], v[112:113], 0.5, v[176:177] op_sel_hi:[1,0,1]
	v_pk_fma_f32 v[114:115], v[114:115], 0.5, v[178:179] op_sel_hi:[1,0,1]
	global_store_dwordx4 v133, v[112:115], s[22:23] offset:576
	global_load_dwordx4 v[176:179], v133, s[20:21] offset:64
	s_waitcnt vmcnt(17)
	v_pk_mul_f32 v[180:181], v[180:181], s[74:75] op_sel_hi:[1,0]
	v_pk_mul_f32 v[182:183], v[182:183], s[74:75] op_sel_hi:[1,0]
	v_pk_fma_f32 v[108:109], v[108:109], 0.5, v[180:181] op_sel_hi:[1,0,1]
	v_pk_fma_f32 v[110:111], v[110:111], 0.5, v[182:183] op_sel_hi:[1,0,1]
	s_add_u32 s22, s22, 0x20000
	s_addc_u32 s23, s23, 0
	global_store_dwordx4 v133, v[108:111], s[22:23] offset:0
	global_load_dwordx4 v[180:183], v133, s[20:21] offset:512
	s_waitcnt vmcnt(18)
	v_pk_mul_f32 v[184:185], v[184:185], s[74:75] op_sel_hi:[1,0]
	v_pk_mul_f32 v[186:187], v[186:187], s[74:75] op_sel_hi:[1,0]
	v_pk_fma_f32 v[104:105], v[104:105], 0.5, v[184:185] op_sel_hi:[1,0,1]
	v_pk_fma_f32 v[106:107], v[106:107], 0.5, v[186:187] op_sel_hi:[1,0,1]
	global_store_dwordx4 v133, v[104:107], s[22:23] offset:64
	global_load_dwordx4 v[184:187], v133, s[20:21] offset:576
	s_waitcnt vmcnt(19)
	v_pk_mul_f32 v[188:189], v[188:189], s[74:75] op_sel_hi:[1,0]
	v_pk_mul_f32 v[190:191], v[190:191], s[74:75] op_sel_hi:[1,0]
	v_pk_fma_f32 v[100:101], v[100:101], 0.5, v[188:189] op_sel_hi:[1,0,1]
	v_pk_fma_f32 v[102:103], v[102:103], 0.5, v[190:191] op_sel_hi:[1,0,1]
	global_store_dwordx4 v133, v[100:103], s[22:23] offset:512
	s_add_u32 s20, s20, 0x20000
	s_addc_u32 s21, s21, 0
	global_load_dwordx4 v[188:191], v133, s[20:21] offset:0
	s_waitcnt vmcnt(20)
	v_pk_mul_f32 v[192:193], v[192:193], s[74:75] op_sel_hi:[1,0]
	v_pk_mul_f32 v[194:195], v[194:195], s[74:75] op_sel_hi:[1,0]
	v_pk_fma_f32 v[96:97], v[96:97], 0.5, v[192:193] op_sel_hi:[1,0,1]
	v_pk_fma_f32 v[98:99], v[98:99], 0.5, v[194:195] op_sel_hi:[1,0,1]
	global_store_dwordx4 v133, v[96:99], s[22:23] offset:576
	global_load_dwordx4 v[192:195], v133, s[20:21] offset:64
	s_waitcnt vmcnt(21)
	v_pk_mul_f32 v[208:209], v[208:209], s[74:75] op_sel_hi:[1,0]
	v_pk_mul_f32 v[210:211], v[210:211], s[74:75] op_sel_hi:[1,0]
	v_pk_fma_f32 v[92:93], v[92:93], 0.5, v[208:209] op_sel_hi:[1,0,1]
	v_pk_fma_f32 v[94:95], v[94:95], 0.5, v[210:211] op_sel_hi:[1,0,1]
	s_add_u32 s22, s22, 0x20000
	s_addc_u32 s23, s23, 0
	global_store_dwordx4 v133, v[92:95], s[22:23] offset:0
	global_load_dwordx4 v[208:211], v133, s[20:21] offset:512
	s_waitcnt vmcnt(22)
	v_pk_mul_f32 v[212:213], v[212:213], s[74:75] op_sel_hi:[1,0]
	v_pk_mul_f32 v[214:215], v[214:215], s[74:75] op_sel_hi:[1,0]
	v_pk_fma_f32 v[88:89], v[88:89], 0.5, v[212:213] op_sel_hi:[1,0,1]
	v_pk_fma_f32 v[90:91], v[90:91], 0.5, v[214:215] op_sel_hi:[1,0,1]
	global_store_dwordx4 v133, v[88:91], s[22:23] offset:64
	global_load_dwordx4 v[212:215], v133, s[20:21] offset:576
	s_waitcnt vmcnt(23)
	v_pk_mul_f32 v[216:217], v[216:217], s[74:75] op_sel_hi:[1,0]
	v_pk_mul_f32 v[218:219], v[218:219], s[74:75] op_sel_hi:[1,0]
	v_pk_fma_f32 v[84:85], v[84:85], 0.5, v[216:217] op_sel_hi:[1,0,1]
	v_pk_fma_f32 v[86:87], v[86:87], 0.5, v[218:219] op_sel_hi:[1,0,1]
	global_store_dwordx4 v133, v[84:87], s[22:23] offset:512
	s_add_u32 s20, s20, 0x20000
	s_addc_u32 s21, s21, 0
	global_load_dwordx4 v[216:219], v133, s[20:21] offset:0
	s_waitcnt vmcnt(24)
	v_pk_mul_f32 v[220:221], v[220:221], s[74:75] op_sel_hi:[1,0]
	v_pk_mul_f32 v[222:223], v[222:223], s[74:75] op_sel_hi:[1,0]
	v_pk_fma_f32 v[80:81], v[80:81], 0.5, v[220:221] op_sel_hi:[1,0,1]
	v_pk_fma_f32 v[82:83], v[82:83], 0.5, v[222:223] op_sel_hi:[1,0,1]
	global_store_dwordx4 v133, v[80:83], s[22:23] offset:576
	global_load_dwordx4 v[220:223], v133, s[20:21] offset:64
	s_waitcnt vmcnt(25)
	v_pk_mul_f32 v[224:225], v[224:225], s[74:75] op_sel_hi:[1,0]
	v_pk_mul_f32 v[226:227], v[226:227], s[74:75] op_sel_hi:[1,0]
	v_pk_fma_f32 v[76:77], v[76:77], 0.5, v[224:225] op_sel_hi:[1,0,1]
	v_pk_fma_f32 v[78:79], v[78:79], 0.5, v[226:227] op_sel_hi:[1,0,1]
	s_add_u32 s22, s22, 0x20000
	s_addc_u32 s23, s23, 0
	global_store_dwordx4 v133, v[76:79], s[22:23] offset:0
	global_load_dwordx4 v[224:227], v133, s[20:21] offset:512
	s_waitcnt vmcnt(26)
	v_pk_mul_f32 v[228:229], v[228:229], s[74:75] op_sel_hi:[1,0]
	v_pk_mul_f32 v[230:231], v[230:231], s[74:75] op_sel_hi:[1,0]
	v_pk_fma_f32 v[72:73], v[72:73], 0.5, v[228:229] op_sel_hi:[1,0,1]
	v_pk_fma_f32 v[74:75], v[74:75], 0.5, v[230:231] op_sel_hi:[1,0,1]
	global_store_dwordx4 v133, v[72:75], s[22:23] offset:64
	global_load_dwordx4 v[228:231], v133, s[20:21] offset:576
	s_waitcnt vmcnt(26)
	v_pk_mul_f32 v[142:143], v[142:143], s[74:75] op_sel_hi:[1,0]
	v_pk_mul_f32 v[144:145], v[144:145], s[74:75] op_sel_hi:[1,0]
	v_pk_fma_f32 v[68:69], v[68:69], 0.5, v[142:143] op_sel_hi:[1,0,1]
	v_pk_fma_f32 v[70:71], v[70:71], 0.5, v[144:145] op_sel_hi:[1,0,1]
	global_store_dwordx4 v133, v[68:71], s[22:23] offset:512
	s_add_u32 s20, s20, 0x20000
	s_addc_u32 s21, s21, 0
	global_load_dwordx4 v[142:145], v133, s[20:21] offset:0
	s_waitcnt vmcnt(26)
	v_pk_mul_f32 v[154:155], v[154:155], s[74:75] op_sel_hi:[1,0]
	v_pk_mul_f32 v[156:157], v[156:157], s[74:75] op_sel_hi:[1,0]
	v_pk_fma_f32 v[64:65], v[64:65], 0.5, v[154:155] op_sel_hi:[1,0,1]
	v_pk_fma_f32 v[66:67], v[66:67], 0.5, v[156:157] op_sel_hi:[1,0,1]
	global_store_dwordx4 v133, v[64:67], s[22:23] offset:576
	global_load_dwordx4 v[154:157], v133, s[20:21] offset:64
	s_waitcnt vmcnt(26)
	v_pk_mul_f32 v[158:159], v[158:159], s[74:75] op_sel_hi:[1,0]
	v_pk_mul_f32 v[160:161], v[160:161], s[74:75] op_sel_hi:[1,0]
	v_pk_fma_f32 v[60:61], v[60:61], 0.5, v[158:159] op_sel_hi:[1,0,1]
	v_pk_fma_f32 v[62:63], v[62:63], 0.5, v[160:161] op_sel_hi:[1,0,1]
	s_add_u32 s22, s22, 0xa0000
	s_addc_u32 s23, s23, 0
	global_store_dwordx4 v133, v[60:63], s[22:23] offset:0
	global_load_dwordx4 v[158:161], v133, s[20:21] offset:512
	s_waitcnt vmcnt(26)
	v_pk_mul_f32 v[176:177], v[176:177], s[74:75] op_sel_hi:[1,0]
	v_pk_mul_f32 v[178:179], v[178:179], s[74:75] op_sel_hi:[1,0]
	v_pk_fma_f32 v[56:57], v[56:57], 0.5, v[176:177] op_sel_hi:[1,0,1]
	v_pk_fma_f32 v[58:59], v[58:59], 0.5, v[178:179] op_sel_hi:[1,0,1]
	global_store_dwordx4 v133, v[56:59], s[22:23] offset:64
	global_load_dwordx4 v[176:179], v133, s[20:21] offset:576
	s_waitcnt vmcnt(26)
	v_pk_mul_f32 v[180:181], v[180:181], s[74:75] op_sel_hi:[1,0]
	v_pk_mul_f32 v[182:183], v[182:183], s[74:75] op_sel_hi:[1,0]
	v_pk_fma_f32 v[52:53], v[52:53], 0.5, v[180:181] op_sel_hi:[1,0,1]
	v_pk_fma_f32 v[54:55], v[54:55], 0.5, v[182:183] op_sel_hi:[1,0,1]
	global_store_dwordx4 v133, v[52:55], s[22:23] offset:512
	s_waitcnt vmcnt(25)
	v_pk_mul_f32 v[184:185], v[184:185], s[74:75] op_sel_hi:[1,0]
	v_pk_mul_f32 v[186:187], v[186:187], s[74:75] op_sel_hi:[1,0]
	v_pk_fma_f32 v[48:49], v[48:49], 0.5, v[184:185] op_sel_hi:[1,0,1]
	v_pk_fma_f32 v[50:51], v[50:51], 0.5, v[186:187] op_sel_hi:[1,0,1]
	global_store_dwordx4 v133, v[48:51], s[22:23] offset:576
	s_waitcnt vmcnt(24)
	v_pk_mul_f32 v[188:189], v[188:189], s[74:75] op_sel_hi:[1,0]
	v_pk_mul_f32 v[190:191], v[190:191], s[74:75] op_sel_hi:[1,0]
	v_pk_fma_f32 v[44:45], v[44:45], 0.5, v[188:189] op_sel_hi:[1,0,1]
	v_pk_fma_f32 v[46:47], v[46:47], 0.5, v[190:191] op_sel_hi:[1,0,1]
	s_add_u32 s22, s22, 0x20000
	s_addc_u32 s23, s23, 0
	global_store_dwordx4 v133, v[44:47], s[22:23] offset:0
	s_waitcnt vmcnt(23)
	v_pk_mul_f32 v[192:193], v[192:193], s[74:75] op_sel_hi:[1,0]
	v_pk_mul_f32 v[194:195], v[194:195], s[74:75] op_sel_hi:[1,0]
	v_pk_fma_f32 v[40:41], v[40:41], 0.5, v[192:193] op_sel_hi:[1,0,1]
	v_pk_fma_f32 v[42:43], v[42:43], 0.5, v[194:195] op_sel_hi:[1,0,1]
	global_store_dwordx4 v133, v[40:43], s[22:23] offset:64
	s_waitcnt vmcnt(22)
	v_pk_mul_f32 v[208:209], v[208:209], s[74:75] op_sel_hi:[1,0]
	v_pk_mul_f32 v[210:211], v[210:211], s[74:75] op_sel_hi:[1,0]
	v_pk_fma_f32 v[36:37], v[36:37], 0.5, v[208:209] op_sel_hi:[1,0,1]
	v_pk_fma_f32 v[38:39], v[38:39], 0.5, v[210:211] op_sel_hi:[1,0,1]
	global_store_dwordx4 v133, v[36:39], s[22:23] offset:512
	s_waitcnt vmcnt(21)
	v_pk_mul_f32 v[212:213], v[212:213], s[74:75] op_sel_hi:[1,0]
	v_pk_mul_f32 v[214:215], v[214:215], s[74:75] op_sel_hi:[1,0]
	v_pk_fma_f32 v[32:33], v[32:33], 0.5, v[212:213] op_sel_hi:[1,0,1]
	v_pk_fma_f32 v[34:35], v[34:35], 0.5, v[214:215] op_sel_hi:[1,0,1]
	global_store_dwordx4 v133, v[32:35], s[22:23] offset:576
	s_waitcnt vmcnt(20)
	v_pk_mul_f32 v[216:217], v[216:217], s[74:75] op_sel_hi:[1,0]
	v_pk_mul_f32 v[218:219], v[218:219], s[74:75] op_sel_hi:[1,0]
	v_pk_fma_f32 v[28:29], v[28:29], 0.5, v[216:217] op_sel_hi:[1,0,1]
	v_pk_fma_f32 v[30:31], v[30:31], 0.5, v[218:219] op_sel_hi:[1,0,1]
	s_add_u32 s22, s22, 0x20000
	s_addc_u32 s23, s23, 0
	global_store_dwordx4 v133, v[28:31], s[22:23] offset:0
	s_waitcnt vmcnt(19)
	v_pk_mul_f32 v[220:221], v[220:221], s[74:75] op_sel_hi:[1,0]
	v_pk_mul_f32 v[222:223], v[222:223], s[74:75] op_sel_hi:[1,0]
	v_pk_fma_f32 v[24:25], v[24:25], 0.5, v[220:221] op_sel_hi:[1,0,1]
	v_pk_fma_f32 v[26:27], v[26:27], 0.5, v[222:223] op_sel_hi:[1,0,1]
	global_store_dwordx4 v133, v[24:27], s[22:23] offset:64
	s_waitcnt vmcnt(18)
	v_pk_mul_f32 v[224:225], v[224:225], s[74:75] op_sel_hi:[1,0]
	v_pk_mul_f32 v[226:227], v[226:227], s[74:75] op_sel_hi:[1,0]
	v_pk_fma_f32 v[20:21], v[20:21], 0.5, v[224:225] op_sel_hi:[1,0,1]
	v_pk_fma_f32 v[22:23], v[22:23], 0.5, v[226:227] op_sel_hi:[1,0,1]
	global_store_dwordx4 v133, v[20:23], s[22:23] offset:512
	s_waitcnt vmcnt(17)
	v_pk_mul_f32 v[228:229], v[228:229], s[74:75] op_sel_hi:[1,0]
	v_pk_mul_f32 v[230:231], v[230:231], s[74:75] op_sel_hi:[1,0]
	v_pk_fma_f32 v[16:17], v[16:17], 0.5, v[228:229] op_sel_hi:[1,0,1]
	v_pk_fma_f32 v[18:19], v[18:19], 0.5, v[230:231] op_sel_hi:[1,0,1]
	global_store_dwordx4 v133, v[16:19], s[22:23] offset:576
	s_waitcnt vmcnt(16)
	v_pk_mul_f32 v[142:143], v[142:143], s[74:75] op_sel_hi:[1,0]
	v_pk_mul_f32 v[144:145], v[144:145], s[74:75] op_sel_hi:[1,0]
	v_pk_fma_f32 v[12:13], v[12:13], 0.5, v[142:143] op_sel_hi:[1,0,1]
	v_pk_fma_f32 v[14:15], v[14:15], 0.5, v[144:145] op_sel_hi:[1,0,1]
	s_add_u32 s22, s22, 0x20000
	s_addc_u32 s23, s23, 0
	global_store_dwordx4 v133, v[12:15], s[22:23] offset:0
	s_waitcnt vmcnt(15)
	v_pk_mul_f32 v[154:155], v[154:155], s[74:75] op_sel_hi:[1,0]
	v_pk_mul_f32 v[156:157], v[156:157], s[74:75] op_sel_hi:[1,0]
	v_pk_fma_f32 v[8:9], v[8:9], 0.5, v[154:155] op_sel_hi:[1,0,1]
	v_pk_fma_f32 v[10:11], v[10:11], 0.5, v[156:157] op_sel_hi:[1,0,1]
	global_store_dwordx4 v133, v[8:11], s[22:23] offset:64
	s_waitcnt vmcnt(14)
	v_pk_mul_f32 v[158:159], v[158:159], s[74:75] op_sel_hi:[1,0]
	v_pk_mul_f32 v[160:161], v[160:161], s[74:75] op_sel_hi:[1,0]
	v_pk_fma_f32 v[4:5], v[4:5], 0.5, v[158:159] op_sel_hi:[1,0,1]
	v_pk_fma_f32 v[6:7], v[6:7], 0.5, v[160:161] op_sel_hi:[1,0,1]
	global_store_dwordx4 v133, v[4:7], s[22:23] offset:512
	s_waitcnt vmcnt(13)
	v_pk_mul_f32 v[176:177], v[176:177], s[74:75] op_sel_hi:[1,0]
	v_pk_mul_f32 v[178:179], v[178:179], s[74:75] op_sel_hi:[1,0]
	v_pk_fma_f32 v[0:1], v[0:1], 0.5, v[176:177] op_sel_hi:[1,0,1]
	v_pk_fma_f32 v[2:3], v[2:3], 0.5, v[178:179] op_sel_hi:[1,0,1]
	global_store_dwordx4 v133, v[0:3], s[22:23] offset:576
	s_branch .Le484_join
.Le484_bf16:
	v_readlane_b32 s20, v255, 34
	v_readlane_b32 s21, v255, 35
	s_nop 4
	s_mov_b64 s[22:23], s[76:77]
	global_load_dwordx2 v[142:143], v132, s[20:21] offset:0
	global_load_dwordx2 v[144:145], v132, s[20:21] offset:32
	global_load_dwordx2 v[146:147], v132, s[20:21] offset:256
	global_load_dwordx2 v[154:155], v132, s[20:21] offset:288
	s_add_u32 s20, s20, 0x10000
	s_addc_u32 s21, s21, 0
	global_load_dwordx2 v[156:157], v132, s[20:21] offset:0
	global_load_dwordx2 v[158:159], v132, s[20:21] offset:32
	global_load_dwordx2 v[160:161], v132, s[20:21] offset:256
	global_load_dwordx2 v[176:177], v132, s[20:21] offset:288
	s_add_u32 s20, s20, 0x10000
	s_addc_u32 s21, s21, 0
	global_load_dwordx2 v[178:179], v132, s[20:21] offset:0
	global_load_dwordx2 v[180:181], v132, s[20:21] offset:32
	global_load_dwordx2 v[182:183], v132, s[20:21] offset:256
	global_load_dwordx2 v[184:185], v132, s[20:21] offset:288
	s_add_u32 s20, s20, 0x10000
	s_addc_u32 s21, s21, 0
	global_load_dwordx2 v[186:187], v132, s[20:21] offset:0
	global_load_dwordx2 v[188:189], v132, s[20:21] offset:32
	global_load_dwordx2 v[190:191], v132, s[20:21] offset:256
	global_load_dwordx2 v[192:193], v132, s[20:21] offset:288
	s_add_u32 s20, s20, 0x50000
	s_addc_u32 s21, s21, 0
	global_load_dwordx2 v[194:195], v132, s[20:21] offset:0
	global_load_dwordx2 v[208:209], v132, s[20:21] offset:32
	global_load_dwordx2 v[210:211], v132, s[20:21] offset:256
	global_load_dwordx2 v[212:213], v132, s[20:21] offset:288
	s_add_u32 s20, s20, 0x10000
	s_addc_u32 s21, s21, 0
	global_load_dwordx2 v[214:215], v132, s[20:21] offset:0
	global_load_dwordx2 v[216:217], v132, s[20:21] offset:32
	global_load_dwordx2 v[218:219], v132, s[20:21] offset:256
	global_load_dwordx2 v[220:221], v132, s[20:21] offset:288
	s_add_u32 s20, s20, 0x10000
	s_addc_u32 s21, s21, 0
	global_load_dwordx2 v[222:223], v132, s[20:21] offset:0
	global_load_dwordx2 v[224:225], v132, s[20:21] offset:32
	global_load_dwordx2 v[226:227], v132, s[20:21] offset:256
	global_load_dwordx2 v[228:229], v132, s[20:21] offset:288
	s_add_u32 s20, s20, 0x10000
	s_addc_u32 s21, s21, 0
	global_load_dwordx2 v[230:231], v132, s[20:21] offset:0
	s_waitcnt vmcnt(28)
	v_lshlrev_b32_e32 v140, 16, v142
	v_and_b32_e32 v141, 0xffff0000, v142
	v_lshlrev_b32_e32 v142, 16, v143
	v_and_b32_e32 v143, 0xffff0000, v143
	v_pk_mul_f32 v[140:141], v[140:141], s[74:75] op_sel_hi:[1,0]
	v_pk_mul_f32 v[142:143], v[142:143], s[74:75] op_sel_hi:[1,0]
	v_pk_fma_f32 v[124:125], v[124:125], 0.5, v[140:141] op_sel_hi:[1,0,1]
	v_pk_fma_f32 v[126:127], v[126:127], 0.5, v[142:143] op_sel_hi:[1,0,1]
	global_store_dwordx4 v133, v[124:127], s[22:23] offset:0
	global_load_dwordx2 v[142:143], v132, s[20:21] offset:32
	s_waitcnt vmcnt(29)
	v_lshlrev_b32_e32 v140, 16, v144
	v_and_b32_e32 v141, 0xffff0000, v144
	v_lshlrev_b32_e32 v144, 16, v145
	v_and_b32_e32 v145, 0xffff0000, v145
	v_pk_mul_f32 v[140:141], v[140:141], s[74:75] op_sel_hi:[1,0]
	v_pk_mul_f32 v[144:145], v[144:145], s[74:75] op_sel_hi:[1,0]
	v_pk_fma_f32 v[120:121], v[120:121], 0.5, v[140:141] op_sel_hi:[1,0,1]
	v_pk_fma_f32 v[122:123], v[122:123], 0.5, v[144:145] op_sel_hi:[1,0,1]
	global_store_dwordx4 v133, v[120:123], s[22:23] offset:64
	global_load_dwordx2 v[144:145], v132, s[20:21] offset:256
	s_waitcnt vmcnt(30)
	v_lshlrev_b32_e32 v140, 16, v146
	v_and_b32_e32 v141, 0xffff0000, v146
	v_lshlrev_b32_e32 v146, 16, v147
	v_and_b32_e32 v147, 0xffff0000, v147
	v_pk_mul_f32 v[140:141], v[140:141], s[74:75] op_sel_hi:[1,0]
	v_pk_mul_f32 v[146:147], v[146:147], s[74:75] op_sel_hi:[1,0]
	v_pk_fma_f32 v[116:117], v[116:117], 0.5, v[140:141] op_sel_hi:[1,0,1]
	v_pk_fma_f32 v[118:119], v[118:119], 0.5, v[146:147] op_sel_hi:[1,0,1]
	global_store_dwordx4 v133, v[116:119], s[22:23] offset:512
	global_load_dwordx2 v[146:147], v132, s[20:21] offset:288
	s_waitcnt vmcnt(31)
	v_lshlrev_b32_e32 v140, 16, v154
	v_and_b32_e32 v141, 0xffff0000, v154
	v_lshlrev_b32_e32 v154, 16, v155
	v_and_b32_e32 v155, 0xffff0000, v155
	v_pk_mul_f32 v[140:141], v[140:141], s[74:75] op_sel_hi:[1,0]
	v_pk_mul_f32 v[154:155], v[154:155], s[74:75] op_sel_hi:[1,0]
	v_pk_fma_f32 v[112:113], v[112:113], 0.5, v[140:141] op_sel_hi:[1,0,1]
	v_pk_fma_f32 v[114:115], v[114:115], 0.5, v[154:155] op_sel_hi:[1,0,1]
	global_store_dwordx4 v133, v[112:115], s[22:23] offset:576
	s_waitcnt vmcnt(31)
	v_lshlrev_b32_e32 v140, 16, v156
	v_and_b32_e32 v141, 0xffff0000, v156
	v_lshlrev_b32_e32 v156, 16, v157
	v_and_b32_e32 v157, 0xffff0000, v157
	v_pk_mul_f32 v[140:141], v[140:141], s[74:75] op_sel_hi:[1,0]
	v_pk_mul_f32 v[156:157], v[156:157], s[74:75] op_sel_hi:[1,0]
	v_pk_fma_f32 v[108:109], v[108:109], 0.5, v[140:141] op_sel_hi:[1,0,1]
	v_pk_fma_f32 v[110:111], v[110:111], 0.5, v[156:157] op_sel_hi:[1,0,1]
	s_add_u32 s22, s22, 0x20000
	s_addc_u32 s23, s23, 0
	global_store_dwordx4 v133, v[108:111], s[22:23] offset:0
	s_waitcnt vmcnt(31)
	v_lshlrev_b32_e32 v140, 16, v158
	v_and_b32_e32 v141, 0xffff0000, v158
	v_lshlrev_b32_e32 v158, 16, v159
	v_and_b32_e32 v159, 0xffff0000, v159
	v_pk_mul_f32 v[140:141], v[140:141], s[74:75] op_sel_hi:[1,0]
	v_pk_mul_f32 v[158:159], v[158:159], s[74:75] op_sel_hi:[1,0]
	v_pk_fma_f32 v[104:105], v[104:105], 0.5, v[140:141] op_sel_hi:[1,0,1]
	v_pk_fma_f32 v[106:107], v[106:107], 0.5, v[158:159] op_sel_hi:[1,0,1]
	global_store_dwordx4 v133, v[104:107], s[22:23] offset:64
	s_waitcnt vmcnt(31)
	v_lshlrev_b32_e32 v140, 16, v160
	v_and_b32_e32 v141, 0xffff0000, v160
	v_lshlrev_b32_e32 v160, 16, v161
	v_and_b32_e32 v161, 0xffff0000, v161
	v_pk_mul_f32 v[140:141], v[140:141], s[74:75] op_sel_hi:[1,0]
	v_pk_mul_f32 v[160:161], v[160:161], s[74:75] op_sel_hi:[1,0]
	v_pk_fma_f32 v[100:101], v[100:101], 0.5, v[140:141] op_sel_hi:[1,0,1]
	v_pk_fma_f32 v[102:103], v[102:103], 0.5, v[160:161] op_sel_hi:[1,0,1]
	global_store_dwordx4 v133, v[100:103], s[22:23] offset:512
	s_waitcnt vmcnt(31)
	v_lshlrev_b32_e32 v140, 16, v176
	v_and_b32_e32 v141, 0xffff0000, v176
	v_lshlrev_b32_e32 v176, 16, v177
	v_and_b32_e32 v177, 0xffff0000, v177
	v_pk_mul_f32 v[140:141], v[140:141], s[74:75] op_sel_hi:[1,0]
	v_pk_mul_f32 v[176:177], v[176:177], s[74:75] op_sel_hi:[1,0]
	v_pk_fma_f32 v[96:97], v[96:97], 0.5, v[140:141] op_sel_hi:[1,0,1]
	v_pk_fma_f32 v[98:99], v[98:99], 0.5, v[176:177] op_sel_hi:[1,0,1]
	global_store_dwordx4 v133, v[96:99], s[22:23] offset:576
	s_waitcnt vmcnt(31)
	v_lshlrev_b32_e32 v140, 16, v178
	v_and_b32_e32 v141, 0xffff0000, v178
	v_lshlrev_b32_e32 v178, 16, v179
	v_and_b32_e32 v179, 0xffff0000, v179
	v_pk_mul_f32 v[140:141], v[140:141], s[74:75] op_sel_hi:[1,0]
	v_pk_mul_f32 v[178:179], v[178:179], s[74:75] op_sel_hi:[1,0]
	v_pk_fma_f32 v[92:93], v[92:93], 0.5, v[140:141] op_sel_hi:[1,0,1]
	v_pk_fma_f32 v[94:95], v[94:95], 0.5, v[178:179] op_sel_hi:[1,0,1]
	s_add_u32 s22, s22, 0x20000
	s_addc_u32 s23, s23, 0
	global_store_dwordx4 v133, v[92:95], s[22:23] offset:0
	s_waitcnt vmcnt(31)
	v_lshlrev_b32_e32 v140, 16, v180
	v_and_b32_e32 v141, 0xffff0000, v180
	v_lshlrev_b32_e32 v180, 16, v181
	v_and_b32_e32 v181, 0xffff0000, v181
	v_pk_mul_f32 v[140:141], v[140:141], s[74:75] op_sel_hi:[1,0]
	v_pk_mul_f32 v[180:181], v[180:181], s[74:75] op_sel_hi:[1,0]
	v_pk_fma_f32 v[88:89], v[88:89], 0.5, v[140:141] op_sel_hi:[1,0,1]
	v_pk_fma_f32 v[90:91], v[90:91], 0.5, v[180:181] op_sel_hi:[1,0,1]
	global_store_dwordx4 v133, v[88:91], s[22:23] offset:64
	s_waitcnt vmcnt(31)
	v_lshlrev_b32_e32 v140, 16, v182
	v_and_b32_e32 v141, 0xffff0000, v182
	v_lshlrev_b32_e32 v182, 16, v183
	v_and_b32_e32 v183, 0xffff0000, v183
	v_pk_mul_f32 v[140:141], v[140:141], s[74:75] op_sel_hi:[1,0]
	v_pk_mul_f32 v[182:183], v[182:183], s[74:75] op_sel_hi:[1,0]
	v_pk_fma_f32 v[84:85], v[84:85], 0.5, v[140:141] op_sel_hi:[1,0,1]
	v_pk_fma_f32 v[86:87], v[86:87], 0.5, v[182:183] op_sel_hi:[1,0,1]
	global_store_dwordx4 v133, v[84:87], s[22:23] offset:512
	s_waitcnt vmcnt(31)
	v_lshlrev_b32_e32 v140, 16, v184
	v_and_b32_e32 v141, 0xffff0000, v184
	v_lshlrev_b32_e32 v184, 16, v185
	v_and_b32_e32 v185, 0xffff0000, v185
	v_pk_mul_f32 v[140:141], v[140:141], s[74:75] op_sel_hi:[1,0]
	v_pk_mul_f32 v[184:185], v[184:185], s[74:75] op_sel_hi:[1,0]
	v_pk_fma_f32 v[80:81], v[80:81], 0.5, v[140:141] op_sel_hi:[1,0,1]
	v_pk_fma_f32 v[82:83], v[82:83], 0.5, v[184:185] op_sel_hi:[1,0,1]
	global_store_dwordx4 v133, v[80:83], s[22:23] offset:576
	s_waitcnt vmcnt(31)
	v_lshlrev_b32_e32 v140, 16, v186
	v_and_b32_e32 v141, 0xffff0000, v186
	v_lshlrev_b32_e32 v186, 16, v187
	v_and_b32_e32 v187, 0xffff0000, v187
	v_pk_mul_f32 v[140:141], v[140:141], s[74:75] op_sel_hi:[1,0]
	v_pk_mul_f32 v[186:187], v[186:187], s[74:75] op_sel_hi:[1,0]
	v_pk_fma_f32 v[76:77], v[76:77], 0.5, v[140:141] op_sel_hi:[1,0,1]
	v_pk_fma_f32 v[78:79], v[78:79], 0.5, v[186:187] op_sel_hi:[1,0,1]
	s_add_u32 s22, s22, 0x20000
	s_addc_u32 s23, s23, 0
	global_store_dwordx4 v133, v[76:79], s[22:23] offset:0
	s_waitcnt vmcnt(31)
	v_lshlrev_b32_e32 v140, 16, v188
	v_and_b32_e32 v141, 0xffff0000, v188
	v_lshlrev_b32_e32 v188, 16, v189
	v_and_b32_e32 v189, 0xffff0000, v189
	v_pk_mul_f32 v[140:141], v[140:141], s[74:75] op_sel_hi:[1,0]
	v_pk_mul_f32 v[188:189], v[188:189], s[74:75] op_sel_hi:[1,0]
	v_pk_fma_f32 v[72:73], v[72:73], 0.5, v[140:141] op_sel_hi:[1,0,1]
	v_pk_fma_f32 v[74:75], v[74:75], 0.5, v[188:189] op_sel_hi:[1,0,1]
	global_store_dwordx4 v133, v[72:75], s[22:23] offset:64
	s_waitcnt vmcnt(31)
	v_lshlrev_b32_e32 v140, 16, v190
	v_and_b32_e32 v141, 0xffff0000, v190
	v_lshlrev_b32_e32 v190, 16, v191
	v_and_b32_e32 v191, 0xffff0000, v191
	v_pk_mul_f32 v[140:141], v[140:141], s[74:75] op_sel_hi:[1,0]
	v_pk_mul_f32 v[190:191], v[190:191], s[74:75] op_sel_hi:[1,0]
	v_pk_fma_f32 v[68:69], v[68:69], 0.5, v[140:141] op_sel_hi:[1,0,1]
	v_pk_fma_f32 v[70:71], v[70:71], 0.5, v[190:191] op_sel_hi:[1,0,1]
	global_store_dwordx4 v133, v[68:71], s[22:23] offset:512
	s_waitcnt vmcnt(31)
	v_lshlrev_b32_e32 v140, 16, v192
	v_and_b32_e32 v141, 0xffff0000, v192
	v_lshlrev_b32_e32 v192, 16, v193
	v_and_b32_e32 v193, 0xffff0000, v193
	v_pk_mul_f32 v[140:141], v[140:141], s[74:75] op_sel_hi:[1,0]
	v_pk_mul_f32 v[192:193], v[192:193], s[74:75] op_sel_hi:[1,0]
	v_pk_fma_f32 v[64:65], v[64:65], 0.5, v[140:141] op_sel_hi:[1,0,1]
	v_pk_fma_f32 v[66:67], v[66:67], 0.5, v[192:193] op_sel_hi:[1,0,1]
	global_store_dwordx4 v133, v[64:67], s[22:23] offset:576
	s_waitcnt vmcnt(31)
	v_lshlrev_b32_e32 v140, 16, v194
	v_and_b32_e32 v141, 0xffff0000, v194
	v_lshlrev_b32_e32 v194, 16, v195
	v_and_b32_e32 v195, 0xffff0000, v195
	v_pk_mul_f32 v[140:141], v[140:141], s[74:75] op_sel_hi:[1,0]
	v_pk_mul_f32 v[194:195], v[194:195], s[74:75] op_sel_hi:[1,0]
	v_pk_fma_f32 v[60:61], v[60:61], 0.5, v[140:141] op_sel_hi:[1,0,1]
	v_pk_fma_f32 v[62:63], v[62:63], 0.5, v[194:195] op_sel_hi:[1,0,1]
	s_add_u32 s22, s22, 0xa0000
	s_addc_u32 s23, s23, 0
	global_store_dwordx4 v133, v[60:63], s[22:23] offset:0
	s_waitcnt vmcnt(31)
	v_lshlrev_b32_e32 v140, 16, v208
	v_and_b32_e32 v141, 0xffff0000, v208
	v_lshlrev_b32_e32 v208, 16, v209
	v_and_b32_e32 v209, 0xffff0000, v209
	v_pk_mul_f32 v[140:141], v[140:141], s[74:75] op_sel_hi:[1,0]
	v_pk_mul_f32 v[208:209], v[208:209], s[74:75] op_sel_hi:[1,0]
	v_pk_fma_f32 v[56:57], v[56:57], 0.5, v[140:141] op_sel_hi:[1,0,1]
	v_pk_fma_f32 v[58:59], v[58:59], 0.5, v[208:209] op_sel_hi:[1,0,1]
	global_store_dwordx4 v133, v[56:59], s[22:23] offset:64
	s_waitcnt vmcnt(31)
	v_lshlrev_b32_e32 v140, 16, v210
	v_and_b32_e32 v141, 0xffff0000, v210
	v_lshlrev_b32_e32 v210, 16, v211
	v_and_b32_e32 v211, 0xffff0000, v211
	v_pk_mul_f32 v[140:141], v[140:141], s[74:75] op_sel_hi:[1,0]
	v_pk_mul_f32 v[210:211], v[210:211], s[74:75] op_sel_hi:[1,0]
	v_pk_fma_f32 v[52:53], v[52:53], 0.5, v[140:141] op_sel_hi:[1,0,1]
	v_pk_fma_f32 v[54:55], v[54:55], 0.5, v[210:211] op_sel_hi:[1,0,1]
	global_store_dwordx4 v133, v[52:55], s[22:23] offset:512
	s_waitcnt vmcnt(31)
	v_lshlrev_b32_e32 v140, 16, v212
	v_and_b32_e32 v141, 0xffff0000, v212
	v_lshlrev_b32_e32 v212, 16, v213
	v_and_b32_e32 v213, 0xffff0000, v213
	v_pk_mul_f32 v[140:141], v[140:141], s[74:75] op_sel_hi:[1,0]
	v_pk_mul_f32 v[212:213], v[212:213], s[74:75] op_sel_hi:[1,0]
	v_pk_fma_f32 v[48:49], v[48:49], 0.5, v[140:141] op_sel_hi:[1,0,1]
	v_pk_fma_f32 v[50:51], v[50:51], 0.5, v[212:213] op_sel_hi:[1,0,1]
	global_store_dwordx4 v133, v[48:51], s[22:23] offset:576
	s_waitcnt vmcnt(31)
	v_lshlrev_b32_e32 v140, 16, v214
	v_and_b32_e32 v141, 0xffff0000, v214
	v_lshlrev_b32_e32 v214, 16, v215
	v_and_b32_e32 v215, 0xffff0000, v215
	v_pk_mul_f32 v[140:141], v[140:141], s[74:75] op_sel_hi:[1,0]
	v_pk_mul_f32 v[214:215], v[214:215], s[74:75] op_sel_hi:[1,0]
	v_pk_fma_f32 v[44:45], v[44:45], 0.5, v[140:141] op_sel_hi:[1,0,1]
	v_pk_fma_f32 v[46:47], v[46:47], 0.5, v[214:215] op_sel_hi:[1,0,1]
	s_add_u32 s22, s22, 0x20000
	s_addc_u32 s23, s23, 0
	global_store_dwordx4 v133, v[44:47], s[22:23] offset:0
	s_waitcnt vmcnt(31)
	v_lshlrev_b32_e32 v140, 16, v216
	v_and_b32_e32 v141, 0xffff0000, v216
	v_lshlrev_b32_e32 v216, 16, v217
	v_and_b32_e32 v217, 0xffff0000, v217
	v_pk_mul_f32 v[140:141], v[140:141], s[74:75] op_sel_hi:[1,0]
	v_pk_mul_f32 v[216:217], v[216:217], s[74:75] op_sel_hi:[1,0]
	v_pk_fma_f32 v[40:41], v[40:41], 0.5, v[140:141] op_sel_hi:[1,0,1]
	v_pk_fma_f32 v[42:43], v[42:43], 0.5, v[216:217] op_sel_hi:[1,0,1]
	global_store_dwordx4 v133, v[40:43], s[22:23] offset:64
	s_waitcnt vmcnt(31)
	v_lshlrev_b32_e32 v140, 16, v218
	v_and_b32_e32 v141, 0xffff0000, v218
	v_lshlrev_b32_e32 v218, 16, v219
	v_and_b32_e32 v219, 0xffff0000, v219
	v_pk_mul_f32 v[140:141], v[140:141], s[74:75] op_sel_hi:[1,0]
	v_pk_mul_f32 v[218:219], v[218:219], s[74:75] op_sel_hi:[1,0]
	v_pk_fma_f32 v[36:37], v[36:37], 0.5, v[140:141] op_sel_hi:[1,0,1]
	v_pk_fma_f32 v[38:39], v[38:39], 0.5, v[218:219] op_sel_hi:[1,0,1]
	global_store_dwordx4 v133, v[36:39], s[22:23] offset:512
	s_waitcnt vmcnt(31)
	v_lshlrev_b32_e32 v140, 16, v220
	v_and_b32_e32 v141, 0xffff0000, v220
	v_lshlrev_b32_e32 v220, 16, v221
	v_and_b32_e32 v221, 0xffff0000, v221
	v_pk_mul_f32 v[140:141], v[140:141], s[74:75] op_sel_hi:[1,0]
	v_pk_mul_f32 v[220:221], v[220:221], s[74:75] op_sel_hi:[1,0]
	v_pk_fma_f32 v[32:33], v[32:33], 0.5, v[140:141] op_sel_hi:[1,0,1]
	v_pk_fma_f32 v[34:35], v[34:35], 0.5, v[220:221] op_sel_hi:[1,0,1]
	global_store_dwordx4 v133, v[32:35], s[22:23] offset:576
	s_waitcnt vmcnt(31)
	v_lshlrev_b32_e32 v140, 16, v222
	v_and_b32_e32 v141, 0xffff0000, v222
	v_lshlrev_b32_e32 v222, 16, v223
	v_and_b32_e32 v223, 0xffff0000, v223
	v_pk_mul_f32 v[140:141], v[140:141], s[74:75] op_sel_hi:[1,0]
	v_pk_mul_f32 v[222:223], v[222:223], s[74:75] op_sel_hi:[1,0]
	v_pk_fma_f32 v[28:29], v[28:29], 0.5, v[140:141] op_sel_hi:[1,0,1]
	v_pk_fma_f32 v[30:31], v[30:31], 0.5, v[222:223] op_sel_hi:[1,0,1]
	s_add_u32 s22, s22, 0x20000
	s_addc_u32 s23, s23, 0
	global_store_dwordx4 v133, v[28:31], s[22:23] offset:0
	s_waitcnt vmcnt(31)
	v_lshlrev_b32_e32 v140, 16, v224
	v_and_b32_e32 v141, 0xffff0000, v224
	v_lshlrev_b32_e32 v224, 16, v225
	v_and_b32_e32 v225, 0xffff0000, v225
	v_pk_mul_f32 v[140:141], v[140:141], s[74:75] op_sel_hi:[1,0]
	v_pk_mul_f32 v[224:225], v[224:225], s[74:75] op_sel_hi:[1,0]
	v_pk_fma_f32 v[24:25], v[24:25], 0.5, v[140:141] op_sel_hi:[1,0,1]
	v_pk_fma_f32 v[26:27], v[26:27], 0.5, v[224:225] op_sel_hi:[1,0,1]
	global_store_dwordx4 v133, v[24:27], s[22:23] offset:64
	s_waitcnt vmcnt(31)
	v_lshlrev_b32_e32 v140, 16, v226
	v_and_b32_e32 v141, 0xffff0000, v226
	v_lshlrev_b32_e32 v226, 16, v227
	v_and_b32_e32 v227, 0xffff0000, v227
	v_pk_mul_f32 v[140:141], v[140:141], s[74:75] op_sel_hi:[1,0]
	v_pk_mul_f32 v[226:227], v[226:227], s[74:75] op_sel_hi:[1,0]
	v_pk_fma_f32 v[20:21], v[20:21], 0.5, v[140:141] op_sel_hi:[1,0,1]
	v_pk_fma_f32 v[22:23], v[22:23], 0.5, v[226:227] op_sel_hi:[1,0,1]
	global_store_dwordx4 v133, v[20:23], s[22:23] offset:512
	s_waitcnt vmcnt(31)
	v_lshlrev_b32_e32 v140, 16, v228
	v_and_b32_e32 v141, 0xffff0000, v228
	v_lshlrev_b32_e32 v228, 16, v229
	v_and_b32_e32 v229, 0xffff0000, v229
	v_pk_mul_f32 v[140:141], v[140:141], s[74:75] op_sel_hi:[1,0]
	v_pk_mul_f32 v[228:229], v[228:229], s[74:75] op_sel_hi:[1,0]
	v_pk_fma_f32 v[16:17], v[16:17], 0.5, v[140:141] op_sel_hi:[1,0,1]
	v_pk_fma_f32 v[18:19], v[18:19], 0.5, v[228:229] op_sel_hi:[1,0,1]
	global_store_dwordx4 v133, v[16:19], s[22:23] offset:576
	s_waitcnt vmcnt(31)
	v_lshlrev_b32_e32 v140, 16, v230
	v_and_b32_e32 v141, 0xffff0000, v230
	v_lshlrev_b32_e32 v230, 16, v231
	v_and_b32_e32 v231, 0xffff0000, v231
	v_pk_mul_f32 v[140:141], v[140:141], s[74:75] op_sel_hi:[1,0]
	v_pk_mul_f32 v[230:231], v[230:231], s[74:75] op_sel_hi:[1,0]
	v_pk_fma_f32 v[12:13], v[12:13], 0.5, v[140:141] op_sel_hi:[1,0,1]
	v_pk_fma_f32 v[14:15], v[14:15], 0.5, v[230:231] op_sel_hi:[1,0,1]
	s_add_u32 s22, s22, 0x20000
	s_addc_u32 s23, s23, 0
	global_store_dwordx4 v133, v[12:15], s[22:23] offset:0
	s_waitcnt vmcnt(30)
	v_lshlrev_b32_e32 v140, 16, v142
	v_and_b32_e32 v141, 0xffff0000, v142
	v_lshlrev_b32_e32 v142, 16, v143
	v_and_b32_e32 v143, 0xffff0000, v143
	v_pk_mul_f32 v[140:141], v[140:141], s[74:75] op_sel_hi:[1,0]
	v_pk_mul_f32 v[142:143], v[142:143], s[74:75] op_sel_hi:[1,0]
	v_pk_fma_f32 v[8:9], v[8:9], 0.5, v[140:141] op_sel_hi:[1,0,1]
	v_pk_fma_f32 v[10:11], v[10:11], 0.5, v[142:143] op_sel_hi:[1,0,1]
	global_store_dwordx4 v133, v[8:11], s[22:23] offset:64
	s_waitcnt vmcnt(29)
	v_lshlrev_b32_e32 v140, 16, v144
	v_and_b32_e32 v141, 0xffff0000, v144
	v_lshlrev_b32_e32 v144, 16, v145
	v_and_b32_e32 v145, 0xffff0000, v145
	v_pk_mul_f32 v[140:141], v[140:141], s[74:75] op_sel_hi:[1,0]
	v_pk_mul_f32 v[144:145], v[144:145], s[74:75] op_sel_hi:[1,0]
	v_pk_fma_f32 v[4:5], v[4:5], 0.5, v[140:141] op_sel_hi:[1,0,1]
	v_pk_fma_f32 v[6:7], v[6:7], 0.5, v[144:145] op_sel_hi:[1,0,1]
	global_store_dwordx4 v133, v[4:7], s[22:23] offset:512
	s_waitcnt vmcnt(28)
	v_lshlrev_b32_e32 v140, 16, v146
	v_and_b32_e32 v141, 0xffff0000, v146
	v_lshlrev_b32_e32 v146, 16, v147
	v_and_b32_e32 v147, 0xffff0000, v147
	v_pk_mul_f32 v[140:141], v[140:141], s[74:75] op_sel_hi:[1,0]
	v_pk_mul_f32 v[146:147], v[146:147], s[74:75] op_sel_hi:[1,0]
	v_pk_fma_f32 v[0:1], v[0:1], 0.5, v[140:141] op_sel_hi:[1,0,1]
	v_pk_fma_f32 v[2:3], v[2:3], 0.5, v[146:147] op_sel_hi:[1,0,1]
	global_store_dwordx4 v133, v[0:3], s[22:23] offset:576
.Le484_join:
	s_mov_b32 s41, s39
	s_mov_b32 s42, s40
	s_mov_b64 s[22:23], s[12:13]
	s_mov_b64 s[20:21], s[18:19]
	s_and_b64 vcc, exec, s[8:9]
	s_cbranch_vccnz .LBB0_624
	s_branch .LBB0_473
